# weight conversion phases: f32 weight reads (read exactly once) use the non-temporal cache policy so they do not displace activations/bf16 weights from L2/MALL
# speedup vs baseline: 1.0178x; 1.0178x over previous
.LBB0_126:
	s_add_i32 s60, s26, 0x4000
	s_cmpk_lt_u32 s60, 0x2c00
	s_cselect_b32 s8, s28, 0x1000
	s_cmpk_gt_i32 s60, 0x1fff
	s_cselect_b32 s19, s8, 0x800
	s_add_i32 s19, s19, s26
	s_add_i32 s18, s19, 0x4000
	s_cmpk_gt_i32 s18, 0xfff
	s_mov_b64 s[16:17], -1
	s_cbranch_scc0 .LBB0_144
	s_cmpk_gt_u32 s18, 0x1fff
	s_cbranch_scc0 .LBB0_141
	s_cmpk_gt_u32 s18, 0x27ff
	s_cbranch_scc0 .LBB0_138
	s_cmpk_gt_u32 s18, 0x37ff
	s_cbranch_scc0 .LBB0_135
	s_cmpk_gt_u32 s18, 0x3fff
	s_cbranch_scc0 .LBB0_132
	s_load_dwordx2 s[16:17], s[2:3], 0x98
	s_lshr_b32 s8, s19, 6
	s_lshl_b64 s[62:63], s[8:9], 20
	v_mov_b32_e32 v3, v65
	v_mov_b32_e32 v73, v65
	s_waitcnt lgkmcnt(0)
	s_add_u32 s61, s16, s62
	s_addc_u32 s62, s17, s63
	s_lshl_b64 s[16:17], s[8:9], 19
	s_add_u32 s8, s20, s16
	s_addc_u32 s63, s21, s17
	s_lshl_b32 s16, s18, 3
	s_and_b32 s64, s16, 0x1c0
	s_add_u32 s16, s61, s29
	v_or_b32_e32 v2, s64, v88
	s_addc_u32 s17, s62, 0
	v_lshl_add_u64 v[0:1], s[16:17], 0, v[64:65]
	v_lshlrev_b32_e32 v2, 11, v2
	v_lshl_add_u64 v[60:61], v[0:1], 0, v[2:3]
	v_add_co_u32_e32 v4, vcc, s30, v60
	s_lshl_b32 s16, s64, 1
	s_nop 0
	v_addc_co_u32_e32 v5, vcc, 0, v61, vcc
	v_add_co_u32_e32 v8, vcc, s27, v60
	global_load_dwordx4 v[0:3], v[60:61], off nt
	s_nop 0
	global_load_dwordx4 v[4:7], v[4:5], off nt
	v_addc_co_u32_e32 v9, vcc, 0, v61, vcc
	v_add_co_u32_e32 v12, vcc, s31, v60
	s_add_u32 s16, s8, s16
	s_nop 0
	v_addc_co_u32_e32 v13, vcc, 0, v61, vcc
	v_add_co_u32_e32 v16, vcc, s34, v60
	global_load_dwordx4 v[8:11], v[8:9], off nt
	s_nop 0
	global_load_dwordx4 v[12:15], v[12:13], off nt
	v_addc_co_u32_e32 v17, vcc, 0, v61, vcc
	v_add_co_u32_e32 v20, vcc, s35, v60
	s_addc_u32 s17, s63, 0
	s_nop 0
	v_addc_co_u32_e32 v21, vcc, 0, v61, vcc
	v_add_co_u32_e32 v24, vcc, s36, v60
	global_load_dwordx4 v[16:19], v[16:17], off nt
	s_nop 0
	global_load_dwordx4 v[20:23], v[20:21], off nt
	v_addc_co_u32_e32 v25, vcc, 0, v61, vcc
	v_add_co_u32_e32 v28, vcc, s37, v60
	v_mov_b32_e32 v75, v65
	s_nop 0
	v_addc_co_u32_e32 v29, vcc, 0, v61, vcc
	v_add_co_u32_e32 v32, vcc, s38, v60
	global_load_dwordx4 v[24:27], v[24:25], off nt
	s_nop 0
	global_load_dwordx4 v[28:31], v[28:29], off nt
	v_addc_co_u32_e32 v33, vcc, 0, v61, vcc
	v_add_co_u32_e32 v36, vcc, s39, v60
	v_mov_b32_e32 v77, v65
	s_nop 0
	v_addc_co_u32_e32 v37, vcc, 0, v61, vcc
	v_add_co_u32_e32 v40, vcc, s40, v60
	global_load_dwordx4 v[32:35], v[32:33], off nt
	s_nop 0
	global_load_dwordx4 v[36:39], v[36:37], off nt
	v_addc_co_u32_e32 v41, vcc, 0, v61, vcc
	v_add_co_u32_e32 v44, vcc, s41, v60
	v_mov_b32_e32 v79, v65
	s_nop 0
	v_addc_co_u32_e32 v45, vcc, 0, v61, vcc
	v_add_co_u32_e32 v48, vcc, s42, v60
	global_load_dwordx4 v[40:43], v[40:41], off nt
	s_nop 0
	global_load_dwordx4 v[44:47], v[44:45], off nt
	v_addc_co_u32_e32 v49, vcc, 0, v61, vcc
	v_add_co_u32_e32 v52, vcc, s43, v60
	v_mov_b32_e32 v81, v65
	s_nop 0
	v_addc_co_u32_e32 v53, vcc, 0, v61, vcc
	v_add_co_u32_e32 v56, vcc, s44, v60
	global_load_dwordx4 v[48:51], v[48:49], off nt
	s_nop 0
	global_load_dwordx4 v[52:55], v[52:53], off nt
	v_addc_co_u32_e32 v57, vcc, 0, v61, vcc
	v_add_co_u32_e32 v60, vcc, s45, v60
	global_load_dwordx4 v[56:59], v[56:57], off nt
	s_nop 0
	v_addc_co_u32_e32 v61, vcc, 0, v61, vcc
	global_load_dwordx4 v[60:63], v[60:61], off nt
	v_mov_b32_e32 v83, v65
	v_mov_b32_e32 v85, v65
	v_mov_b32_e32 v87, v65
	s_waitcnt vmcnt(15)
	ds_write2_b32 v89, v0, v1 offset1:1
	ds_write2_b32 v89, v2, v3 offset0:2 offset1:3
	s_waitcnt vmcnt(14)
	ds_write2_b32 v99, v4, v5 offset1:1
	ds_write2_b32 v100, v6, v7 offset1:1
	s_waitcnt vmcnt(13)
	ds_write2_b32 v101, v8, v9 offset1:1
	ds_write2_b32 v102, v10, v11 offset1:1
	s_waitcnt vmcnt(12)
	ds_write2_b32 v103, v12, v13 offset1:1
	ds_write2_b32 v104, v14, v15 offset1:1
	s_waitcnt vmcnt(11)
	ds_write2_b32 v105, v16, v17 offset1:1
	ds_write2_b32 v106, v18, v19 offset1:1
	s_waitcnt vmcnt(10)
	ds_write2_b32 v107, v20, v21 offset1:1
	ds_write2_b32 v108, v22, v23 offset1:1
	s_waitcnt vmcnt(9)
	ds_write2_b32 v109, v24, v25 offset1:1
	ds_write2_b32 v110, v26, v27 offset1:1
	s_waitcnt vmcnt(8)
	ds_write2_b32 v111, v28, v29 offset1:1
	ds_write2_b32 v112, v30, v31 offset1:1
	s_waitcnt vmcnt(7)
	ds_write2_b32 v113, v32, v33 offset1:1
	ds_write2_b32 v114, v34, v35 offset1:1
	s_waitcnt vmcnt(6)
	ds_write2_b32 v115, v36, v37 offset1:1
	ds_write2_b32 v116, v38, v39 offset1:1
	s_waitcnt vmcnt(5)
	ds_write2_b32 v117, v40, v41 offset1:1
	ds_write2_b32 v118, v42, v43 offset1:1
	s_waitcnt vmcnt(4)
	ds_write2_b32 v119, v44, v45 offset1:1
	ds_write2_b32 v120, v46, v47 offset1:1
	s_waitcnt vmcnt(3)
	ds_write2_b32 v121, v48, v49 offset1:1
	ds_write2_b32 v122, v50, v51 offset1:1
	s_waitcnt vmcnt(2)
	ds_write2_b32 v123, v52, v53 offset1:1
	ds_write2_b32 v124, v54, v55 offset1:1
	s_waitcnt vmcnt(1)
	ds_write2_b32 v125, v56, v57 offset1:1
	v_add_u32_e32 v0, 0x38e8, v89
	v_add_u32_e32 v24, 0x400, v91
	v_mov_b32_e32 v1, v65
	ds_write2_b32 v0, v58, v59 offset1:1
	v_add_u32_e32 v0, 0x3cf0, v89
	s_waitcnt vmcnt(0)
	ds_write2_b32 v0, v60, v61 offset1:1
	v_add_u32_e32 v0, 0x3cf8, v89
	ds_write2_b32 v0, v62, v63 offset1:1
	s_waitcnt lgkmcnt(0)
	ds_read2_b32 v[6:7], v91 offset1:8
	ds_read2_b32 v[8:9], v91 offset0:65 offset1:73
	ds_read2_b32 v[10:11], v91 offset0:130 offset1:138
	ds_read2_b32 v[12:13], v91 offset0:195 offset1:203
	ds_read2_b32 v[14:15], v24 offset0:4 offset1:12
	s_waitcnt lgkmcnt(4)
	v_bfe_u32 v2, v6, 16, 1
	v_add3_u32 v2, v6, v2, s46
	s_waitcnt lgkmcnt(3)
	v_bfe_u32 v3, v8, 16, 1
	v_lshrrev_b32_e32 v2, 16, v2
	v_add3_u32 v3, v8, v3, s46
	ds_read2_b32 v[16:17], v24 offset0:69 offset1:77
	v_and_or_b32 v2, v3, s47, v2
	s_waitcnt lgkmcnt(3)
	v_bfe_u32 v3, v10, 16, 1
	v_add3_u32 v3, v10, v3, s46
	s_waitcnt lgkmcnt(2)
	v_bfe_u32 v4, v12, 16, 1
	ds_read2_b32 v[18:19], v24 offset0:134 offset1:142
	v_lshrrev_b32_e32 v3, 16, v3
	v_add3_u32 v4, v12, v4, s46
	ds_read2_b32 v[20:21], v24 offset0:199 offset1:207
	v_and_or_b32 v3, v4, s47, v3
	s_waitcnt lgkmcnt(3)
	v_bfe_u32 v4, v14, 16, 1
	v_add3_u32 v4, v14, v4, s46
	s_waitcnt lgkmcnt(2)
	v_bfe_u32 v5, v16, 16, 1
	v_lshrrev_b32_e32 v4, 16, v4
	v_add3_u32 v5, v16, v5, s46
	v_and_or_b32 v4, v5, s47, v4
	s_waitcnt lgkmcnt(1)
	v_bfe_u32 v5, v18, 16, 1
	v_lshlrev_b32_e32 v0, 1, v66
	v_add3_u32 v5, v18, v5, s46
	s_waitcnt lgkmcnt(0)
	v_bfe_u32 v6, v20, 16, 1
	v_lshl_add_u64 v[0:1], s[16:17], 0, v[0:1]
	v_lshrrev_b32_e32 v5, 16, v5
	v_add3_u32 v6, v20, v6, s46
	v_and_or_b32 v5, v6, s47, v5
	v_lshl_add_u64 v[22:23], v[0:1], 0, v[72:73]
	global_store_dwordx4 v[22:23], v[2:5], off
	v_bfe_u32 v6, v21, 16, 1
	v_add3_u32 v6, v21, v6, s46
	v_bfe_u32 v2, v7, 16, 1
	v_add3_u32 v2, v7, v2, s46
	v_bfe_u32 v3, v9, 16, 1
	v_lshrrev_b32_e32 v2, 16, v2
	v_add3_u32 v3, v9, v3, s46
	v_and_or_b32 v2, v3, s47, v2
	v_bfe_u32 v3, v11, 16, 1
	v_add3_u32 v3, v11, v3, s46
	v_bfe_u32 v4, v13, 16, 1
	v_lshrrev_b32_e32 v3, 16, v3
	v_add3_u32 v4, v13, v4, s46
	v_and_or_b32 v3, v4, s47, v3
	v_bfe_u32 v4, v15, 16, 1
	v_add3_u32 v4, v15, v4, s46
	v_bfe_u32 v5, v17, 16, 1
	v_lshrrev_b32_e32 v4, 16, v4
	v_add3_u32 v5, v17, v5, s46
	v_and_or_b32 v4, v5, s47, v4
	v_bfe_u32 v5, v19, 16, 1
	v_add3_u32 v5, v19, v5, s46
	v_lshrrev_b32_e32 v5, 16, v5
	v_and_or_b32 v5, v6, s47, v5
	ds_read2_b32 v[6:7], v91 offset0:16 offset1:24
	v_lshl_add_u64 v[8:9], v[0:1], 0, v[74:75]
	global_store_dwordx4 v[8:9], v[2:5], off
	ds_read2_b32 v[8:9], v91 offset0:81 offset1:89
	ds_read2_b32 v[10:11], v91 offset0:146 offset1:154
	ds_read2_b32 v[12:13], v91 offset0:211 offset1:219
	s_waitcnt lgkmcnt(3)
	v_bfe_u32 v2, v6, 16, 1
	v_add3_u32 v2, v6, v2, s46
	s_waitcnt lgkmcnt(2)
	v_bfe_u32 v3, v8, 16, 1
	ds_read2_b32 v[14:15], v24 offset0:20 offset1:28
	v_lshrrev_b32_e32 v2, 16, v2
	v_add3_u32 v3, v8, v3, s46
	ds_read2_b32 v[16:17], v24 offset0:85 offset1:93
	v_and_or_b32 v2, v3, s47, v2
	s_waitcnt lgkmcnt(3)
	v_bfe_u32 v3, v10, 16, 1
	v_add3_u32 v3, v10, v3, s46
	s_waitcnt lgkmcnt(2)
	v_bfe_u32 v4, v12, 16, 1
	ds_read2_b32 v[18:19], v24 offset0:150 offset1:158
	v_lshrrev_b32_e32 v3, 16, v3
	v_add3_u32 v4, v12, v4, s46
	ds_read2_b32 v[20:21], v24 offset0:215 offset1:223
	v_and_or_b32 v3, v4, s47, v3
	s_waitcnt lgkmcnt(3)
	v_bfe_u32 v4, v14, 16, 1
	v_add3_u32 v4, v14, v4, s46
	s_waitcnt lgkmcnt(2)
	v_bfe_u32 v5, v16, 16, 1
	v_lshrrev_b32_e32 v4, 16, v4
	v_add3_u32 v5, v16, v5, s46
	v_and_or_b32 v4, v5, s47, v4
	s_waitcnt lgkmcnt(1)
	v_bfe_u32 v5, v18, 16, 1
	v_add3_u32 v5, v18, v5, s46
	s_waitcnt lgkmcnt(0)
	v_bfe_u32 v6, v20, 16, 1
	v_lshrrev_b32_e32 v5, 16, v5
	v_add3_u32 v6, v20, v6, s46
	v_and_or_b32 v5, v6, s47, v5
	v_lshl_add_u64 v[22:23], v[0:1], 0, v[76:77]
	global_store_dwordx4 v[22:23], v[2:5], off
	v_bfe_u32 v6, v21, 16, 1
	v_add3_u32 v6, v21, v6, s46
	v_bfe_u32 v2, v7, 16, 1
	v_add3_u32 v2, v7, v2, s46
	v_bfe_u32 v3, v9, 16, 1
	v_lshrrev_b32_e32 v2, 16, v2
	v_add3_u32 v3, v9, v3, s46
	v_and_or_b32 v2, v3, s47, v2
	v_bfe_u32 v3, v11, 16, 1
	v_add3_u32 v3, v11, v3, s46
	v_bfe_u32 v4, v13, 16, 1
	v_lshrrev_b32_e32 v3, 16, v3
	v_add3_u32 v4, v13, v4, s46
	v_and_or_b32 v3, v4, s47, v3
	v_bfe_u32 v4, v15, 16, 1
	v_add3_u32 v4, v15, v4, s46
	v_bfe_u32 v5, v17, 16, 1
	v_lshrrev_b32_e32 v4, 16, v4
	v_add3_u32 v5, v17, v5, s46
	v_and_or_b32 v4, v5, s47, v4
	v_bfe_u32 v5, v19, 16, 1
	v_add3_u32 v5, v19, v5, s46
	v_lshrrev_b32_e32 v5, 16, v5
	v_and_or_b32 v5, v6, s47, v5
	ds_read2_b32 v[6:7], v91 offset0:32 offset1:40
	v_lshl_add_u64 v[8:9], v[0:1], 0, v[78:79]
	global_store_dwordx4 v[8:9], v[2:5], off
	ds_read2_b32 v[8:9], v91 offset0:97 offset1:105
	ds_read2_b32 v[10:11], v91 offset0:162 offset1:170
	ds_read2_b32 v[12:13], v91 offset0:227 offset1:235
	s_waitcnt lgkmcnt(3)
	v_bfe_u32 v2, v6, 16, 1
	v_add3_u32 v2, v6, v2, s46
	s_waitcnt lgkmcnt(2)
	v_bfe_u32 v3, v8, 16, 1
	ds_read2_b32 v[14:15], v24 offset0:36 offset1:44
	v_lshrrev_b32_e32 v2, 16, v2
	v_add3_u32 v3, v8, v3, s46
	ds_read2_b32 v[16:17], v24 offset0:101 offset1:109
	v_and_or_b32 v2, v3, s47, v2
	s_waitcnt lgkmcnt(3)
	v_bfe_u32 v3, v10, 16, 1
	v_add3_u32 v3, v10, v3, s46
	s_waitcnt lgkmcnt(2)
	v_bfe_u32 v4, v12, 16, 1
	ds_read2_b32 v[18:19], v24 offset0:166 offset1:174
	v_lshrrev_b32_e32 v3, 16, v3
	v_add3_u32 v4, v12, v4, s46
	ds_read2_b32 v[20:21], v24 offset0:231 offset1:239
	v_and_or_b32 v3, v4, s47, v3
	s_waitcnt lgkmcnt(3)
	v_bfe_u32 v4, v14, 16, 1
	v_add3_u32 v4, v14, v4, s46
	s_waitcnt lgkmcnt(2)
	v_bfe_u32 v5, v16, 16, 1
	v_lshrrev_b32_e32 v4, 16, v4
	v_add3_u32 v5, v16, v5, s46
	v_and_or_b32 v4, v5, s47, v4
	s_waitcnt lgkmcnt(1)
	v_bfe_u32 v5, v18, 16, 1
	v_add3_u32 v5, v18, v5, s46
	s_waitcnt lgkmcnt(0)
	v_bfe_u32 v6, v20, 16, 1
	v_lshrrev_b32_e32 v5, 16, v5
	v_add3_u32 v6, v20, v6, s46
	v_and_or_b32 v5, v6, s47, v5
	v_lshl_add_u64 v[22:23], v[0:1], 0, v[80:81]
	global_store_dwordx4 v[22:23], v[2:5], off
	v_bfe_u32 v6, v21, 16, 1
	v_add3_u32 v6, v21, v6, s46
	v_bfe_u32 v2, v7, 16, 1
	v_add3_u32 v2, v7, v2, s46
	v_bfe_u32 v3, v9, 16, 1
	v_lshrrev_b32_e32 v2, 16, v2
	v_add3_u32 v3, v9, v3, s46
	v_and_or_b32 v2, v3, s47, v2
	v_bfe_u32 v3, v11, 16, 1
	v_add3_u32 v3, v11, v3, s46
	v_bfe_u32 v4, v13, 16, 1
	v_lshrrev_b32_e32 v3, 16, v3
	v_add3_u32 v4, v13, v4, s46
	v_and_or_b32 v3, v4, s47, v3
	v_bfe_u32 v4, v15, 16, 1
	v_add3_u32 v4, v15, v4, s46
	v_bfe_u32 v5, v17, 16, 1
	v_lshrrev_b32_e32 v4, 16, v4
	v_add3_u32 v5, v17, v5, s46
	v_and_or_b32 v4, v5, s47, v4
	v_bfe_u32 v5, v19, 16, 1
	v_add3_u32 v5, v19, v5, s46
	v_lshrrev_b32_e32 v5, 16, v5
	v_and_or_b32 v5, v6, s47, v5
	ds_read2_b32 v[6:7], v91 offset0:48 offset1:56
	v_lshl_add_u64 v[8:9], v[0:1], 0, v[82:83]
	global_store_dwordx4 v[8:9], v[2:5], off
	ds_read2_b32 v[8:9], v91 offset0:113 offset1:121
	ds_read2_b32 v[10:11], v91 offset0:178 offset1:186
	ds_read2_b32 v[12:13], v91 offset0:243 offset1:251
	s_waitcnt lgkmcnt(3)
	v_bfe_u32 v2, v6, 16, 1
	v_add3_u32 v2, v6, v2, s46
	s_waitcnt lgkmcnt(2)
	v_bfe_u32 v3, v8, 16, 1
	ds_read2_b32 v[14:15], v24 offset0:52 offset1:60
	v_lshrrev_b32_e32 v2, 16, v2
	v_add3_u32 v3, v8, v3, s46
	ds_read2_b32 v[16:17], v24 offset0:117 offset1:125
	v_and_or_b32 v2, v3, s47, v2
	s_waitcnt lgkmcnt(3)
	v_bfe_u32 v3, v10, 16, 1
	v_add3_u32 v3, v10, v3, s46
	s_waitcnt lgkmcnt(2)
	v_bfe_u32 v4, v12, 16, 1
	ds_read2_b32 v[18:19], v24 offset0:182 offset1:190
	v_lshrrev_b32_e32 v3, 16, v3
	v_add3_u32 v4, v12, v4, s46
	ds_read2_b32 v[20:21], v24 offset0:247 offset1:255
	v_and_or_b32 v3, v4, s47, v3
	s_waitcnt lgkmcnt(3)
	v_bfe_u32 v4, v14, 16, 1
	v_add3_u32 v4, v14, v4, s46
	s_waitcnt lgkmcnt(2)
	v_bfe_u32 v5, v16, 16, 1
	v_lshrrev_b32_e32 v4, 16, v4
	v_add3_u32 v5, v16, v5, s46
	v_and_or_b32 v4, v5, s47, v4
	s_waitcnt lgkmcnt(1)
	v_bfe_u32 v5, v18, 16, 1
	v_add3_u32 v5, v18, v5, s46
	s_waitcnt lgkmcnt(0)
	v_bfe_u32 v6, v20, 16, 1
	v_lshrrev_b32_e32 v5, 16, v5
	v_add3_u32 v6, v20, v6, s46
	v_and_or_b32 v5, v6, s47, v5
	v_lshl_add_u64 v[22:23], v[0:1], 0, v[84:85]
	global_store_dwordx4 v[22:23], v[2:5], off
	v_bfe_u32 v6, v21, 16, 1
	v_add3_u32 v6, v21, v6, s46
	v_bfe_u32 v2, v7, 16, 1
	v_add3_u32 v2, v7, v2, s46
	v_bfe_u32 v3, v9, 16, 1
	v_lshrrev_b32_e32 v2, 16, v2
	v_add3_u32 v3, v9, v3, s46
	v_and_or_b32 v2, v3, s47, v2
	v_bfe_u32 v3, v11, 16, 1
	v_add3_u32 v3, v11, v3, s46
	v_bfe_u32 v4, v13, 16, 1
	v_lshrrev_b32_e32 v3, 16, v3
	v_add3_u32 v4, v13, v4, s46
	v_and_or_b32 v3, v4, s47, v3
	v_bfe_u32 v4, v15, 16, 1
	v_add3_u32 v4, v15, v4, s46
	v_bfe_u32 v5, v17, 16, 1
	v_lshrrev_b32_e32 v4, 16, v4
	v_add3_u32 v5, v17, v5, s46
	v_and_or_b32 v4, v5, s47, v4
	v_bfe_u32 v5, v19, 16, 1
	v_add3_u32 v5, v19, v5, s46
	v_lshrrev_b32_e32 v5, 16, v5
	v_and_or_b32 v5, v6, s47, v5
	v_lshl_add_u64 v[0:1], v[0:1], 0, v[86:87]
	global_store_dwordx4 v[0:1], v[2:5], off
	s_waitcnt lgkmcnt(0)
	s_mov_b64 s[16:17], 0
.LBB0_132:
	s_andn2_b64 vcc, exec, s[16:17]
	s_cbranch_vccnz .LBB0_134
	s_load_dwordx2 s[16:17], s[2:3], 0x60
	s_add_i32 s8, s19, 0x800
	s_lshr_b32 s8, s8, 10
	s_lshl_b64 s[62:63], s[8:9], 24
	v_mov_b32_e32 v3, v65
	s_waitcnt lgkmcnt(0)
	s_add_u32 s61, s16, s62
	s_addc_u32 s62, s17, s63
	s_lshl_b64 s[16:17], s[8:9], 23
	s_add_u32 s63, s22, s16
	s_addc_u32 s64, s23, s17
	s_lshl_b32 s8, s18, 1
	s_and_b32 s65, s8, 0x7c0
	s_lshl_b32 s8, s60, 6
	s_and_b32 s8, s8, 0x7c0
	s_lshl_b32 s16, s8, 2
	s_add_u32 s16, s61, s16
	v_or_b32_e32 v2, s65, v88
	s_addc_u32 s17, s62, 0
	v_lshl_add_u64 v[0:1], s[16:17], 0, v[64:65]
	v_lshlrev_b32_e32 v2, 13, v2
	v_lshl_add_u64 v[60:61], v[0:1], 0, v[2:3]
	v_add_co_u32_e32 v4, vcc, s34, v60
	s_lshl_b32 s16, s65, 1
	s_nop 0
	v_addc_co_u32_e32 v5, vcc, 0, v61, vcc
	v_add_co_u32_e32 v8, vcc, s38, v60
	global_load_dwordx4 v[0:3], v[60:61], off nt
	s_nop 0
	global_load_dwordx4 v[4:7], v[4:5], off nt
	v_addc_co_u32_e32 v9, vcc, 0, v61, vcc
	v_add_co_u32_e32 v12, vcc, s42, v60
	s_add_u32 s16, s63, s16
	s_nop 0
	v_addc_co_u32_e32 v13, vcc, 0, v61, vcc
	v_add_co_u32_e32 v16, vcc, s48, v60
	global_load_dwordx4 v[8:11], v[8:9], off nt
	s_nop 0
	global_load_dwordx4 v[12:15], v[12:13], off nt
	v_addc_co_u32_e32 v17, vcc, 0, v61, vcc
	v_add_co_u32_e32 v20, vcc, s49, v60
	s_addc_u32 s17, s64, 0
	s_nop 0
	v_addc_co_u32_e32 v21, vcc, 0, v61, vcc
	v_add_co_u32_e32 v24, vcc, s50, v60
	global_load_dwordx4 v[16:19], v[16:17], off nt
	s_nop 0
	global_load_dwordx4 v[20:23], v[20:21], off nt
	v_addc_co_u32_e32 v25, vcc, 0, v61, vcc
	v_add_co_u32_e32 v28, vcc, s51, v60
	s_nop 1
	v_addc_co_u32_e32 v29, vcc, 0, v61, vcc
	v_add_co_u32_e32 v32, vcc, s52, v60
	global_load_dwordx4 v[24:27], v[24:25], off nt
	s_nop 0
	global_load_dwordx4 v[28:31], v[28:29], off nt
	v_addc_co_u32_e32 v33, vcc, 0, v61, vcc
	v_add_co_u32_e32 v36, vcc, s53, v60
	s_nop 1
	v_addc_co_u32_e32 v37, vcc, 0, v61, vcc
	v_add_co_u32_e32 v40, vcc, s54, v60
	global_load_dwordx4 v[32:35], v[32:33], off nt
	s_nop 0
	global_load_dwordx4 v[36:39], v[36:37], off nt
	v_addc_co_u32_e32 v41, vcc, 0, v61, vcc
	v_add_co_u32_e32 v44, vcc, s55, v60
	s_nop 1
	v_addc_co_u32_e32 v45, vcc, 0, v61, vcc
	v_add_co_u32_e32 v48, vcc, s56, v60
	global_load_dwordx4 v[40:43], v[40:41], off nt
	s_nop 0
	global_load_dwordx4 v[44:47], v[44:45], off nt
	v_addc_co_u32_e32 v49, vcc, 0, v61, vcc
	v_add_co_u32_e32 v52, vcc, s57, v60
	s_nop 1
	v_addc_co_u32_e32 v53, vcc, 0, v61, vcc
	v_add_co_u32_e32 v56, vcc, s58, v60
	global_load_dwordx4 v[48:51], v[48:49], off nt
	s_nop 0
	global_load_dwordx4 v[52:55], v[52:53], off nt
	v_addc_co_u32_e32 v57, vcc, 0, v61, vcc
	v_add_co_u32_e32 v60, vcc, s59, v60
	global_load_dwordx4 v[56:59], v[56:57], off nt
	s_nop 0
	v_addc_co_u32_e32 v61, vcc, 0, v61, vcc
	global_load_dwordx4 v[60:63], v[60:61], off nt
	s_waitcnt vmcnt(15)
	ds_write2_b32 v89, v0, v1 offset1:1
	ds_write2_b32 v89, v2, v3 offset0:2 offset1:3
	s_waitcnt vmcnt(14)
	ds_write2_b32 v99, v4, v5 offset1:1
	ds_write2_b32 v100, v6, v7 offset1:1
	s_waitcnt vmcnt(13)
	ds_write2_b32 v101, v8, v9 offset1:1
	ds_write2_b32 v102, v10, v11 offset1:1
	s_waitcnt vmcnt(12)
	ds_write2_b32 v103, v12, v13 offset1:1
	ds_write2_b32 v104, v14, v15 offset1:1
	s_waitcnt vmcnt(11)
	ds_write2_b32 v105, v16, v17 offset1:1
	ds_write2_b32 v106, v18, v19 offset1:1
	s_waitcnt vmcnt(10)
	ds_write2_b32 v107, v20, v21 offset1:1
	ds_write2_b32 v108, v22, v23 offset1:1
	s_waitcnt vmcnt(9)
	ds_write2_b32 v109, v24, v25 offset1:1
	ds_write2_b32 v110, v26, v27 offset1:1
	s_waitcnt vmcnt(8)
	ds_write2_b32 v111, v28, v29 offset1:1
	ds_write2_b32 v112, v30, v31 offset1:1
	s_waitcnt vmcnt(7)
	ds_write2_b32 v113, v32, v33 offset1:1
	ds_write2_b32 v114, v34, v35 offset1:1
	s_waitcnt vmcnt(6)
	ds_write2_b32 v115, v36, v37 offset1:1
	ds_write2_b32 v116, v38, v39 offset1:1
	s_waitcnt vmcnt(5)
	ds_write2_b32 v117, v40, v41 offset1:1
	ds_write2_b32 v118, v42, v43 offset1:1
	s_waitcnt vmcnt(4)
	ds_write2_b32 v119, v44, v45 offset1:1
	ds_write2_b32 v120, v46, v47 offset1:1
	s_waitcnt vmcnt(3)
	ds_write2_b32 v121, v48, v49 offset1:1
	ds_write2_b32 v122, v50, v51 offset1:1
	s_waitcnt vmcnt(2)
	ds_write2_b32 v123, v52, v53 offset1:1
	ds_write2_b32 v124, v54, v55 offset1:1
	s_waitcnt vmcnt(1)
	ds_write2_b32 v125, v56, v57 offset1:1
	v_add_u32_e32 v0, 0x38e8, v89
	v_add_u32_e32 v24, 0x400, v91
	v_mov_b32_e32 v1, v65
	v_mov_b32_e32 v23, v65
	ds_write2_b32 v0, v58, v59 offset1:1
	v_add_u32_e32 v0, 0x3cf0, v89
	s_waitcnt vmcnt(0)
	ds_write2_b32 v0, v60, v61 offset1:1
	v_add_u32_e32 v0, 0x3cf8, v89
	ds_write2_b32 v0, v62, v63 offset1:1
	s_waitcnt lgkmcnt(0)
	ds_read2_b32 v[6:7], v91 offset1:8
	ds_read2_b32 v[8:9], v91 offset0:65 offset1:73
	ds_read2_b32 v[10:11], v91 offset0:130 offset1:138
	ds_read2_b32 v[12:13], v91 offset0:195 offset1:203
	ds_read2_b32 v[14:15], v24 offset0:4 offset1:12
	s_waitcnt lgkmcnt(4)
	v_bfe_u32 v2, v6, 16, 1
	v_add3_u32 v2, v6, v2, s46
	s_waitcnt lgkmcnt(3)
	v_bfe_u32 v3, v8, 16, 1
	v_lshrrev_b32_e32 v2, 16, v2
	v_add3_u32 v3, v8, v3, s46
	ds_read2_b32 v[16:17], v24 offset0:69 offset1:77
	v_and_or_b32 v2, v3, s47, v2
	s_waitcnt lgkmcnt(3)
	v_bfe_u32 v3, v10, 16, 1
	v_add3_u32 v3, v10, v3, s46
	s_waitcnt lgkmcnt(2)
	v_bfe_u32 v4, v12, 16, 1
	ds_read2_b32 v[18:19], v24 offset0:134 offset1:142
	v_lshrrev_b32_e32 v3, 16, v3
	v_add3_u32 v4, v12, v4, s46
	ds_read2_b32 v[20:21], v24 offset0:199 offset1:207
	v_and_or_b32 v3, v4, s47, v3
	s_waitcnt lgkmcnt(3)
	v_bfe_u32 v4, v14, 16, 1
	v_add3_u32 v4, v14, v4, s46
	s_waitcnt lgkmcnt(2)
	v_bfe_u32 v5, v16, 16, 1
	v_lshrrev_b32_e32 v4, 16, v4
	v_add3_u32 v5, v16, v5, s46
	v_and_or_b32 v4, v5, s47, v4
	s_waitcnt lgkmcnt(1)
	v_bfe_u32 v5, v18, 16, 1
	v_add3_u32 v5, v18, v5, s46
	s_waitcnt lgkmcnt(0)
	v_bfe_u32 v6, v20, 16, 1
	v_lshrrev_b32_e32 v5, 16, v5
	v_add3_u32 v6, v20, v6, s46
	v_lshlrev_b32_e32 v0, 1, v66
	v_and_or_b32 v5, v6, s47, v5
	v_or_b32_e32 v6, s8, v90
	v_lshl_add_u64 v[0:1], s[16:17], 0, v[0:1]
	v_lshlrev_b32_e32 v22, 12, v6
	v_lshl_add_u64 v[22:23], v[0:1], 0, v[22:23]
	global_store_dwordx4 v[22:23], v[2:5], off
	v_bfe_u32 v6, v21, 16, 1
	v_add3_u32 v6, v21, v6, s46
	v_bfe_u32 v2, v7, 16, 1
	v_add3_u32 v2, v7, v2, s46
	v_bfe_u32 v3, v9, 16, 1
	v_lshrrev_b32_e32 v2, 16, v2
	v_add3_u32 v3, v9, v3, s46
	v_and_or_b32 v2, v3, s47, v2
	v_bfe_u32 v3, v11, 16, 1
	v_add3_u32 v3, v11, v3, s46
	v_bfe_u32 v4, v13, 16, 1
	v_lshrrev_b32_e32 v3, 16, v3
	v_add3_u32 v4, v13, v4, s46
	v_and_or_b32 v3, v4, s47, v3
	v_bfe_u32 v4, v15, 16, 1
	v_add3_u32 v4, v15, v4, s46
	v_bfe_u32 v5, v17, 16, 1
	v_lshrrev_b32_e32 v4, 16, v4
	v_add3_u32 v5, v17, v5, s46
	v_and_or_b32 v4, v5, s47, v4
	v_bfe_u32 v5, v19, 16, 1
	v_add3_u32 v5, v19, v5, s46
	v_lshrrev_b32_e32 v5, 16, v5
	v_and_or_b32 v5, v6, s47, v5
	v_or_b32_e32 v6, s8, v92
	v_lshlrev_b32_e32 v6, 12, v6
	v_mov_b32_e32 v7, v65
	ds_read2_b32 v[8:9], v91 offset0:16 offset1:24
	v_lshl_add_u64 v[6:7], v[0:1], 0, v[6:7]
	global_store_dwordx4 v[6:7], v[2:5], off
	ds_read2_b32 v[6:7], v91 offset0:81 offset1:89
	ds_read2_b32 v[10:11], v91 offset0:146 offset1:154
	ds_read2_b32 v[12:13], v91 offset0:211 offset1:219
	s_waitcnt lgkmcnt(3)
	v_bfe_u32 v2, v8, 16, 1
	v_add3_u32 v2, v8, v2, s46
	s_waitcnt lgkmcnt(2)
	v_bfe_u32 v3, v6, 16, 1
	ds_read2_b32 v[14:15], v24 offset0:20 offset1:28
	v_lshrrev_b32_e32 v2, 16, v2
	v_add3_u32 v3, v6, v3, s46
	ds_read2_b32 v[16:17], v24 offset0:85 offset1:93
	v_and_or_b32 v2, v3, s47, v2
	s_waitcnt lgkmcnt(3)
	v_bfe_u32 v3, v10, 16, 1
	v_add3_u32 v3, v10, v3, s46
	s_waitcnt lgkmcnt(2)
	v_bfe_u32 v4, v12, 16, 1
	ds_read2_b32 v[18:19], v24 offset0:150 offset1:158
	v_lshrrev_b32_e32 v3, 16, v3
	v_add3_u32 v4, v12, v4, s46
	ds_read2_b32 v[20:21], v24 offset0:215 offset1:223
	v_and_or_b32 v3, v4, s47, v3
	s_waitcnt lgkmcnt(3)
	v_bfe_u32 v4, v14, 16, 1
	v_add3_u32 v4, v14, v4, s46
	s_waitcnt lgkmcnt(2)
	v_bfe_u32 v5, v16, 16, 1
	v_lshrrev_b32_e32 v4, 16, v4
	v_add3_u32 v5, v16, v5, s46
	v_and_or_b32 v4, v5, s47, v4
	s_waitcnt lgkmcnt(1)
	v_bfe_u32 v5, v18, 16, 1
	v_add3_u32 v5, v18, v5, s46
	s_waitcnt lgkmcnt(0)
	v_bfe_u32 v6, v20, 16, 1
	v_lshrrev_b32_e32 v5, 16, v5
	v_add3_u32 v6, v20, v6, s46
	v_and_or_b32 v5, v6, s47, v5
	v_or_b32_e32 v6, s8, v93
	v_lshlrev_b32_e32 v22, 12, v6
	v_mov_b32_e32 v23, v65
	v_lshl_add_u64 v[22:23], v[0:1], 0, v[22:23]
	global_store_dwordx4 v[22:23], v[2:5], off
	v_bfe_u32 v6, v21, 16, 1
	v_add3_u32 v6, v21, v6, s46
	v_bfe_u32 v2, v9, 16, 1
	v_add3_u32 v2, v9, v2, s46
	v_bfe_u32 v3, v7, 16, 1
	v_lshrrev_b32_e32 v2, 16, v2
	v_add3_u32 v3, v7, v3, s46
	v_and_or_b32 v2, v3, s47, v2
	v_bfe_u32 v3, v11, 16, 1
	v_add3_u32 v3, v11, v3, s46
	v_bfe_u32 v4, v13, 16, 1
	v_lshrrev_b32_e32 v3, 16, v3
	v_add3_u32 v4, v13, v4, s46
	v_and_or_b32 v3, v4, s47, v3
	v_bfe_u32 v4, v15, 16, 1
	v_add3_u32 v4, v15, v4, s46
	v_bfe_u32 v5, v17, 16, 1
	v_lshrrev_b32_e32 v4, 16, v4
	v_add3_u32 v5, v17, v5, s46
	v_and_or_b32 v4, v5, s47, v4
	v_bfe_u32 v5, v19, 16, 1
	v_add3_u32 v5, v19, v5, s46
	v_lshrrev_b32_e32 v5, 16, v5
	v_and_or_b32 v5, v6, s47, v5
	v_or_b32_e32 v6, s8, v94
	v_lshlrev_b32_e32 v6, 12, v6
	v_mov_b32_e32 v7, v65
	ds_read2_b32 v[8:9], v91 offset0:32 offset1:40
	v_lshl_add_u64 v[6:7], v[0:1], 0, v[6:7]
	global_store_dwordx4 v[6:7], v[2:5], off
	ds_read2_b32 v[6:7], v91 offset0:97 offset1:105
	ds_read2_b32 v[10:11], v91 offset0:162 offset1:170
	ds_read2_b32 v[12:13], v91 offset0:227 offset1:235
	s_waitcnt lgkmcnt(3)
	v_bfe_u32 v2, v8, 16, 1
	v_add3_u32 v2, v8, v2, s46
	s_waitcnt lgkmcnt(2)
	v_bfe_u32 v3, v6, 16, 1
	ds_read2_b32 v[14:15], v24 offset0:36 offset1:44
	v_lshrrev_b32_e32 v2, 16, v2
	v_add3_u32 v3, v6, v3, s46
	ds_read2_b32 v[16:17], v24 offset0:101 offset1:109
	v_and_or_b32 v2, v3, s47, v2
	s_waitcnt lgkmcnt(3)
	v_bfe_u32 v3, v10, 16, 1
	v_add3_u32 v3, v10, v3, s46
	s_waitcnt lgkmcnt(2)
	v_bfe_u32 v4, v12, 16, 1
	ds_read2_b32 v[18:19], v24 offset0:166 offset1:174
	v_lshrrev_b32_e32 v3, 16, v3
	v_add3_u32 v4, v12, v4, s46
	ds_read2_b32 v[20:21], v24 offset0:231 offset1:239
	v_and_or_b32 v3, v4, s47, v3
	s_waitcnt lgkmcnt(3)
	v_bfe_u32 v4, v14, 16, 1
	v_add3_u32 v4, v14, v4, s46
	s_waitcnt lgkmcnt(2)
	v_bfe_u32 v5, v16, 16, 1
	v_lshrrev_b32_e32 v4, 16, v4
	v_add3_u32 v5, v16, v5, s46
	v_and_or_b32 v4, v5, s47, v4
	s_waitcnt lgkmcnt(1)
	v_bfe_u32 v5, v18, 16, 1
	v_add3_u32 v5, v18, v5, s46
	s_waitcnt lgkmcnt(0)
	v_bfe_u32 v6, v20, 16, 1
	v_lshrrev_b32_e32 v5, 16, v5
	v_add3_u32 v6, v20, v6, s46
	v_and_or_b32 v5, v6, s47, v5
	v_or_b32_e32 v6, s8, v95
	v_lshlrev_b32_e32 v22, 12, v6
	v_mov_b32_e32 v23, v65
	v_lshl_add_u64 v[22:23], v[0:1], 0, v[22:23]
	global_store_dwordx4 v[22:23], v[2:5], off
	v_bfe_u32 v6, v21, 16, 1
	v_add3_u32 v6, v21, v6, s46
	v_bfe_u32 v2, v9, 16, 1
	v_add3_u32 v2, v9, v2, s46
	v_bfe_u32 v3, v7, 16, 1
	v_lshrrev_b32_e32 v2, 16, v2
	v_add3_u32 v3, v7, v3, s46
	v_and_or_b32 v2, v3, s47, v2
	v_bfe_u32 v3, v11, 16, 1
	v_add3_u32 v3, v11, v3, s46
	v_bfe_u32 v4, v13, 16, 1
	v_lshrrev_b32_e32 v3, 16, v3
	v_add3_u32 v4, v13, v4, s46
	v_and_or_b32 v3, v4, s47, v3
	v_bfe_u32 v4, v15, 16, 1
	v_add3_u32 v4, v15, v4, s46
	v_bfe_u32 v5, v17, 16, 1
	v_lshrrev_b32_e32 v4, 16, v4
	v_add3_u32 v5, v17, v5, s46
	v_and_or_b32 v4, v5, s47, v4
	v_bfe_u32 v5, v19, 16, 1
	v_add3_u32 v5, v19, v5, s46
	v_lshrrev_b32_e32 v5, 16, v5
	v_and_or_b32 v5, v6, s47, v5
	v_or_b32_e32 v6, s8, v96
	v_lshlrev_b32_e32 v6, 12, v6
	v_mov_b32_e32 v7, v65
	ds_read2_b32 v[8:9], v91 offset0:48 offset1:56
	v_lshl_add_u64 v[6:7], v[0:1], 0, v[6:7]
	global_store_dwordx4 v[6:7], v[2:5], off
	ds_read2_b32 v[6:7], v91 offset0:113 offset1:121
	ds_read2_b32 v[10:11], v91 offset0:178 offset1:186
	ds_read2_b32 v[12:13], v91 offset0:243 offset1:251
	s_waitcnt lgkmcnt(3)
	v_bfe_u32 v2, v8, 16, 1
	v_add3_u32 v2, v8, v2, s46
	s_waitcnt lgkmcnt(2)
	v_bfe_u32 v3, v6, 16, 1
	ds_read2_b32 v[14:15], v24 offset0:52 offset1:60
	v_lshrrev_b32_e32 v2, 16, v2
	v_add3_u32 v3, v6, v3, s46
	ds_read2_b32 v[16:17], v24 offset0:117 offset1:125
	v_and_or_b32 v2, v3, s47, v2
	s_waitcnt lgkmcnt(3)
	v_bfe_u32 v3, v10, 16, 1
	v_add3_u32 v3, v10, v3, s46
	s_waitcnt lgkmcnt(2)
	v_bfe_u32 v4, v12, 16, 1
	ds_read2_b32 v[18:19], v24 offset0:182 offset1:190
	v_lshrrev_b32_e32 v3, 16, v3
	v_add3_u32 v4, v12, v4, s46
	ds_read2_b32 v[20:21], v24 offset0:247 offset1:255
	v_and_or_b32 v3, v4, s47, v3
	s_waitcnt lgkmcnt(3)
	v_bfe_u32 v4, v14, 16, 1
	v_add3_u32 v4, v14, v4, s46
	s_waitcnt lgkmcnt(2)
	v_bfe_u32 v5, v16, 16, 1
	v_lshrrev_b32_e32 v4, 16, v4
	v_add3_u32 v5, v16, v5, s46
	v_and_or_b32 v4, v5, s47, v4
	s_waitcnt lgkmcnt(1)
	v_bfe_u32 v5, v18, 16, 1
	v_add3_u32 v5, v18, v5, s46
	s_waitcnt lgkmcnt(0)
	v_bfe_u32 v6, v20, 16, 1
	v_lshrrev_b32_e32 v5, 16, v5
	v_add3_u32 v6, v20, v6, s46
	v_and_or_b32 v5, v6, s47, v5
	v_or_b32_e32 v6, s8, v97
	v_lshlrev_b32_e32 v22, 12, v6
	v_mov_b32_e32 v23, v65
	v_lshl_add_u64 v[22:23], v[0:1], 0, v[22:23]
	global_store_dwordx4 v[22:23], v[2:5], off
	v_bfe_u32 v6, v21, 16, 1
	v_add3_u32 v6, v21, v6, s46
	v_bfe_u32 v2, v9, 16, 1
	v_add3_u32 v2, v9, v2, s46
	v_bfe_u32 v3, v7, 16, 1
	v_lshrrev_b32_e32 v2, 16, v2
	v_add3_u32 v3, v7, v3, s46
	v_and_or_b32 v2, v3, s47, v2
	v_bfe_u32 v3, v11, 16, 1
	v_add3_u32 v3, v11, v3, s46
	v_bfe_u32 v4, v13, 16, 1
	v_lshrrev_b32_e32 v3, 16, v3
	v_add3_u32 v4, v13, v4, s46
	v_and_or_b32 v3, v4, s47, v3
	v_bfe_u32 v4, v15, 16, 1
	v_add3_u32 v4, v15, v4, s46
	v_bfe_u32 v5, v17, 16, 1
	v_lshrrev_b32_e32 v4, 16, v4
	v_add3_u32 v5, v17, v5, s46
	v_and_or_b32 v4, v5, s47, v4
	v_bfe_u32 v5, v19, 16, 1
	v_add3_u32 v5, v19, v5, s46
	v_lshrrev_b32_e32 v5, 16, v5
	v_and_or_b32 v5, v6, s47, v5
	v_or_b32_e32 v6, s8, v98
	v_lshlrev_b32_e32 v6, 12, v6
	v_mov_b32_e32 v7, v65
	v_lshl_add_u64 v[0:1], v[0:1], 0, v[6:7]
	global_store_dwordx4 v[0:1], v[2:5], off
	s_waitcnt lgkmcnt(0)

.LBB0_135:
	s_andn2_b64 vcc, exec, s[16:17]
	s_cbranch_vccnz .LBB0_137
	s_load_dwordx2 s[16:17], s[2:3], 0x10
	s_add_i32 s8, s19, 0x1800
	s_lshr_b32 s8, s8, 10
	s_lshl_b64 s[62:63], s[8:9], 24
	v_mov_b32_e32 v3, v65
	s_waitcnt lgkmcnt(0)
	s_add_u32 s61, s16, s62
	s_addc_u32 s62, s17, s63
	s_lshl_b64 s[16:17], s[8:9], 23
	s_add_u32 s63, s24, s16
	s_addc_u32 s64, s25, s17
	s_lshl_b32 s8, s18, 1
	s_and_b32 s65, s8, 0x7c0
	s_lshl_b32 s8, s60, 6
	s_and_b32 s8, s8, 0x7c0
	s_lshl_b32 s16, s8, 2
	s_add_u32 s16, s61, s16
	v_or_b32_e32 v2, s65, v88
	s_addc_u32 s17, s62, 0
	v_lshl_add_u64 v[0:1], s[16:17], 0, v[64:65]
	v_lshlrev_b32_e32 v2, 13, v2
	v_lshl_add_u64 v[60:61], v[0:1], 0, v[2:3]
	v_add_co_u32_e32 v4, vcc, s34, v60
	s_lshl_b32 s16, s65, 1
	s_nop 0
	v_addc_co_u32_e32 v5, vcc, 0, v61, vcc
	v_add_co_u32_e32 v8, vcc, s38, v60
	global_load_dwordx4 v[0:3], v[60:61], off nt
	s_nop 0
	global_load_dwordx4 v[4:7], v[4:5], off nt
	v_addc_co_u32_e32 v9, vcc, 0, v61, vcc
	v_add_co_u32_e32 v12, vcc, s42, v60
	s_add_u32 s16, s63, s16
	s_nop 0
	v_addc_co_u32_e32 v13, vcc, 0, v61, vcc
	v_add_co_u32_e32 v16, vcc, s48, v60
	global_load_dwordx4 v[8:11], v[8:9], off nt
	s_nop 0
	global_load_dwordx4 v[12:15], v[12:13], off nt
	v_addc_co_u32_e32 v17, vcc, 0, v61, vcc
	v_add_co_u32_e32 v20, vcc, s49, v60
	s_addc_u32 s17, s64, 0
	s_nop 0
	v_addc_co_u32_e32 v21, vcc, 0, v61, vcc
	v_add_co_u32_e32 v24, vcc, s50, v60
	global_load_dwordx4 v[16:19], v[16:17], off nt
	s_nop 0
	global_load_dwordx4 v[20:23], v[20:21], off nt
	v_addc_co_u32_e32 v25, vcc, 0, v61, vcc
	v_add_co_u32_e32 v28, vcc, s51, v60
	s_nop 1
	v_addc_co_u32_e32 v29, vcc, 0, v61, vcc
	v_add_co_u32_e32 v32, vcc, s52, v60
	global_load_dwordx4 v[24:27], v[24:25], off nt
	s_nop 0
	global_load_dwordx4 v[28:31], v[28:29], off nt
	v_addc_co_u32_e32 v33, vcc, 0, v61, vcc
	v_add_co_u32_e32 v36, vcc, s53, v60
	s_nop 1
	v_addc_co_u32_e32 v37, vcc, 0, v61, vcc
	v_add_co_u32_e32 v40, vcc, s54, v60
	global_load_dwordx4 v[32:35], v[32:33], off nt
	s_nop 0
	global_load_dwordx4 v[36:39], v[36:37], off nt
	v_addc_co_u32_e32 v41, vcc, 0, v61, vcc
	v_add_co_u32_e32 v44, vcc, s55, v60
	s_nop 1
	v_addc_co_u32_e32 v45, vcc, 0, v61, vcc
	v_add_co_u32_e32 v48, vcc, s56, v60
	global_load_dwordx4 v[40:43], v[40:41], off nt
	s_nop 0
	global_load_dwordx4 v[44:47], v[44:45], off nt
	v_addc_co_u32_e32 v49, vcc, 0, v61, vcc
	v_add_co_u32_e32 v52, vcc, s57, v60
	s_nop 1
	v_addc_co_u32_e32 v53, vcc, 0, v61, vcc
	v_add_co_u32_e32 v56, vcc, s58, v60
	global_load_dwordx4 v[48:51], v[48:49], off nt
	s_nop 0
	global_load_dwordx4 v[52:55], v[52:53], off nt
	v_addc_co_u32_e32 v57, vcc, 0, v61, vcc
	v_add_co_u32_e32 v60, vcc, s59, v60
	global_load_dwordx4 v[56:59], v[56:57], off nt
	s_nop 0
	v_addc_co_u32_e32 v61, vcc, 0, v61, vcc
	global_load_dwordx4 v[60:63], v[60:61], off nt
	s_waitcnt vmcnt(15)
	ds_write2_b32 v89, v0, v1 offset1:1
	ds_write2_b32 v89, v2, v3 offset0:2 offset1:3
	s_waitcnt vmcnt(14)
	ds_write2_b32 v99, v4, v5 offset1:1
	ds_write2_b32 v100, v6, v7 offset1:1
	s_waitcnt vmcnt(13)
	ds_write2_b32 v101, v8, v9 offset1:1
	ds_write2_b32 v102, v10, v11 offset1:1
	s_waitcnt vmcnt(12)
	ds_write2_b32 v103, v12, v13 offset1:1
	ds_write2_b32 v104, v14, v15 offset1:1
	s_waitcnt vmcnt(11)
	ds_write2_b32 v105, v16, v17 offset1:1
	ds_write2_b32 v106, v18, v19 offset1:1
	s_waitcnt vmcnt(10)
	ds_write2_b32 v107, v20, v21 offset1:1
	ds_write2_b32 v108, v22, v23 offset1:1
	s_waitcnt vmcnt(9)
	ds_write2_b32 v109, v24, v25 offset1:1
	ds_write2_b32 v110, v26, v27 offset1:1
	s_waitcnt vmcnt(8)
	ds_write2_b32 v111, v28, v29 offset1:1
	ds_write2_b32 v112, v30, v31 offset1:1
	s_waitcnt vmcnt(7)
	ds_write2_b32 v113, v32, v33 offset1:1
	ds_write2_b32 v114, v34, v35 offset1:1
	s_waitcnt vmcnt(6)
	ds_write2_b32 v115, v36, v37 offset1:1
	ds_write2_b32 v116, v38, v39 offset1:1
	s_waitcnt vmcnt(5)
	ds_write2_b32 v117, v40, v41 offset1:1
	ds_write2_b32 v118, v42, v43 offset1:1
	s_waitcnt vmcnt(4)
	ds_write2_b32 v119, v44, v45 offset1:1
	ds_write2_b32 v120, v46, v47 offset1:1
	s_waitcnt vmcnt(3)
	ds_write2_b32 v121, v48, v49 offset1:1
	ds_write2_b32 v122, v50, v51 offset1:1
	s_waitcnt vmcnt(2)
	ds_write2_b32 v123, v52, v53 offset1:1
	ds_write2_b32 v124, v54, v55 offset1:1
	s_waitcnt vmcnt(1)
	ds_write2_b32 v125, v56, v57 offset1:1
	v_add_u32_e32 v0, 0x38e8, v89
	v_add_u32_e32 v24, 0x400, v91
	v_mov_b32_e32 v1, v65
	v_mov_b32_e32 v23, v65
	ds_write2_b32 v0, v58, v59 offset1:1
	v_add_u32_e32 v0, 0x3cf0, v89
	s_waitcnt vmcnt(0)
	ds_write2_b32 v0, v60, v61 offset1:1
	v_add_u32_e32 v0, 0x3cf8, v89
	ds_write2_b32 v0, v62, v63 offset1:1
	s_waitcnt lgkmcnt(0)
	ds_read2_b32 v[6:7], v91 offset1:8
	ds_read2_b32 v[8:9], v91 offset0:65 offset1:73
	ds_read2_b32 v[10:11], v91 offset0:130 offset1:138
	ds_read2_b32 v[12:13], v91 offset0:195 offset1:203
	ds_read2_b32 v[14:15], v24 offset0:4 offset1:12
	s_waitcnt lgkmcnt(4)
	v_bfe_u32 v2, v6, 16, 1
	v_add3_u32 v2, v6, v2, s46
	s_waitcnt lgkmcnt(3)
	v_bfe_u32 v3, v8, 16, 1
	v_lshrrev_b32_e32 v2, 16, v2
	v_add3_u32 v3, v8, v3, s46
	ds_read2_b32 v[16:17], v24 offset0:69 offset1:77
	v_and_or_b32 v2, v3, s47, v2
	s_waitcnt lgkmcnt(3)
	v_bfe_u32 v3, v10, 16, 1
	v_add3_u32 v3, v10, v3, s46
	s_waitcnt lgkmcnt(2)
	v_bfe_u32 v4, v12, 16, 1
	ds_read2_b32 v[18:19], v24 offset0:134 offset1:142
	v_lshrrev_b32_e32 v3, 16, v3
	v_add3_u32 v4, v12, v4, s46
	ds_read2_b32 v[20:21], v24 offset0:199 offset1:207
	v_and_or_b32 v3, v4, s47, v3
	s_waitcnt lgkmcnt(3)
	v_bfe_u32 v4, v14, 16, 1
	v_add3_u32 v4, v14, v4, s46
	s_waitcnt lgkmcnt(2)
	v_bfe_u32 v5, v16, 16, 1
	v_lshrrev_b32_e32 v4, 16, v4
	v_add3_u32 v5, v16, v5, s46
	v_and_or_b32 v4, v5, s47, v4
	s_waitcnt lgkmcnt(1)
	v_bfe_u32 v5, v18, 16, 1
	v_add3_u32 v5, v18, v5, s46
	s_waitcnt lgkmcnt(0)
	v_bfe_u32 v6, v20, 16, 1
	v_lshrrev_b32_e32 v5, 16, v5
	v_add3_u32 v6, v20, v6, s46
	v_lshlrev_b32_e32 v0, 1, v66
	v_and_or_b32 v5, v6, s47, v5
	v_or_b32_e32 v6, s8, v90
	v_lshl_add_u64 v[0:1], s[16:17], 0, v[0:1]
	v_lshlrev_b32_e32 v22, 12, v6
	v_lshl_add_u64 v[22:23], v[0:1], 0, v[22:23]
	global_store_dwordx4 v[22:23], v[2:5], off
	v_bfe_u32 v6, v21, 16, 1
	v_add3_u32 v6, v21, v6, s46
	v_bfe_u32 v2, v7, 16, 1
	v_add3_u32 v2, v7, v2, s46
	v_bfe_u32 v3, v9, 16, 1
	v_lshrrev_b32_e32 v2, 16, v2
	v_add3_u32 v3, v9, v3, s46
	v_and_or_b32 v2, v3, s47, v2
	v_bfe_u32 v3, v11, 16, 1
	v_add3_u32 v3, v11, v3, s46
	v_bfe_u32 v4, v13, 16, 1
	v_lshrrev_b32_e32 v3, 16, v3
	v_add3_u32 v4, v13, v4, s46
	v_and_or_b32 v3, v4, s47, v3
	v_bfe_u32 v4, v15, 16, 1
	v_add3_u32 v4, v15, v4, s46
	v_bfe_u32 v5, v17, 16, 1
	v_lshrrev_b32_e32 v4, 16, v4
	v_add3_u32 v5, v17, v5, s46
	v_and_or_b32 v4, v5, s47, v4
	v_bfe_u32 v5, v19, 16, 1
	v_add3_u32 v5, v19, v5, s46
	v_lshrrev_b32_e32 v5, 16, v5
	v_and_or_b32 v5, v6, s47, v5
	v_or_b32_e32 v6, s8, v92
	v_lshlrev_b32_e32 v6, 12, v6
	v_mov_b32_e32 v7, v65
	ds_read2_b32 v[8:9], v91 offset0:16 offset1:24
	v_lshl_add_u64 v[6:7], v[0:1], 0, v[6:7]
	global_store_dwordx4 v[6:7], v[2:5], off
	ds_read2_b32 v[6:7], v91 offset0:81 offset1:89
	ds_read2_b32 v[10:11], v91 offset0:146 offset1:154
	ds_read2_b32 v[12:13], v91 offset0:211 offset1:219
	s_waitcnt lgkmcnt(3)
	v_bfe_u32 v2, v8, 16, 1
	v_add3_u32 v2, v8, v2, s46
	s_waitcnt lgkmcnt(2)
	v_bfe_u32 v3, v6, 16, 1
	ds_read2_b32 v[14:15], v24 offset0:20 offset1:28
	v_lshrrev_b32_e32 v2, 16, v2
	v_add3_u32 v3, v6, v3, s46
	ds_read2_b32 v[16:17], v24 offset0:85 offset1:93
	v_and_or_b32 v2, v3, s47, v2
	s_waitcnt lgkmcnt(3)
	v_bfe_u32 v3, v10, 16, 1
	v_add3_u32 v3, v10, v3, s46
	s_waitcnt lgkmcnt(2)
	v_bfe_u32 v4, v12, 16, 1
	ds_read2_b32 v[18:19], v24 offset0:150 offset1:158
	v_lshrrev_b32_e32 v3, 16, v3
	v_add3_u32 v4, v12, v4, s46
	ds_read2_b32 v[20:21], v24 offset0:215 offset1:223
	v_and_or_b32 v3, v4, s47, v3
	s_waitcnt lgkmcnt(3)
	v_bfe_u32 v4, v14, 16, 1
	v_add3_u32 v4, v14, v4, s46
	s_waitcnt lgkmcnt(2)
	v_bfe_u32 v5, v16, 16, 1
	v_lshrrev_b32_e32 v4, 16, v4
	v_add3_u32 v5, v16, v5, s46
	v_and_or_b32 v4, v5, s47, v4
	s_waitcnt lgkmcnt(1)
	v_bfe_u32 v5, v18, 16, 1
	v_add3_u32 v5, v18, v5, s46
	s_waitcnt lgkmcnt(0)
	v_bfe_u32 v6, v20, 16, 1
	v_lshrrev_b32_e32 v5, 16, v5
	v_add3_u32 v6, v20, v6, s46
	v_and_or_b32 v5, v6, s47, v5
	v_or_b32_e32 v6, s8, v93
	v_lshlrev_b32_e32 v22, 12, v6
	v_mov_b32_e32 v23, v65
	v_lshl_add_u64 v[22:23], v[0:1], 0, v[22:23]
	global_store_dwordx4 v[22:23], v[2:5], off
	v_bfe_u32 v6, v21, 16, 1
	v_add3_u32 v6, v21, v6, s46
	v_bfe_u32 v2, v9, 16, 1
	v_add3_u32 v2, v9, v2, s46
	v_bfe_u32 v3, v7, 16, 1
	v_lshrrev_b32_e32 v2, 16, v2
	v_add3_u32 v3, v7, v3, s46
	v_and_or_b32 v2, v3, s47, v2
	v_bfe_u32 v3, v11, 16, 1
	v_add3_u32 v3, v11, v3, s46
	v_bfe_u32 v4, v13, 16, 1
	v_lshrrev_b32_e32 v3, 16, v3
	v_add3_u32 v4, v13, v4, s46
	v_and_or_b32 v3, v4, s47, v3
	v_bfe_u32 v4, v15, 16, 1
	v_add3_u32 v4, v15, v4, s46
	v_bfe_u32 v5, v17, 16, 1
	v_lshrrev_b32_e32 v4, 16, v4
	v_add3_u32 v5, v17, v5, s46
	v_and_or_b32 v4, v5, s47, v4
	v_bfe_u32 v5, v19, 16, 1
	v_add3_u32 v5, v19, v5, s46
	v_lshrrev_b32_e32 v5, 16, v5
	v_and_or_b32 v5, v6, s47, v5
	v_or_b32_e32 v6, s8, v94
	v_lshlrev_b32_e32 v6, 12, v6
	v_mov_b32_e32 v7, v65
	ds_read2_b32 v[8:9], v91 offset0:32 offset1:40
	v_lshl_add_u64 v[6:7], v[0:1], 0, v[6:7]
	global_store_dwordx4 v[6:7], v[2:5], off
	ds_read2_b32 v[6:7], v91 offset0:97 offset1:105
	ds_read2_b32 v[10:11], v91 offset0:162 offset1:170
	ds_read2_b32 v[12:13], v91 offset0:227 offset1:235
	s_waitcnt lgkmcnt(3)
	v_bfe_u32 v2, v8, 16, 1
	v_add3_u32 v2, v8, v2, s46
	s_waitcnt lgkmcnt(2)
	v_bfe_u32 v3, v6, 16, 1
	ds_read2_b32 v[14:15], v24 offset0:36 offset1:44
	v_lshrrev_b32_e32 v2, 16, v2
	v_add3_u32 v3, v6, v3, s46
	ds_read2_b32 v[16:17], v24 offset0:101 offset1:109
	v_and_or_b32 v2, v3, s47, v2
	s_waitcnt lgkmcnt(3)
	v_bfe_u32 v3, v10, 16, 1
	v_add3_u32 v3, v10, v3, s46
	s_waitcnt lgkmcnt(2)
	v_bfe_u32 v4, v12, 16, 1
	ds_read2_b32 v[18:19], v24 offset0:166 offset1:174
	v_lshrrev_b32_e32 v3, 16, v3
	v_add3_u32 v4, v12, v4, s46
	ds_read2_b32 v[20:21], v24 offset0:231 offset1:239
	v_and_or_b32 v3, v4, s47, v3
	s_waitcnt lgkmcnt(3)
	v_bfe_u32 v4, v14, 16, 1
	v_add3_u32 v4, v14, v4, s46
	s_waitcnt lgkmcnt(2)
	v_bfe_u32 v5, v16, 16, 1
	v_lshrrev_b32_e32 v4, 16, v4
	v_add3_u32 v5, v16, v5, s46
	v_and_or_b32 v4, v5, s47, v4
	s_waitcnt lgkmcnt(1)
	v_bfe_u32 v5, v18, 16, 1
	v_add3_u32 v5, v18, v5, s46
	s_waitcnt lgkmcnt(0)
	v_bfe_u32 v6, v20, 16, 1
	v_lshrrev_b32_e32 v5, 16, v5
	v_add3_u32 v6, v20, v6, s46
	v_and_or_b32 v5, v6, s47, v5
	v_or_b32_e32 v6, s8, v95
	v_lshlrev_b32_e32 v22, 12, v6
	v_mov_b32_e32 v23, v65
	v_lshl_add_u64 v[22:23], v[0:1], 0, v[22:23]
	global_store_dwordx4 v[22:23], v[2:5], off
	v_bfe_u32 v6, v21, 16, 1
	v_add3_u32 v6, v21, v6, s46
	v_bfe_u32 v2, v9, 16, 1
	v_add3_u32 v2, v9, v2, s46
	v_bfe_u32 v3, v7, 16, 1
	v_lshrrev_b32_e32 v2, 16, v2
	v_add3_u32 v3, v7, v3, s46
	v_and_or_b32 v2, v3, s47, v2
	v_bfe_u32 v3, v11, 16, 1
	v_add3_u32 v3, v11, v3, s46
	v_bfe_u32 v4, v13, 16, 1
	v_lshrrev_b32_e32 v3, 16, v3
	v_add3_u32 v4, v13, v4, s46
	v_and_or_b32 v3, v4, s47, v3
	v_bfe_u32 v4, v15, 16, 1
	v_add3_u32 v4, v15, v4, s46
	v_bfe_u32 v5, v17, 16, 1
	v_lshrrev_b32_e32 v4, 16, v4
	v_add3_u32 v5, v17, v5, s46
	v_and_or_b32 v4, v5, s47, v4
	v_bfe_u32 v5, v19, 16, 1
	v_add3_u32 v5, v19, v5, s46
	v_lshrrev_b32_e32 v5, 16, v5
	v_and_or_b32 v5, v6, s47, v5
	v_or_b32_e32 v6, s8, v96
	v_lshlrev_b32_e32 v6, 12, v6
	v_mov_b32_e32 v7, v65
	ds_read2_b32 v[8:9], v91 offset0:48 offset1:56
	v_lshl_add_u64 v[6:7], v[0:1], 0, v[6:7]
	global_store_dwordx4 v[6:7], v[2:5], off
	ds_read2_b32 v[6:7], v91 offset0:113 offset1:121
	ds_read2_b32 v[10:11], v91 offset0:178 offset1:186
	ds_read2_b32 v[12:13], v91 offset0:243 offset1:251
	s_waitcnt lgkmcnt(3)
	v_bfe_u32 v2, v8, 16, 1
	v_add3_u32 v2, v8, v2, s46
	s_waitcnt lgkmcnt(2)
	v_bfe_u32 v3, v6, 16, 1
	ds_read2_b32 v[14:15], v24 offset0:52 offset1:60
	v_lshrrev_b32_e32 v2, 16, v2
	v_add3_u32 v3, v6, v3, s46
	ds_read2_b32 v[16:17], v24 offset0:117 offset1:125
	v_and_or_b32 v2, v3, s47, v2
	s_waitcnt lgkmcnt(3)
	v_bfe_u32 v3, v10, 16, 1
	v_add3_u32 v3, v10, v3, s46
	s_waitcnt lgkmcnt(2)
	v_bfe_u32 v4, v12, 16, 1
	ds_read2_b32 v[18:19], v24 offset0:182 offset1:190
	v_lshrrev_b32_e32 v3, 16, v3
	v_add3_u32 v4, v12, v4, s46
	ds_read2_b32 v[20:21], v24 offset0:247 offset1:255
	v_and_or_b32 v3, v4, s47, v3
	s_waitcnt lgkmcnt(3)
	v_bfe_u32 v4, v14, 16, 1
	v_add3_u32 v4, v14, v4, s46
	s_waitcnt lgkmcnt(2)
	v_bfe_u32 v5, v16, 16, 1
	v_lshrrev_b32_e32 v4, 16, v4
	v_add3_u32 v5, v16, v5, s46
	v_and_or_b32 v4, v5, s47, v4
	s_waitcnt lgkmcnt(1)
	v_bfe_u32 v5, v18, 16, 1
	v_add3_u32 v5, v18, v5, s46
	s_waitcnt lgkmcnt(0)
	v_bfe_u32 v6, v20, 16, 1
	v_lshrrev_b32_e32 v5, 16, v5
	v_add3_u32 v6, v20, v6, s46
	v_and_or_b32 v5, v6, s47, v5
	v_or_b32_e32 v6, s8, v97
	v_lshlrev_b32_e32 v22, 12, v6
	v_mov_b32_e32 v23, v65
	v_lshl_add_u64 v[22:23], v[0:1], 0, v[22:23]
	global_store_dwordx4 v[22:23], v[2:5], off
	v_bfe_u32 v6, v21, 16, 1
	v_add3_u32 v6, v21, v6, s46
	v_bfe_u32 v2, v9, 16, 1
	v_add3_u32 v2, v9, v2, s46
	v_bfe_u32 v3, v7, 16, 1
	v_lshrrev_b32_e32 v2, 16, v2
	v_add3_u32 v3, v7, v3, s46
	v_and_or_b32 v2, v3, s47, v2
	v_bfe_u32 v3, v11, 16, 1
	v_add3_u32 v3, v11, v3, s46
	v_bfe_u32 v4, v13, 16, 1
	v_lshrrev_b32_e32 v3, 16, v3
	v_add3_u32 v4, v13, v4, s46
	v_and_or_b32 v3, v4, s47, v3
	v_bfe_u32 v4, v15, 16, 1
	v_add3_u32 v4, v15, v4, s46
	v_bfe_u32 v5, v17, 16, 1
	v_lshrrev_b32_e32 v4, 16, v4
	v_add3_u32 v5, v17, v5, s46
	v_and_or_b32 v4, v5, s47, v4
	v_bfe_u32 v5, v19, 16, 1
	v_add3_u32 v5, v19, v5, s46
	v_lshrrev_b32_e32 v5, 16, v5
	v_and_or_b32 v5, v6, s47, v5
	v_or_b32_e32 v6, s8, v98
	v_lshlrev_b32_e32 v6, 12, v6
	v_mov_b32_e32 v7, v65
	v_lshl_add_u64 v[0:1], v[0:1], 0, v[6:7]
	global_store_dwordx4 v[0:1], v[2:5], off
	s_waitcnt lgkmcnt(0)

.LBB0_138:
	s_andn2_b64 vcc, exec, s[16:17]
	s_cbranch_vccnz .LBB0_140
	s_load_dwordx2 s[62:63], s[2:3], 0x90
	s_lshl_b32 s16, s60, 6
	s_add_i32 s8, s19, 0x12000
	s_and_b32 s16, s16, 0xfc0
	s_and_b32 s8, s8, 0xffc0
	s_lshl_b32 s17, s16, 2
	v_or_b32_e32 v60, s8, v88
	s_waitcnt lgkmcnt(0)
	s_add_u32 s62, s62, s17
	s_addc_u32 s63, s63, 0
	v_or_b32_e32 v24, 4, v60
	v_or_b32_e32 v30, 8, v60
	v_or_b32_e32 v31, 12, v60
	v_or_b32_e32 v32, 16, v60
	v_or_b32_e32 v33, 20, v60
	v_or_b32_e32 v35, 24, v60
	v_or_b32_e32 v37, 28, v60
	v_lshl_add_u64 v[56:57], s[62:63], 0, v[64:65]
	v_lshlrev_b32_e32 v0, 14, v60
	v_mov_b32_e32 v1, v65
	v_lshlrev_b32_e32 v2, 14, v24
	v_mov_b32_e32 v3, v65
	v_lshlrev_b32_e32 v8, 14, v30
	v_mov_b32_e32 v9, v65
	v_lshlrev_b32_e32 v10, 14, v31
	v_mov_b32_e32 v11, v65
	v_lshlrev_b32_e32 v16, 14, v32
	v_mov_b32_e32 v17, v65
	v_lshlrev_b32_e32 v18, 14, v33
	v_mov_b32_e32 v19, v65
	v_lshlrev_b32_e32 v36, 2, v24
	v_lshlrev_b32_e32 v24, 14, v35
	v_mov_b32_e32 v25, v65
	v_lshlrev_b32_e32 v26, 14, v37
	v_mov_b32_e32 v27, v65
	v_lshl_add_u64 v[0:1], v[56:57], 0, v[0:1]
	v_lshl_add_u64 v[2:3], v[56:57], 0, v[2:3]
	v_lshl_add_u64 v[8:9], v[56:57], 0, v[8:9]
	v_lshl_add_u64 v[10:11], v[56:57], 0, v[10:11]
	v_lshl_add_u64 v[16:17], v[56:57], 0, v[16:17]
	v_lshl_add_u64 v[20:21], v[56:57], 0, v[18:19]
	v_lshlrev_b32_e32 v34, 2, v60
	v_lshl_add_u64 v[24:25], v[56:57], 0, v[24:25]
	v_lshl_add_u64 v[28:29], v[56:57], 0, v[26:27]
	v_lshlrev_b32_e32 v32, 2, v32
	v_lshlrev_b32_e32 v33, 2, v33
	v_lshlrev_b32_e32 v35, 2, v35
	v_or_b32_e32 v73, 32, v60
	v_or_b32_e32 v75, 36, v60
	v_or_b32_e32 v77, 40, v60
	v_or_b32_e32 v79, 44, v60
	v_or_b32_e32 v81, 48, v60
	v_or_b32_e32 v83, 52, v60
	v_or_b32_e32 v85, 56, v60
	v_or_b32_e32 v87, 60, v60
	global_load_dwordx4 v[4:7], v[0:1], off nt
	s_nop 0
	global_load_dwordx4 v[0:3], v[2:3], off nt
	s_nop 0
	global_load_dwordx4 v[12:15], v[8:9], off nt
	s_nop 0
	global_load_dwordx4 v[8:11], v[10:11], off nt
	s_nop 0
	global_load_dwordx4 v[16:19], v[16:17], off nt
	s_nop 0
	global_load_dwordx4 v[20:23], v[20:21], off nt
	v_lshlrev_b32_e32 v38, 2, v30
	v_lshlrev_b32_e32 v39, 2, v31
	global_load_dwordx4 v[24:27], v[24:25], off nt
	s_nop 0
	global_load_dwordx4 v[28:31], v[28:29], off nt
	v_lshlrev_b32_e32 v37, 2, v37
	global_load_dword v126, v34, s[10:11]
	global_load_dword v128, v36, s[10:11]
	global_load_dword v130, v38, s[10:11]
	global_load_dword v132, v39, s[10:11]
	global_load_dword v134, v32, s[10:11]
	global_load_dword v136, v33, s[10:11]
	global_load_dword v138, v35, s[10:11]
	global_load_dword v140, v37, s[10:11]
	v_lshlrev_b32_e32 v32, 14, v73
	v_mov_b32_e32 v33, v65
	v_lshlrev_b32_e32 v34, 14, v75
	v_mov_b32_e32 v35, v65
	v_lshlrev_b32_e32 v40, 14, v77
	v_mov_b32_e32 v41, v65
	v_lshlrev_b32_e32 v42, 14, v79
	v_mov_b32_e32 v43, v65
	v_lshlrev_b32_e32 v48, 14, v81
	v_mov_b32_e32 v49, v65
	v_lshlrev_b32_e32 v50, 14, v83
	v_mov_b32_e32 v51, v65
	v_lshlrev_b32_e32 v58, 14, v85
	v_mov_b32_e32 v59, v65
	v_lshlrev_b32_e32 v60, 14, v87
	v_mov_b32_e32 v61, v65
	v_lshl_add_u64 v[32:33], v[56:57], 0, v[32:33]
	v_lshl_add_u64 v[36:37], v[56:57], 0, v[34:35]
	v_lshl_add_u64 v[40:41], v[56:57], 0, v[40:41]
	v_lshl_add_u64 v[44:45], v[56:57], 0, v[42:43]
	v_lshl_add_u64 v[48:49], v[56:57], 0, v[48:49]
	v_lshl_add_u64 v[52:53], v[56:57], 0, v[50:51]
	v_lshl_add_u64 v[58:59], v[56:57], 0, v[58:59]
	v_lshl_add_u64 v[60:61], v[56:57], 0, v[60:61]
	v_lshlrev_b32_e32 v73, 2, v73
	global_load_dwordx4 v[32:35], v[32:33], off nt
	s_nop 0
	global_load_dwordx4 v[36:39], v[36:37], off nt
	s_nop 0
	global_load_dwordx4 v[40:43], v[40:41], off nt
	s_nop 0
	global_load_dwordx4 v[44:47], v[44:45], off nt
	s_nop 0
	global_load_dwordx4 v[48:51], v[48:49], off nt
	s_nop 0
	global_load_dwordx4 v[52:55], v[52:53], off nt
	s_nop 0
	global_load_dwordx4 v[56:59], v[58:59], off nt
	s_nop 0
	global_load_dwordx4 v[60:63], v[60:61], off nt
	s_lshl_b32 s8, s8, 1
	global_load_dword v142, v73, s[10:11]
	v_lshlrev_b32_e32 v73, 2, v75
	global_load_dword v144, v73, s[10:11]
	v_lshlrev_b32_e32 v73, 2, v77
	global_load_dword v146, v73, s[10:11]
	v_lshlrev_b32_e32 v73, 2, v79
	global_load_dword v148, v73, s[10:11]
	v_lshlrev_b32_e32 v73, 2, v81
	global_load_dword v150, v73, s[10:11]
	v_lshlrev_b32_e32 v73, 2, v83
	global_load_dword v152, v73, s[10:11]
	v_lshlrev_b32_e32 v73, 2, v85
	global_load_dword v154, v73, s[10:11]
	v_lshlrev_b32_e32 v73, 2, v87
	global_load_dword v156, v73, s[10:11]
	s_waitcnt vmcnt(23)
	v_pk_mul_f32 v[4:5], v[4:5], v[126:127] op_sel_hi:[1,0]
	s_waitcnt vmcnt(22)
	v_pk_mul_f32 v[0:1], v[0:1], v[128:129] op_sel_hi:[1,0]
	v_pk_mul_f32 v[6:7], v[6:7], v[126:127] op_sel_hi:[1,0]
	v_pk_mul_f32 v[2:3], v[2:3], v[128:129] op_sel_hi:[1,0]
	s_waitcnt vmcnt(21)
	v_pk_mul_f32 v[14:15], v[14:15], v[130:131] op_sel_hi:[1,0]
	v_pk_mul_f32 v[12:13], v[12:13], v[130:131] op_sel_hi:[1,0]
	s_waitcnt vmcnt(20)
	v_pk_mul_f32 v[10:11], v[10:11], v[132:133] op_sel_hi:[1,0]
	v_pk_mul_f32 v[8:9], v[8:9], v[132:133] op_sel_hi:[1,0]
	s_waitcnt vmcnt(19)
	v_pk_mul_f32 v[18:19], v[18:19], v[134:135] op_sel_hi:[1,0]
	v_pk_mul_f32 v[16:17], v[16:17], v[134:135] op_sel_hi:[1,0]
	s_waitcnt vmcnt(18)
	v_pk_mul_f32 v[22:23], v[22:23], v[136:137] op_sel_hi:[1,0]
	v_pk_mul_f32 v[20:21], v[20:21], v[136:137] op_sel_hi:[1,0]
	s_waitcnt vmcnt(17)
	v_pk_mul_f32 v[26:27], v[26:27], v[138:139] op_sel_hi:[1,0]
	v_pk_mul_f32 v[24:25], v[24:25], v[138:139] op_sel_hi:[1,0]
	s_waitcnt vmcnt(16)
	v_pk_mul_f32 v[30:31], v[30:31], v[140:141] op_sel_hi:[1,0]
	v_pk_mul_f32 v[28:29], v[28:29], v[140:141] op_sel_hi:[1,0]
	s_waitcnt vmcnt(7)
	v_pk_mul_f32 v[34:35], v[34:35], v[142:143] op_sel_hi:[1,0]
	v_pk_mul_f32 v[32:33], v[32:33], v[142:143] op_sel_hi:[1,0]
	s_waitcnt vmcnt(6)
	v_pk_mul_f32 v[38:39], v[38:39], v[144:145] op_sel_hi:[1,0]
	v_pk_mul_f32 v[36:37], v[36:37], v[144:145] op_sel_hi:[1,0]
	s_waitcnt vmcnt(5)
	v_pk_mul_f32 v[42:43], v[42:43], v[146:147] op_sel_hi:[1,0]
	v_pk_mul_f32 v[40:41], v[40:41], v[146:147] op_sel_hi:[1,0]
	s_waitcnt vmcnt(4)
	v_pk_mul_f32 v[46:47], v[46:47], v[148:149] op_sel_hi:[1,0]
	v_pk_mul_f32 v[44:45], v[44:45], v[148:149] op_sel_hi:[1,0]
	s_waitcnt vmcnt(3)
	v_pk_mul_f32 v[50:51], v[50:51], v[150:151] op_sel_hi:[1,0]
	v_pk_mul_f32 v[48:49], v[48:49], v[150:151] op_sel_hi:[1,0]
	s_waitcnt vmcnt(2)
	v_pk_mul_f32 v[54:55], v[54:55], v[152:153] op_sel_hi:[1,0]
	v_pk_mul_f32 v[52:53], v[52:53], v[152:153] op_sel_hi:[1,0]
	s_waitcnt vmcnt(1)
	v_pk_mul_f32 v[58:59], v[58:59], v[154:155] op_sel_hi:[1,0]
	v_pk_mul_f32 v[56:57], v[56:57], v[154:155] op_sel_hi:[1,0]
	ds_write2_b32 v89, v4, v5 offset1:1
	ds_write2_b32 v89, v6, v7 offset0:2 offset1:3
	ds_write2_b32 v99, v0, v1 offset1:1
	ds_write2_b32 v100, v2, v3 offset1:1
	ds_write2_b32 v101, v12, v13 offset1:1
	ds_write2_b32 v102, v14, v15 offset1:1
	ds_write2_b32 v103, v8, v9 offset1:1
	ds_write2_b32 v104, v10, v11 offset1:1
	ds_write2_b32 v105, v16, v17 offset1:1
	ds_write2_b32 v106, v18, v19 offset1:1
	ds_write2_b32 v107, v20, v21 offset1:1
	ds_write2_b32 v108, v22, v23 offset1:1
	ds_write2_b32 v109, v24, v25 offset1:1
	ds_write2_b32 v110, v26, v27 offset1:1
	ds_write2_b32 v111, v28, v29 offset1:1
	ds_write2_b32 v112, v30, v31 offset1:1
	ds_write2_b32 v113, v32, v33 offset1:1
	ds_write2_b32 v114, v34, v35 offset1:1
	ds_write2_b32 v115, v36, v37 offset1:1
	ds_write2_b32 v116, v38, v39 offset1:1
	ds_write2_b32 v117, v40, v41 offset1:1
	ds_write2_b32 v118, v42, v43 offset1:1
	ds_write2_b32 v119, v44, v45 offset1:1
	ds_write2_b32 v120, v46, v47 offset1:1
	ds_write2_b32 v121, v48, v49 offset1:1
	ds_write2_b32 v122, v50, v51 offset1:1
	ds_write2_b32 v123, v52, v53 offset1:1
	ds_write2_b32 v124, v54, v55 offset1:1
	ds_write2_b32 v125, v56, v57 offset1:1
	v_add_u32_e32 v0, 0x38e8, v89
	s_waitcnt vmcnt(0)
	v_pk_mul_f32 v[60:61], v[60:61], v[156:157] op_sel_hi:[1,0]
	ds_write2_b32 v0, v58, v59 offset1:1
	v_add_u32_e32 v0, 0x3cf0, v89
	v_pk_mul_f32 v[62:63], v[62:63], v[156:157] op_sel_hi:[1,0]
	ds_write2_b32 v0, v60, v61 offset1:1
	v_add_u32_e32 v0, 0x3cf8, v89
	ds_write2_b32 v0, v62, v63 offset1:1
	s_waitcnt lgkmcnt(0)
	ds_read2_b32 v[6:7], v91 offset1:8
	ds_read2_b32 v[8:9], v91 offset0:65 offset1:73
	ds_read2_b32 v[10:11], v91 offset0:130 offset1:138
	ds_read2_b32 v[12:13], v91 offset0:195 offset1:203
	v_add_u32_e32 v24, 0x400, v91
	s_waitcnt lgkmcnt(3)
	v_bfe_u32 v2, v6, 16, 1
	v_add3_u32 v2, v6, v2, s46
	s_waitcnt lgkmcnt(2)
	v_bfe_u32 v3, v8, 16, 1
	ds_read2_b32 v[14:15], v24 offset0:4 offset1:12
	v_lshrrev_b32_e32 v2, 16, v2
	v_add3_u32 v3, v8, v3, s46
	ds_read2_b32 v[16:17], v24 offset0:69 offset1:77
	v_and_or_b32 v2, v3, s47, v2
	s_waitcnt lgkmcnt(3)
	v_bfe_u32 v3, v10, 16, 1
	v_add3_u32 v3, v10, v3, s46
	s_waitcnt lgkmcnt(2)
	v_bfe_u32 v4, v12, 16, 1
	ds_read2_b32 v[18:19], v24 offset0:134 offset1:142
	v_lshrrev_b32_e32 v3, 16, v3
	v_add3_u32 v4, v12, v4, s46
	ds_read2_b32 v[20:21], v24 offset0:199 offset1:207
	v_and_or_b32 v3, v4, s47, v3
	s_waitcnt lgkmcnt(3)
	v_bfe_u32 v4, v14, 16, 1
	v_add3_u32 v4, v14, v4, s46
	s_waitcnt lgkmcnt(2)
	v_bfe_u32 v5, v16, 16, 1
	v_lshrrev_b32_e32 v4, 16, v4
	v_add3_u32 v5, v16, v5, s46
	v_and_or_b32 v4, v5, s47, v4
	s_waitcnt lgkmcnt(1)
	v_bfe_u32 v5, v18, 16, 1
	v_add3_u32 v5, v18, v5, s46
	s_waitcnt lgkmcnt(0)
	v_bfe_u32 v6, v20, 16, 1
	v_lshrrev_b32_e32 v5, 16, v5
	v_add3_u32 v6, v20, v6, s46
	v_and_or_b32 v5, v6, s47, v5
	v_or_b32_e32 v6, s16, v90
	v_lshl_add_u64 v[0:1], v[68:69], 0, s[8:9]
	v_lshlrev_b32_e32 v22, 12, v6
	v_mov_b32_e32 v23, v65
	v_lshl_add_u64 v[22:23], v[0:1], 0, v[22:23]
	global_store_dwordx4 v[22:23], v[2:5], off
	v_bfe_u32 v6, v21, 16, 1
	v_add3_u32 v6, v21, v6, s46
	v_bfe_u32 v2, v7, 16, 1
	v_add3_u32 v2, v7, v2, s46
	v_bfe_u32 v3, v9, 16, 1
	v_lshrrev_b32_e32 v2, 16, v2
	v_add3_u32 v3, v9, v3, s46
	v_and_or_b32 v2, v3, s47, v2
	v_bfe_u32 v3, v11, 16, 1
	v_add3_u32 v3, v11, v3, s46
	v_bfe_u32 v4, v13, 16, 1
	v_lshrrev_b32_e32 v3, 16, v3
	v_add3_u32 v4, v13, v4, s46
	v_and_or_b32 v3, v4, s47, v3
	v_bfe_u32 v4, v15, 16, 1
	v_add3_u32 v4, v15, v4, s46
	v_bfe_u32 v5, v17, 16, 1
	v_lshrrev_b32_e32 v4, 16, v4
	v_add3_u32 v5, v17, v5, s46
	v_and_or_b32 v4, v5, s47, v4
	v_bfe_u32 v5, v19, 16, 1
	v_add3_u32 v5, v19, v5, s46
	v_lshrrev_b32_e32 v5, 16, v5
	v_and_or_b32 v5, v6, s47, v5
	v_or_b32_e32 v6, s16, v92
	v_lshlrev_b32_e32 v6, 12, v6
	v_mov_b32_e32 v7, v65
	ds_read2_b32 v[8:9], v91 offset0:16 offset1:24
	v_lshl_add_u64 v[6:7], v[0:1], 0, v[6:7]
	global_store_dwordx4 v[6:7], v[2:5], off
	ds_read2_b32 v[6:7], v91 offset0:81 offset1:89
	ds_read2_b32 v[10:11], v91 offset0:146 offset1:154
	ds_read2_b32 v[12:13], v91 offset0:211 offset1:219
	s_waitcnt lgkmcnt(3)
	v_bfe_u32 v2, v8, 16, 1
	v_add3_u32 v2, v8, v2, s46
	s_waitcnt lgkmcnt(2)
	v_bfe_u32 v3, v6, 16, 1
	ds_read2_b32 v[14:15], v24 offset0:20 offset1:28
	v_lshrrev_b32_e32 v2, 16, v2
	v_add3_u32 v3, v6, v3, s46
	ds_read2_b32 v[16:17], v24 offset0:85 offset1:93
	v_and_or_b32 v2, v3, s47, v2
	s_waitcnt lgkmcnt(3)
	v_bfe_u32 v3, v10, 16, 1
	v_add3_u32 v3, v10, v3, s46
	s_waitcnt lgkmcnt(2)
	v_bfe_u32 v4, v12, 16, 1
	ds_read2_b32 v[18:19], v24 offset0:150 offset1:158
	v_lshrrev_b32_e32 v3, 16, v3
	v_add3_u32 v4, v12, v4, s46
	ds_read2_b32 v[20:21], v24 offset0:215 offset1:223
	v_and_or_b32 v3, v4, s47, v3
	s_waitcnt lgkmcnt(3)
	v_bfe_u32 v4, v14, 16, 1
	v_add3_u32 v4, v14, v4, s46
	s_waitcnt lgkmcnt(2)
	v_bfe_u32 v5, v16, 16, 1
	v_lshrrev_b32_e32 v4, 16, v4
	v_add3_u32 v5, v16, v5, s46
	v_and_or_b32 v4, v5, s47, v4
	s_waitcnt lgkmcnt(1)
	v_bfe_u32 v5, v18, 16, 1
	v_add3_u32 v5, v18, v5, s46
	s_waitcnt lgkmcnt(0)
	v_bfe_u32 v6, v20, 16, 1
	v_lshrrev_b32_e32 v5, 16, v5
	v_add3_u32 v6, v20, v6, s46
	v_and_or_b32 v5, v6, s47, v5
	v_or_b32_e32 v6, s16, v93
	v_lshlrev_b32_e32 v22, 12, v6
	v_mov_b32_e32 v23, v65
	v_lshl_add_u64 v[22:23], v[0:1], 0, v[22:23]
	global_store_dwordx4 v[22:23], v[2:5], off
	v_bfe_u32 v6, v21, 16, 1
	v_add3_u32 v6, v21, v6, s46
	v_bfe_u32 v2, v9, 16, 1
	v_add3_u32 v2, v9, v2, s46
	v_bfe_u32 v3, v7, 16, 1
	v_lshrrev_b32_e32 v2, 16, v2
	v_add3_u32 v3, v7, v3, s46
	v_and_or_b32 v2, v3, s47, v2
	v_bfe_u32 v3, v11, 16, 1
	v_add3_u32 v3, v11, v3, s46
	v_bfe_u32 v4, v13, 16, 1
	v_lshrrev_b32_e32 v3, 16, v3
	v_add3_u32 v4, v13, v4, s46
	v_and_or_b32 v3, v4, s47, v3
	v_bfe_u32 v4, v15, 16, 1
	v_add3_u32 v4, v15, v4, s46
	v_bfe_u32 v5, v17, 16, 1
	v_lshrrev_b32_e32 v4, 16, v4
	v_add3_u32 v5, v17, v5, s46
	v_and_or_b32 v4, v5, s47, v4
	v_bfe_u32 v5, v19, 16, 1
	v_add3_u32 v5, v19, v5, s46
	v_lshrrev_b32_e32 v5, 16, v5
	v_and_or_b32 v5, v6, s47, v5
	v_or_b32_e32 v6, s16, v94
	v_lshlrev_b32_e32 v6, 12, v6
	v_mov_b32_e32 v7, v65
	ds_read2_b32 v[8:9], v91 offset0:32 offset1:40
	v_lshl_add_u64 v[6:7], v[0:1], 0, v[6:7]
	global_store_dwordx4 v[6:7], v[2:5], off
	ds_read2_b32 v[6:7], v91 offset0:97 offset1:105
	ds_read2_b32 v[10:11], v91 offset0:162 offset1:170
	ds_read2_b32 v[12:13], v91 offset0:227 offset1:235
	s_waitcnt lgkmcnt(3)
	v_bfe_u32 v2, v8, 16, 1
	v_add3_u32 v2, v8, v2, s46
	s_waitcnt lgkmcnt(2)
	v_bfe_u32 v3, v6, 16, 1
	ds_read2_b32 v[14:15], v24 offset0:36 offset1:44
	v_lshrrev_b32_e32 v2, 16, v2
	v_add3_u32 v3, v6, v3, s46
	ds_read2_b32 v[16:17], v24 offset0:101 offset1:109
	v_and_or_b32 v2, v3, s47, v2
	s_waitcnt lgkmcnt(3)
	v_bfe_u32 v3, v10, 16, 1
	v_add3_u32 v3, v10, v3, s46
	s_waitcnt lgkmcnt(2)
	v_bfe_u32 v4, v12, 16, 1
	ds_read2_b32 v[18:19], v24 offset0:166 offset1:174
	v_lshrrev_b32_e32 v3, 16, v3
	v_add3_u32 v4, v12, v4, s46
	ds_read2_b32 v[20:21], v24 offset0:231 offset1:239
	v_and_or_b32 v3, v4, s47, v3
	s_waitcnt lgkmcnt(3)
	v_bfe_u32 v4, v14, 16, 1
	v_add3_u32 v4, v14, v4, s46
	s_waitcnt lgkmcnt(2)
	v_bfe_u32 v5, v16, 16, 1
	v_lshrrev_b32_e32 v4, 16, v4
	v_add3_u32 v5, v16, v5, s46
	v_and_or_b32 v4, v5, s47, v4
	s_waitcnt lgkmcnt(1)
	v_bfe_u32 v5, v18, 16, 1
	v_add3_u32 v5, v18, v5, s46
	s_waitcnt lgkmcnt(0)
	v_bfe_u32 v6, v20, 16, 1
	v_lshrrev_b32_e32 v5, 16, v5
	v_add3_u32 v6, v20, v6, s46
	v_and_or_b32 v5, v6, s47, v5
	v_or_b32_e32 v6, s16, v95
	v_lshlrev_b32_e32 v22, 12, v6
	v_mov_b32_e32 v23, v65
	v_lshl_add_u64 v[22:23], v[0:1], 0, v[22:23]
	global_store_dwordx4 v[22:23], v[2:5], off
	v_bfe_u32 v6, v21, 16, 1
	v_add3_u32 v6, v21, v6, s46
	v_bfe_u32 v2, v9, 16, 1
	v_add3_u32 v2, v9, v2, s46
	v_bfe_u32 v3, v7, 16, 1
	v_lshrrev_b32_e32 v2, 16, v2
	v_add3_u32 v3, v7, v3, s46
	v_and_or_b32 v2, v3, s47, v2
	v_bfe_u32 v3, v11, 16, 1
	v_add3_u32 v3, v11, v3, s46
	v_bfe_u32 v4, v13, 16, 1
	v_lshrrev_b32_e32 v3, 16, v3
	v_add3_u32 v4, v13, v4, s46
	v_and_or_b32 v3, v4, s47, v3
	v_bfe_u32 v4, v15, 16, 1
	v_add3_u32 v4, v15, v4, s46
	v_bfe_u32 v5, v17, 16, 1
	v_lshrrev_b32_e32 v4, 16, v4
	v_add3_u32 v5, v17, v5, s46
	v_and_or_b32 v4, v5, s47, v4
	v_bfe_u32 v5, v19, 16, 1
	v_add3_u32 v5, v19, v5, s46
	v_lshrrev_b32_e32 v5, 16, v5
	v_and_or_b32 v5, v6, s47, v5
	v_or_b32_e32 v6, s16, v96
	v_lshlrev_b32_e32 v6, 12, v6
	v_mov_b32_e32 v7, v65
	ds_read2_b32 v[8:9], v91 offset0:48 offset1:56
	v_lshl_add_u64 v[6:7], v[0:1], 0, v[6:7]
	global_store_dwordx4 v[6:7], v[2:5], off
	ds_read2_b32 v[6:7], v91 offset0:113 offset1:121
	ds_read2_b32 v[10:11], v91 offset0:178 offset1:186
	ds_read2_b32 v[12:13], v91 offset0:243 offset1:251
	s_waitcnt lgkmcnt(3)
	v_bfe_u32 v2, v8, 16, 1
	v_add3_u32 v2, v8, v2, s46
	s_waitcnt lgkmcnt(2)
	v_bfe_u32 v3, v6, 16, 1
	ds_read2_b32 v[14:15], v24 offset0:52 offset1:60
	v_lshrrev_b32_e32 v2, 16, v2
	v_add3_u32 v3, v6, v3, s46
	ds_read2_b32 v[16:17], v24 offset0:117 offset1:125
	v_and_or_b32 v2, v3, s47, v2
	s_waitcnt lgkmcnt(3)
	v_bfe_u32 v3, v10, 16, 1
	v_add3_u32 v3, v10, v3, s46
	s_waitcnt lgkmcnt(2)
	v_bfe_u32 v4, v12, 16, 1
	ds_read2_b32 v[18:19], v24 offset0:182 offset1:190
	v_lshrrev_b32_e32 v3, 16, v3
	v_add3_u32 v4, v12, v4, s46
	ds_read2_b32 v[20:21], v24 offset0:247 offset1:255
	v_and_or_b32 v3, v4, s47, v3
	s_waitcnt lgkmcnt(3)
	v_bfe_u32 v4, v14, 16, 1
	v_add3_u32 v4, v14, v4, s46
	s_waitcnt lgkmcnt(2)
	v_bfe_u32 v5, v16, 16, 1
	v_lshrrev_b32_e32 v4, 16, v4
	v_add3_u32 v5, v16, v5, s46
	v_and_or_b32 v4, v5, s47, v4
	s_waitcnt lgkmcnt(1)
	v_bfe_u32 v5, v18, 16, 1
	v_add3_u32 v5, v18, v5, s46
	s_waitcnt lgkmcnt(0)
	v_bfe_u32 v6, v20, 16, 1
	v_lshrrev_b32_e32 v5, 16, v5
	v_add3_u32 v6, v20, v6, s46
	v_and_or_b32 v5, v6, s47, v5
	v_or_b32_e32 v6, s16, v97
	v_lshlrev_b32_e32 v22, 12, v6
	v_mov_b32_e32 v23, v65
	v_lshl_add_u64 v[22:23], v[0:1], 0, v[22:23]
	global_store_dwordx4 v[22:23], v[2:5], off
	v_bfe_u32 v6, v21, 16, 1
	v_add3_u32 v6, v21, v6, s46
	v_bfe_u32 v2, v9, 16, 1
	v_add3_u32 v2, v9, v2, s46
	v_bfe_u32 v3, v7, 16, 1
	v_lshrrev_b32_e32 v2, 16, v2
	v_add3_u32 v3, v7, v3, s46
	v_and_or_b32 v2, v3, s47, v2
	v_bfe_u32 v3, v11, 16, 1
	v_add3_u32 v3, v11, v3, s46
	v_bfe_u32 v4, v13, 16, 1
	v_lshrrev_b32_e32 v3, 16, v3
	v_add3_u32 v4, v13, v4, s46
	v_and_or_b32 v3, v4, s47, v3
	v_bfe_u32 v4, v15, 16, 1
	v_add3_u32 v4, v15, v4, s46
	v_bfe_u32 v5, v17, 16, 1
	v_lshrrev_b32_e32 v4, 16, v4
	v_add3_u32 v5, v17, v5, s46
	v_and_or_b32 v4, v5, s47, v4
	v_bfe_u32 v5, v19, 16, 1
	v_add3_u32 v5, v19, v5, s46
	v_lshrrev_b32_e32 v5, 16, v5
	v_and_or_b32 v5, v6, s47, v5
	v_or_b32_e32 v6, s16, v98
	v_lshlrev_b32_e32 v6, 12, v6
	v_mov_b32_e32 v7, v65
	v_lshl_add_u64 v[0:1], v[0:1], 0, v[6:7]
	global_store_dwordx4 v[0:1], v[2:5], off
	s_waitcnt lgkmcnt(0)

.LBB0_141:
	s_andn2_b64 vcc, exec, s[16:17]
	s_cbranch_vccnz .LBB0_143
	s_load_dwordx2 s[62:63], s[2:3], 0x70
	s_add_i32 s19, s19, 0x13000
	s_lshl_b32 s16, s60, 6
	s_lshr_b32 s8, s19, 1
	s_and_b32 s16, s16, 0x1fc0
	s_and_b32 s8, s8, 0x7fc0
	s_lshl_b32 s17, s16, 2
	v_or_b32_e32 v73, s8, v88
	s_waitcnt lgkmcnt(0)
	s_add_u32 s62, s62, s17
	s_addc_u32 s63, s63, 0
	v_mul_u32_u24_e32 v0, 0x2010, v73
	v_lshl_add_u64 v[60:61], s[62:63], 0, v[64:65]
	v_lshlrev_b32_e32 v62, 2, v0
	v_mov_b32_e32 v63, v65
	v_lshl_add_u64 v[8:9], v[60:61], 0, v[62:63]
	v_add_co_u32_e32 v4, vcc, s48, v8
	v_add_u32_e32 v10, 0x60300, v62
	s_nop 0
	v_addc_co_u32_e32 v5, vcc, 0, v9, vcc
	global_load_dwordx4 v[0:3], v[8:9], off nt
	s_nop 0
	global_load_dwordx4 v[4:7], v[4:5], off offset:256
	v_add_co_u32_e32 v8, vcc, s52, v8
	v_mov_b32_e32 v11, v65
	v_add_u32_e32 v16, 0x80400, v62
	v_mov_b32_e32 v17, v65
	v_add_u32_e32 v18, 0xa0500, v62
	v_mov_b32_e32 v19, v65
	v_add_u32_e32 v24, 0xc0600, v62
	v_mov_b32_e32 v25, v65
	v_add_u32_e32 v26, 0xe0700, v62
	v_mov_b32_e32 v27, v65
	v_add_u32_e32 v32, 0x100800, v62
	v_mov_b32_e32 v33, v65
	v_add_u32_e32 v34, 0x120900, v62
	v_mov_b32_e32 v35, v65
	v_add_u32_e32 v40, 0x140a00, v62
	v_mov_b32_e32 v41, v65
	v_add_u32_e32 v42, 0x160b00, v62
	v_mov_b32_e32 v43, v65
	v_add_u32_e32 v48, 0x180c00, v62
	v_mov_b32_e32 v49, v65
	v_add_u32_e32 v50, 0x1a0d00, v62
	v_mov_b32_e32 v51, v65
	v_add_u32_e32 v56, 0x1c0e00, v62
	v_mov_b32_e32 v57, v65
	v_lshlrev_b32_e32 v73, 2, v73
	v_add_u32_e32 v62, 0x1e0f00, v62
	v_addc_co_u32_e32 v9, vcc, 0, v9, vcc
	v_lshl_add_u64 v[12:13], v[60:61], 0, v[10:11]
	v_lshl_add_u64 v[16:17], v[60:61], 0, v[16:17]
	v_lshl_add_u64 v[20:21], v[60:61], 0, v[18:19]
	v_lshl_add_u64 v[24:25], v[60:61], 0, v[24:25]
	v_lshl_add_u64 v[26:27], v[60:61], 0, v[26:27]
	v_lshl_add_u64 v[32:33], v[60:61], 0, v[32:33]
	v_lshl_add_u64 v[34:35], v[60:61], 0, v[34:35]
	v_lshl_add_u64 v[40:41], v[60:61], 0, v[40:41]
	v_lshl_add_u64 v[42:43], v[60:61], 0, v[42:43]
	v_lshl_add_u64 v[48:49], v[60:61], 0, v[48:49]
	v_lshl_add_u64 v[50:51], v[60:61], 0, v[50:51]
	v_lshl_add_u64 v[56:57], v[60:61], 0, v[56:57]
	v_lshl_add_u64 v[60:61], v[60:61], 0, v[62:63]
	v_or_b32_e32 v75, 16, v73
	global_load_dwordx4 v[8:11], v[8:9], off offset:512
	s_nop 0
	global_load_dwordx4 v[12:15], v[12:13], off nt
	s_nop 0
	global_load_dwordx4 v[16:19], v[16:17], off nt
	s_nop 0
	global_load_dwordx4 v[20:23], v[20:21], off nt
	s_nop 0
	global_load_dwordx4 v[28:31], v[24:25], off nt
	s_nop 0
	global_load_dwordx4 v[24:27], v[26:27], off nt
	s_nop 0
	global_load_dwordx4 v[36:39], v[32:33], off nt
	s_nop 0
	global_load_dwordx4 v[32:35], v[34:35], off nt
	s_nop 0
	global_load_dwordx4 v[44:47], v[40:41], off nt
	s_nop 0
	global_load_dwordx4 v[40:43], v[42:43], off nt
	s_nop 0
	global_load_dwordx4 v[52:55], v[48:49], off nt
	s_nop 0
	global_load_dwordx4 v[48:51], v[50:51], off nt
	s_lshl_b32 s8, s8, 1
	global_load_dwordx4 v[56:59], v[56:57], off nt
	s_nop 0
	global_load_dwordx4 v[60:63], v[60:61], off nt
	s_nop 0
	global_load_dword v126, v73, s[12:13]
	global_load_dword v128, v75, s[12:13]
	v_or_b32_e32 v75, 32, v73
	global_load_dword v130, v75, s[12:13]
	v_or_b32_e32 v75, 48, v73
	global_load_dword v132, v75, s[12:13]
	v_or_b32_e32 v75, 64, v73
	global_load_dword v134, v75, s[12:13]
	v_or_b32_e32 v75, 0x50, v73
	global_load_dword v136, v75, s[12:13]
	v_or_b32_e32 v75, 0x60, v73
	global_load_dword v138, v75, s[12:13]
	v_or_b32_e32 v75, 0x70, v73
	global_load_dword v140, v75, s[12:13]
	v_or_b32_e32 v75, 0x80, v73
	global_load_dword v142, v75, s[12:13]
	v_or_b32_e32 v75, 0x90, v73
	global_load_dword v144, v75, s[12:13]
	v_or_b32_e32 v75, 0xa0, v73
	global_load_dword v146, v75, s[12:13]
	v_or_b32_e32 v75, 0xb0, v73
	global_load_dword v148, v75, s[12:13]
	v_or_b32_e32 v75, 0xc0, v73
	global_load_dword v150, v75, s[12:13]
	v_or_b32_e32 v75, 0xd0, v73
	global_load_dword v152, v75, s[12:13]
	v_or_b32_e32 v75, 0xe0, v73
	global_load_dword v154, v75, s[12:13]
	v_or_b32_e32 v73, 0xf0, v73
	global_load_dword v156, v73, s[12:13]
	s_waitcnt vmcnt(15)
	v_pk_mul_f32 v[0:1], v[0:1], v[126:127] op_sel_hi:[1,0]
	v_pk_mul_f32 v[2:3], v[2:3], v[126:127] op_sel_hi:[1,0]
	s_waitcnt vmcnt(14)
	v_pk_mul_f32 v[6:7], v[6:7], v[128:129] op_sel_hi:[1,0]
	v_pk_mul_f32 v[4:5], v[4:5], v[128:129] op_sel_hi:[1,0]
	s_waitcnt vmcnt(13)
	v_pk_mul_f32 v[10:11], v[10:11], v[130:131] op_sel_hi:[1,0]
	v_pk_mul_f32 v[8:9], v[8:9], v[130:131] op_sel_hi:[1,0]
	s_waitcnt vmcnt(12)
	v_pk_mul_f32 v[14:15], v[14:15], v[132:133] op_sel_hi:[1,0]
	v_pk_mul_f32 v[12:13], v[12:13], v[132:133] op_sel_hi:[1,0]
	s_waitcnt vmcnt(11)
	v_pk_mul_f32 v[18:19], v[18:19], v[134:135] op_sel_hi:[1,0]
	v_pk_mul_f32 v[16:17], v[16:17], v[134:135] op_sel_hi:[1,0]
	s_waitcnt vmcnt(10)
	v_pk_mul_f32 v[22:23], v[22:23], v[136:137] op_sel_hi:[1,0]
	v_pk_mul_f32 v[20:21], v[20:21], v[136:137] op_sel_hi:[1,0]
	s_waitcnt vmcnt(9)
	v_pk_mul_f32 v[30:31], v[30:31], v[138:139] op_sel_hi:[1,0]
	v_pk_mul_f32 v[28:29], v[28:29], v[138:139] op_sel_hi:[1,0]
	s_waitcnt vmcnt(8)
	v_pk_mul_f32 v[26:27], v[26:27], v[140:141] op_sel_hi:[1,0]
	v_pk_mul_f32 v[24:25], v[24:25], v[140:141] op_sel_hi:[1,0]
	s_waitcnt vmcnt(7)
	v_pk_mul_f32 v[38:39], v[38:39], v[142:143] op_sel_hi:[1,0]
	v_pk_mul_f32 v[36:37], v[36:37], v[142:143] op_sel_hi:[1,0]
	s_waitcnt vmcnt(6)
	v_pk_mul_f32 v[34:35], v[34:35], v[144:145] op_sel_hi:[1,0]
	v_pk_mul_f32 v[32:33], v[32:33], v[144:145] op_sel_hi:[1,0]
	s_waitcnt vmcnt(5)
	v_pk_mul_f32 v[46:47], v[46:47], v[146:147] op_sel_hi:[1,0]
	v_pk_mul_f32 v[44:45], v[44:45], v[146:147] op_sel_hi:[1,0]
	s_waitcnt vmcnt(4)
	v_pk_mul_f32 v[42:43], v[42:43], v[148:149] op_sel_hi:[1,0]
	v_pk_mul_f32 v[40:41], v[40:41], v[148:149] op_sel_hi:[1,0]
	s_waitcnt vmcnt(3)
	v_pk_mul_f32 v[54:55], v[54:55], v[150:151] op_sel_hi:[1,0]
	v_pk_mul_f32 v[52:53], v[52:53], v[150:151] op_sel_hi:[1,0]
	s_waitcnt vmcnt(2)
	v_pk_mul_f32 v[50:51], v[50:51], v[152:153] op_sel_hi:[1,0]
	v_pk_mul_f32 v[48:49], v[48:49], v[152:153] op_sel_hi:[1,0]
	s_waitcnt vmcnt(1)
	v_pk_mul_f32 v[58:59], v[58:59], v[154:155] op_sel_hi:[1,0]
	v_pk_mul_f32 v[56:57], v[56:57], v[154:155] op_sel_hi:[1,0]
	ds_write2_b32 v89, v0, v1 offset1:1
	ds_write2_b32 v89, v2, v3 offset0:2 offset1:3
	ds_write2_b32 v99, v4, v5 offset1:1
	ds_write2_b32 v100, v6, v7 offset1:1
	ds_write2_b32 v101, v8, v9 offset1:1
	ds_write2_b32 v102, v10, v11 offset1:1
	ds_write2_b32 v103, v12, v13 offset1:1
	ds_write2_b32 v104, v14, v15 offset1:1
	ds_write2_b32 v105, v16, v17 offset1:1
	ds_write2_b32 v106, v18, v19 offset1:1
	ds_write2_b32 v107, v20, v21 offset1:1
	ds_write2_b32 v108, v22, v23 offset1:1
	ds_write2_b32 v109, v28, v29 offset1:1
	ds_write2_b32 v110, v30, v31 offset1:1
	ds_write2_b32 v111, v24, v25 offset1:1
	ds_write2_b32 v112, v26, v27 offset1:1
	ds_write2_b32 v113, v36, v37 offset1:1
	ds_write2_b32 v114, v38, v39 offset1:1
	ds_write2_b32 v115, v32, v33 offset1:1
	ds_write2_b32 v116, v34, v35 offset1:1
	ds_write2_b32 v117, v44, v45 offset1:1
	ds_write2_b32 v118, v46, v47 offset1:1
	ds_write2_b32 v119, v40, v41 offset1:1
	ds_write2_b32 v120, v42, v43 offset1:1
	ds_write2_b32 v121, v52, v53 offset1:1
	ds_write2_b32 v122, v54, v55 offset1:1
	ds_write2_b32 v123, v48, v49 offset1:1
	ds_write2_b32 v124, v50, v51 offset1:1
	ds_write2_b32 v125, v56, v57 offset1:1
	v_add_u32_e32 v0, 0x38e8, v89
	s_waitcnt vmcnt(0)
	v_pk_mul_f32 v[60:61], v[60:61], v[156:157] op_sel_hi:[1,0]
	ds_write2_b32 v0, v58, v59 offset1:1
	v_add_u32_e32 v0, 0x3cf0, v89
	v_pk_mul_f32 v[62:63], v[62:63], v[156:157] op_sel_hi:[1,0]
	ds_write2_b32 v0, v60, v61 offset1:1
	v_add_u32_e32 v0, 0x3cf8, v89
	ds_write2_b32 v0, v62, v63 offset1:1
	s_waitcnt lgkmcnt(0)
	ds_read2_b32 v[6:7], v91 offset1:8
	ds_read2_b32 v[8:9], v91 offset0:65 offset1:73
	ds_read2_b32 v[10:11], v91 offset0:130 offset1:138
	ds_read2_b32 v[12:13], v91 offset0:195 offset1:203
	v_add_u32_e32 v24, 0x400, v91
	s_waitcnt lgkmcnt(3)
	v_bfe_u32 v2, v6, 16, 1
	v_add3_u32 v2, v6, v2, s46
	s_waitcnt lgkmcnt(2)
	v_bfe_u32 v3, v8, 16, 1
	ds_read2_b32 v[14:15], v24 offset0:4 offset1:12
	v_lshrrev_b32_e32 v2, 16, v2
	v_add3_u32 v3, v8, v3, s46
	ds_read2_b32 v[16:17], v24 offset0:69 offset1:77
	v_and_or_b32 v2, v3, s47, v2
	s_waitcnt lgkmcnt(3)
	v_bfe_u32 v3, v10, 16, 1
	v_add3_u32 v3, v10, v3, s46
	s_waitcnt lgkmcnt(2)
	v_bfe_u32 v4, v12, 16, 1
	ds_read2_b32 v[18:19], v24 offset0:134 offset1:142
	v_lshrrev_b32_e32 v3, 16, v3
	v_add3_u32 v4, v12, v4, s46
	ds_read2_b32 v[20:21], v24 offset0:199 offset1:207
	v_and_or_b32 v3, v4, s47, v3
	s_waitcnt lgkmcnt(3)
	v_bfe_u32 v4, v14, 16, 1
	v_add3_u32 v4, v14, v4, s46
	s_waitcnt lgkmcnt(2)
	v_bfe_u32 v5, v16, 16, 1
	v_lshrrev_b32_e32 v4, 16, v4
	v_add3_u32 v5, v16, v5, s46
	v_and_or_b32 v4, v5, s47, v4
	s_waitcnt lgkmcnt(1)
	v_bfe_u32 v5, v18, 16, 1
	v_add3_u32 v5, v18, v5, s46
	s_waitcnt lgkmcnt(0)
	v_bfe_u32 v6, v20, 16, 1
	v_lshrrev_b32_e32 v5, 16, v5
	v_add3_u32 v6, v20, v6, s46
	v_and_or_b32 v5, v6, s47, v5
	v_or_b32_e32 v6, s16, v90
	v_lshl_add_u64 v[0:1], v[70:71], 0, s[8:9]
	v_lshlrev_b32_e32 v22, 12, v6
	v_mov_b32_e32 v23, v65
	v_lshl_add_u64 v[22:23], v[0:1], 0, v[22:23]
	global_store_dwordx4 v[22:23], v[2:5], off
	v_bfe_u32 v6, v21, 16, 1
	v_add3_u32 v6, v21, v6, s46
	v_bfe_u32 v2, v7, 16, 1
	v_add3_u32 v2, v7, v2, s46
	v_bfe_u32 v3, v9, 16, 1
	v_lshrrev_b32_e32 v2, 16, v2
	v_add3_u32 v3, v9, v3, s46
	v_and_or_b32 v2, v3, s47, v2
	v_bfe_u32 v3, v11, 16, 1
	v_add3_u32 v3, v11, v3, s46
	v_bfe_u32 v4, v13, 16, 1
	v_lshrrev_b32_e32 v3, 16, v3
	v_add3_u32 v4, v13, v4, s46
	v_and_or_b32 v3, v4, s47, v3
	v_bfe_u32 v4, v15, 16, 1
	v_add3_u32 v4, v15, v4, s46
	v_bfe_u32 v5, v17, 16, 1
	v_lshrrev_b32_e32 v4, 16, v4
	v_add3_u32 v5, v17, v5, s46
	v_and_or_b32 v4, v5, s47, v4
	v_bfe_u32 v5, v19, 16, 1
	v_add3_u32 v5, v19, v5, s46
	v_lshrrev_b32_e32 v5, 16, v5
	v_and_or_b32 v5, v6, s47, v5
	v_or_b32_e32 v6, s16, v92
	v_lshlrev_b32_e32 v6, 12, v6
	v_mov_b32_e32 v7, v65
	ds_read2_b32 v[8:9], v91 offset0:16 offset1:24
	v_lshl_add_u64 v[6:7], v[0:1], 0, v[6:7]
	global_store_dwordx4 v[6:7], v[2:5], off
	ds_read2_b32 v[6:7], v91 offset0:81 offset1:89
	ds_read2_b32 v[10:11], v91 offset0:146 offset1:154
	ds_read2_b32 v[12:13], v91 offset0:211 offset1:219
	s_waitcnt lgkmcnt(3)
	v_bfe_u32 v2, v8, 16, 1
	v_add3_u32 v2, v8, v2, s46
	s_waitcnt lgkmcnt(2)
	v_bfe_u32 v3, v6, 16, 1
	ds_read2_b32 v[14:15], v24 offset0:20 offset1:28
	v_lshrrev_b32_e32 v2, 16, v2
	v_add3_u32 v3, v6, v3, s46
	ds_read2_b32 v[16:17], v24 offset0:85 offset1:93
	v_and_or_b32 v2, v3, s47, v2
	s_waitcnt lgkmcnt(3)
	v_bfe_u32 v3, v10, 16, 1
	v_add3_u32 v3, v10, v3, s46
	s_waitcnt lgkmcnt(2)
	v_bfe_u32 v4, v12, 16, 1
	ds_read2_b32 v[18:19], v24 offset0:150 offset1:158
	v_lshrrev_b32_e32 v3, 16, v3
	v_add3_u32 v4, v12, v4, s46
	ds_read2_b32 v[20:21], v24 offset0:215 offset1:223
	v_and_or_b32 v3, v4, s47, v3
	s_waitcnt lgkmcnt(3)
	v_bfe_u32 v4, v14, 16, 1
	v_add3_u32 v4, v14, v4, s46
	s_waitcnt lgkmcnt(2)
	v_bfe_u32 v5, v16, 16, 1
	v_lshrrev_b32_e32 v4, 16, v4
	v_add3_u32 v5, v16, v5, s46
	v_and_or_b32 v4, v5, s47, v4
	s_waitcnt lgkmcnt(1)
	v_bfe_u32 v5, v18, 16, 1
	v_add3_u32 v5, v18, v5, s46
	s_waitcnt lgkmcnt(0)
	v_bfe_u32 v6, v20, 16, 1
	v_lshrrev_b32_e32 v5, 16, v5
	v_add3_u32 v6, v20, v6, s46
	v_and_or_b32 v5, v6, s47, v5
	v_or_b32_e32 v6, s16, v93
	v_lshlrev_b32_e32 v22, 12, v6
	v_mov_b32_e32 v23, v65
	v_lshl_add_u64 v[22:23], v[0:1], 0, v[22:23]
	global_store_dwordx4 v[22:23], v[2:5], off
	v_bfe_u32 v6, v21, 16, 1
	v_add3_u32 v6, v21, v6, s46
	v_bfe_u32 v2, v9, 16, 1
	v_add3_u32 v2, v9, v2, s46
	v_bfe_u32 v3, v7, 16, 1
	v_lshrrev_b32_e32 v2, 16, v2
	v_add3_u32 v3, v7, v3, s46
	v_and_or_b32 v2, v3, s47, v2
	v_bfe_u32 v3, v11, 16, 1
	v_add3_u32 v3, v11, v3, s46
	v_bfe_u32 v4, v13, 16, 1
	v_lshrrev_b32_e32 v3, 16, v3
	v_add3_u32 v4, v13, v4, s46
	v_and_or_b32 v3, v4, s47, v3
	v_bfe_u32 v4, v15, 16, 1
	v_add3_u32 v4, v15, v4, s46
	v_bfe_u32 v5, v17, 16, 1
	v_lshrrev_b32_e32 v4, 16, v4
	v_add3_u32 v5, v17, v5, s46
	v_and_or_b32 v4, v5, s47, v4
	v_bfe_u32 v5, v19, 16, 1
	v_add3_u32 v5, v19, v5, s46
	v_lshrrev_b32_e32 v5, 16, v5
	v_and_or_b32 v5, v6, s47, v5
	v_or_b32_e32 v6, s16, v94
	v_lshlrev_b32_e32 v6, 12, v6
	v_mov_b32_e32 v7, v65
	ds_read2_b32 v[8:9], v91 offset0:32 offset1:40
	v_lshl_add_u64 v[6:7], v[0:1], 0, v[6:7]
	global_store_dwordx4 v[6:7], v[2:5], off
	ds_read2_b32 v[6:7], v91 offset0:97 offset1:105
	ds_read2_b32 v[10:11], v91 offset0:162 offset1:170
	ds_read2_b32 v[12:13], v91 offset0:227 offset1:235
	s_waitcnt lgkmcnt(3)
	v_bfe_u32 v2, v8, 16, 1
	v_add3_u32 v2, v8, v2, s46
	s_waitcnt lgkmcnt(2)
	v_bfe_u32 v3, v6, 16, 1
	ds_read2_b32 v[14:15], v24 offset0:36 offset1:44
	v_lshrrev_b32_e32 v2, 16, v2
	v_add3_u32 v3, v6, v3, s46
	ds_read2_b32 v[16:17], v24 offset0:101 offset1:109
	v_and_or_b32 v2, v3, s47, v2
	s_waitcnt lgkmcnt(3)
	v_bfe_u32 v3, v10, 16, 1
	v_add3_u32 v3, v10, v3, s46
	s_waitcnt lgkmcnt(2)
	v_bfe_u32 v4, v12, 16, 1
	ds_read2_b32 v[18:19], v24 offset0:166 offset1:174
	v_lshrrev_b32_e32 v3, 16, v3
	v_add3_u32 v4, v12, v4, s46
	ds_read2_b32 v[20:21], v24 offset0:231 offset1:239
	v_and_or_b32 v3, v4, s47, v3
	s_waitcnt lgkmcnt(3)
	v_bfe_u32 v4, v14, 16, 1
	v_add3_u32 v4, v14, v4, s46
	s_waitcnt lgkmcnt(2)
	v_bfe_u32 v5, v16, 16, 1
	v_lshrrev_b32_e32 v4, 16, v4
	v_add3_u32 v5, v16, v5, s46
	v_and_or_b32 v4, v5, s47, v4
	s_waitcnt lgkmcnt(1)
	v_bfe_u32 v5, v18, 16, 1
	v_add3_u32 v5, v18, v5, s46
	s_waitcnt lgkmcnt(0)
	v_bfe_u32 v6, v20, 16, 1
	v_lshrrev_b32_e32 v5, 16, v5
	v_add3_u32 v6, v20, v6, s46
	v_and_or_b32 v5, v6, s47, v5
	v_or_b32_e32 v6, s16, v95
	v_lshlrev_b32_e32 v22, 12, v6
	v_mov_b32_e32 v23, v65
	v_lshl_add_u64 v[22:23], v[0:1], 0, v[22:23]
	global_store_dwordx4 v[22:23], v[2:5], off
	v_bfe_u32 v6, v21, 16, 1
	v_add3_u32 v6, v21, v6, s46
	v_bfe_u32 v2, v9, 16, 1
	v_add3_u32 v2, v9, v2, s46
	v_bfe_u32 v3, v7, 16, 1
	v_lshrrev_b32_e32 v2, 16, v2
	v_add3_u32 v3, v7, v3, s46
	v_and_or_b32 v2, v3, s47, v2
	v_bfe_u32 v3, v11, 16, 1
	v_add3_u32 v3, v11, v3, s46
	v_bfe_u32 v4, v13, 16, 1
	v_lshrrev_b32_e32 v3, 16, v3
	v_add3_u32 v4, v13, v4, s46
	v_and_or_b32 v3, v4, s47, v3
	v_bfe_u32 v4, v15, 16, 1
	v_add3_u32 v4, v15, v4, s46
	v_bfe_u32 v5, v17, 16, 1
	v_lshrrev_b32_e32 v4, 16, v4
	v_add3_u32 v5, v17, v5, s46
	v_and_or_b32 v4, v5, s47, v4
	v_bfe_u32 v5, v19, 16, 1
	v_add3_u32 v5, v19, v5, s46
	v_lshrrev_b32_e32 v5, 16, v5
	v_and_or_b32 v5, v6, s47, v5
	v_or_b32_e32 v6, s16, v96
	v_lshlrev_b32_e32 v6, 12, v6
	v_mov_b32_e32 v7, v65
	ds_read2_b32 v[8:9], v91 offset0:48 offset1:56
	v_lshl_add_u64 v[6:7], v[0:1], 0, v[6:7]
	global_store_dwordx4 v[6:7], v[2:5], off
	ds_read2_b32 v[6:7], v91 offset0:113 offset1:121
	ds_read2_b32 v[10:11], v91 offset0:178 offset1:186
	ds_read2_b32 v[12:13], v91 offset0:243 offset1:251
	s_waitcnt lgkmcnt(3)
	v_bfe_u32 v2, v8, 16, 1
	v_add3_u32 v2, v8, v2, s46
	s_waitcnt lgkmcnt(2)
	v_bfe_u32 v3, v6, 16, 1
	ds_read2_b32 v[14:15], v24 offset0:52 offset1:60
	v_lshrrev_b32_e32 v2, 16, v2
	v_add3_u32 v3, v6, v3, s46
	ds_read2_b32 v[16:17], v24 offset0:117 offset1:125
	v_and_or_b32 v2, v3, s47, v2
	s_waitcnt lgkmcnt(3)
	v_bfe_u32 v3, v10, 16, 1
	v_add3_u32 v3, v10, v3, s46
	s_waitcnt lgkmcnt(2)
	v_bfe_u32 v4, v12, 16, 1
	ds_read2_b32 v[18:19], v24 offset0:182 offset1:190
	v_lshrrev_b32_e32 v3, 16, v3
	v_add3_u32 v4, v12, v4, s46
	ds_read2_b32 v[20:21], v24 offset0:247 offset1:255
	v_and_or_b32 v3, v4, s47, v3
	s_waitcnt lgkmcnt(3)
	v_bfe_u32 v4, v14, 16, 1
	v_add3_u32 v4, v14, v4, s46
	s_waitcnt lgkmcnt(2)
	v_bfe_u32 v5, v16, 16, 1
	v_lshrrev_b32_e32 v4, 16, v4
	v_add3_u32 v5, v16, v5, s46
	v_and_or_b32 v4, v5, s47, v4
	s_waitcnt lgkmcnt(1)
	v_bfe_u32 v5, v18, 16, 1
	v_add3_u32 v5, v18, v5, s46
	s_waitcnt lgkmcnt(0)
	v_bfe_u32 v6, v20, 16, 1
	v_lshrrev_b32_e32 v5, 16, v5
	v_add3_u32 v6, v20, v6, s46
	v_and_or_b32 v5, v6, s47, v5
	v_or_b32_e32 v6, s16, v97
	v_lshlrev_b32_e32 v22, 12, v6
	v_mov_b32_e32 v23, v65
	v_lshl_add_u64 v[22:23], v[0:1], 0, v[22:23]
	global_store_dwordx4 v[22:23], v[2:5], off
	v_bfe_u32 v6, v21, 16, 1
	v_add3_u32 v6, v21, v6, s46
	v_bfe_u32 v2, v9, 16, 1
	v_add3_u32 v2, v9, v2, s46
	v_bfe_u32 v3, v7, 16, 1
	v_lshrrev_b32_e32 v2, 16, v2
	v_add3_u32 v3, v7, v3, s46
	v_and_or_b32 v2, v3, s47, v2
	v_bfe_u32 v3, v11, 16, 1
	v_add3_u32 v3, v11, v3, s46
	v_bfe_u32 v4, v13, 16, 1
	v_lshrrev_b32_e32 v3, 16, v3
	v_add3_u32 v4, v13, v4, s46
	v_and_or_b32 v3, v4, s47, v3
	v_bfe_u32 v4, v15, 16, 1
	v_add3_u32 v4, v15, v4, s46
	v_bfe_u32 v5, v17, 16, 1
	v_lshrrev_b32_e32 v4, 16, v4
	v_add3_u32 v5, v17, v5, s46
	v_and_or_b32 v4, v5, s47, v4
	v_bfe_u32 v5, v19, 16, 1
	v_add3_u32 v5, v19, v5, s46
	v_lshrrev_b32_e32 v5, 16, v5
	v_and_or_b32 v5, v6, s47, v5
	v_or_b32_e32 v6, s16, v98
	v_lshlrev_b32_e32 v6, 12, v6
	v_mov_b32_e32 v7, v65
	v_lshl_add_u64 v[0:1], v[0:1], 0, v[6:7]
	global_store_dwordx4 v[0:1], v[2:5], off
	s_waitcnt lgkmcnt(0)

.LBB0_145:
	s_load_dwordx2 s[62:63], s[2:3], 0x18
	s_ashr_i32 s16, s18, 11
	s_ashr_i32 s17, s16, 31
	s_lshl_b64 s[64:65], s[16:17], 25
	v_mov_b32_e32 v59, v65
	s_waitcnt lgkmcnt(0)
	s_add_u32 s19, s62, s64
	s_addc_u32 s62, s63, s65
	s_and_b32 s8, s18, 0x7c0
	s_lshl_b32 s18, s60, 6
	s_and_b32 s61, s18, 0xfc0
	s_lshl_b32 s18, s61, 2
	s_add_u32 s18, s19, s18
	v_or_b32_e32 v73, s8, v88
	s_addc_u32 s19, s62, 0
	v_lshl_add_u64 v[56:57], s[18:19], 0, v[64:65]
	v_lshlrev_b32_e32 v58, 14, v73
	v_lshl_add_u64 v[0:1], v[56:57], 0, v[58:59]
	v_or_b32_e32 v2, 0x10000, v58
	v_mov_b32_e32 v3, v65
	v_or_b32_e32 v8, 0x20000, v58
	v_mov_b32_e32 v9, v65
	v_or_b32_e32 v10, 0x30000, v58
	v_mov_b32_e32 v11, v65
	v_or_b32_e32 v16, 0x40000, v58
	v_mov_b32_e32 v17, v65
	v_or_b32_e32 v18, 0x50000, v58
	v_mov_b32_e32 v19, v65
	v_or_b32_e32 v24, 0x60000, v58
	v_mov_b32_e32 v25, v65
	v_or_b32_e32 v26, 0x70000, v58
	v_mov_b32_e32 v27, v65
	v_or_b32_e32 v32, 0x80000, v58
	v_mov_b32_e32 v33, v65
	v_or_b32_e32 v34, 0x90000, v58
	v_mov_b32_e32 v35, v65
	v_or_b32_e32 v40, 0xa0000, v58
	v_mov_b32_e32 v41, v65
	v_or_b32_e32 v42, 0xb0000, v58
	v_mov_b32_e32 v43, v65
	v_or_b32_e32 v48, 0xc0000, v58
	v_mov_b32_e32 v49, v65
	v_or_b32_e32 v50, 0xd0000, v58
	v_mov_b32_e32 v51, v65
	v_or_b32_e32 v60, 0xe0000, v58
	v_mov_b32_e32 v61, v65
	v_or_b32_e32 v58, 0xf0000, v58
	v_lshl_add_u64 v[2:3], v[56:57], 0, v[2:3]
	v_lshl_add_u64 v[8:9], v[56:57], 0, v[8:9]
	v_lshl_add_u64 v[10:11], v[56:57], 0, v[10:11]
	v_lshl_add_u64 v[16:17], v[56:57], 0, v[16:17]
	v_lshl_add_u64 v[18:19], v[56:57], 0, v[18:19]
	v_lshl_add_u64 v[24:25], v[56:57], 0, v[24:25]
	v_lshl_add_u64 v[26:27], v[56:57], 0, v[26:27]
	v_lshl_add_u64 v[32:33], v[56:57], 0, v[32:33]
	v_lshl_add_u64 v[34:35], v[56:57], 0, v[34:35]
	v_lshl_add_u64 v[40:41], v[56:57], 0, v[40:41]
	v_lshl_add_u64 v[42:43], v[56:57], 0, v[42:43]
	v_lshl_add_u64 v[48:49], v[56:57], 0, v[48:49]
	v_lshl_add_u64 v[50:51], v[56:57], 0, v[50:51]
	v_lshl_add_u64 v[60:61], v[56:57], 0, v[60:61]
	v_lshl_add_u64 v[56:57], v[56:57], 0, v[58:59]
	global_load_dwordx4 v[4:7], v[0:1], off nt
	s_nop 0
	global_load_dwordx4 v[0:3], v[2:3], off nt
	s_nop 0
	global_load_dwordx4 v[12:15], v[8:9], off nt
	s_nop 0
	global_load_dwordx4 v[8:11], v[10:11], off nt
	s_nop 0
	global_load_dwordx4 v[20:23], v[16:17], off nt
	s_nop 0
	global_load_dwordx4 v[16:19], v[18:19], off nt
	s_nop 0
	global_load_dwordx4 v[28:31], v[24:25], off nt
	s_nop 0
	global_load_dwordx4 v[24:27], v[26:27], off nt
	s_nop 0
	global_load_dwordx4 v[36:39], v[32:33], off nt
	s_nop 0
	global_load_dwordx4 v[32:35], v[34:35], off nt
	s_nop 0
	global_load_dwordx4 v[44:47], v[40:41], off nt
	s_nop 0
	global_load_dwordx4 v[40:43], v[42:43], off nt
	s_nop 0
	global_load_dwordx4 v[52:55], v[48:49], off nt
	s_nop 0
	global_load_dwordx4 v[48:51], v[50:51], off nt
	s_nop 0
	global_load_dwordx4 v[60:63], v[60:61], off nt
	s_nop 0
	global_load_dwordx4 v[56:59], v[56:57], off nt
	s_andn2_b64 vcc, exec, s[14:15]
	s_cbranch_vccnz .LBB0_124
	s_mul_i32 s18, s16, 0x1800
	s_ashr_i32 s19, s18, 31
	s_lshl_b64 s[18:19], s[18:19], 2
	s_add_u32 s18, s6, s18
	s_addc_u32 s19, s7, s19
	v_lshlrev_b32_e32 v73, 2, v73
	global_load_dword v160, v73, s[18:19]
	global_load_dword v161, v73, s[18:19] offset:16
	global_load_dword v162, v73, s[18:19] offset:32
	global_load_dword v163, v73, s[18:19] offset:48
	global_load_dword v164, v73, s[18:19] offset:64
	global_load_dword v165, v73, s[18:19] offset:80
	global_load_dword v166, v73, s[18:19] offset:96
	global_load_dword v167, v73, s[18:19] offset:112
	global_load_dword v168, v73, s[18:19] offset:128
	global_load_dword v169, v73, s[18:19] offset:144
	global_load_dword v170, v73, s[18:19] offset:160
	global_load_dword v171, v73, s[18:19] offset:176
	global_load_dword v172, v73, s[18:19] offset:192
	global_load_dword v173, v73, s[18:19] offset:208
	global_load_dword v174, v73, s[18:19] offset:224
	global_load_dword v175, v73, s[18:19] offset:240
	s_waitcnt vmcnt(0)
	v_mov_b32_e32 v126, v160
	s_waitcnt vmcnt(0)
	v_pk_mul_f32 v[6:7], v[6:7], v[126:127] op_sel_hi:[1,0]
	v_pk_mul_f32 v[4:5], v[4:5], v[126:127] op_sel_hi:[1,0]
	v_mov_b32_e32 v126, v161
	s_waitcnt vmcnt(0)
	v_pk_mul_f32 v[2:3], v[2:3], v[126:127] op_sel_hi:[1,0]
	v_pk_mul_f32 v[0:1], v[0:1], v[126:127] op_sel_hi:[1,0]
	v_mov_b32_e32 v126, v162
	s_waitcnt vmcnt(0)
	v_pk_mul_f32 v[14:15], v[14:15], v[126:127] op_sel_hi:[1,0]
	v_pk_mul_f32 v[12:13], v[12:13], v[126:127] op_sel_hi:[1,0]
	v_mov_b32_e32 v126, v163
	s_waitcnt vmcnt(0)
	v_pk_mul_f32 v[10:11], v[10:11], v[126:127] op_sel_hi:[1,0]
	v_pk_mul_f32 v[8:9], v[8:9], v[126:127] op_sel_hi:[1,0]
	v_mov_b32_e32 v126, v164
	s_waitcnt vmcnt(0)
	v_pk_mul_f32 v[22:23], v[22:23], v[126:127] op_sel_hi:[1,0]
	v_pk_mul_f32 v[20:21], v[20:21], v[126:127] op_sel_hi:[1,0]
	v_mov_b32_e32 v126, v165
	s_waitcnt vmcnt(0)
	v_pk_mul_f32 v[18:19], v[18:19], v[126:127] op_sel_hi:[1,0]
	v_pk_mul_f32 v[16:17], v[16:17], v[126:127] op_sel_hi:[1,0]
	v_mov_b32_e32 v126, v166
	s_waitcnt vmcnt(0)
	v_pk_mul_f32 v[30:31], v[30:31], v[126:127] op_sel_hi:[1,0]
	v_pk_mul_f32 v[28:29], v[28:29], v[126:127] op_sel_hi:[1,0]
	v_mov_b32_e32 v126, v167
	s_waitcnt vmcnt(0)
	v_pk_mul_f32 v[26:27], v[26:27], v[126:127] op_sel_hi:[1,0]
	v_pk_mul_f32 v[24:25], v[24:25], v[126:127] op_sel_hi:[1,0]
	v_mov_b32_e32 v126, v168
	s_waitcnt vmcnt(0)
	v_pk_mul_f32 v[38:39], v[38:39], v[126:127] op_sel_hi:[1,0]
	v_pk_mul_f32 v[36:37], v[36:37], v[126:127] op_sel_hi:[1,0]
	v_mov_b32_e32 v126, v169
	s_waitcnt vmcnt(0)
	v_pk_mul_f32 v[34:35], v[34:35], v[126:127] op_sel_hi:[1,0]
	v_pk_mul_f32 v[32:33], v[32:33], v[126:127] op_sel_hi:[1,0]
	v_mov_b32_e32 v126, v170
	s_waitcnt vmcnt(0)
	v_pk_mul_f32 v[46:47], v[46:47], v[126:127] op_sel_hi:[1,0]
	v_pk_mul_f32 v[44:45], v[44:45], v[126:127] op_sel_hi:[1,0]
	v_mov_b32_e32 v126, v171
	s_waitcnt vmcnt(0)
	v_pk_mul_f32 v[42:43], v[42:43], v[126:127] op_sel_hi:[1,0]
	v_pk_mul_f32 v[40:41], v[40:41], v[126:127] op_sel_hi:[1,0]
	v_mov_b32_e32 v126, v172
	s_waitcnt vmcnt(0)
	v_pk_mul_f32 v[54:55], v[54:55], v[126:127] op_sel_hi:[1,0]
	v_pk_mul_f32 v[52:53], v[52:53], v[126:127] op_sel_hi:[1,0]
	v_mov_b32_e32 v126, v173
	s_waitcnt vmcnt(0)
	v_pk_mul_f32 v[50:51], v[50:51], v[126:127] op_sel_hi:[1,0]
	v_pk_mul_f32 v[48:49], v[48:49], v[126:127] op_sel_hi:[1,0]
	v_mov_b32_e32 v126, v174
	s_waitcnt vmcnt(0)
	v_pk_mul_f32 v[62:63], v[62:63], v[126:127] op_sel_hi:[1,0]
	v_pk_mul_f32 v[60:61], v[60:61], v[126:127] op_sel_hi:[1,0]
	v_mov_b32_e32 v126, v175
	s_waitcnt vmcnt(0)
	v_pk_mul_f32 v[58:59], v[58:59], v[126:127] op_sel_hi:[1,0]
	v_pk_mul_f32 v[56:57], v[56:57], v[126:127] op_sel_hi:[1,0]
	s_branch .LBB0_124

.LBB0_992:
	s_add_i32 s12, s14, 0x800
	s_cmpk_gt_i32 s14, 0x7ff
	s_mov_b64 s[10:11], -1
	s_cbranch_scc0 .LBB0_998
	s_cmpk_gt_u32 s12, 0x1fff
	s_cbranch_scc0 .LBB0_995
	s_load_dwordx2 s[16:17], s[88:89], 0x90
	s_add_i32 s10, s14, 0xe800
	s_and_b32 s11, s10, 0xffc0
	s_lshl_b32 s10, s14, 6
	s_and_b32 s10, s10, 0xfc0
	s_lshl_b32 s13, s10, 2
	s_waitcnt lgkmcnt(0)
	s_add_u32 s16, s16, s13
	v_or_b32_e32 v4, s11, v65
	s_addc_u32 s17, s17, 0
	v_lshlrev_b32_e32 v208, 2, v64
	v_lshl_add_u64 v[0:1], s[16:17], 0, v[208:209]
	v_lshlrev_b32_e32 v208, 14, v4
	v_lshl_add_u64 v[2:3], v[0:1], 0, v[208:209]
	v_or_b32_e32 v63, 4, v4
	v_or_b32_e32 v71, 8, v4
	v_or_b32_e32 v86, 12, v4
	v_or_b32_e32 v87, 16, v4
	v_or_b32_e32 v88, 20, v4
	v_or_b32_e32 v89, 24, v4
	v_or_b32_e32 v90, 28, v4
	v_or_b32_e32 v91, 32, v4
	v_or_b32_e32 v92, 36, v4
	v_or_b32_e32 v93, 40, v4
	v_or_b32_e32 v94, 44, v4
	v_or_b32_e32 v95, 48, v4
	v_or_b32_e32 v96, 52, v4
	v_or_b32_e32 v97, 56, v4
	v_or_b32_e32 v98, 60, v4
	v_lshlrev_b32_e32 v4, 2, v4
	global_load_dwordx4 v[6:9], v[2:3], off nt
	global_load_dword v62, v4, s[4:5]
	v_lshlrev_b32_e32 v208, 14, v63
	v_lshl_add_u64 v[2:3], v[0:1], 0, v[208:209]
	global_load_dwordx4 v[10:13], v[2:3], off nt
	v_lshlrev_b32_e32 v208, 14, v71
	v_lshl_add_u64 v[2:3], v[0:1], 0, v[208:209]
	global_load_dwordx4 v[14:17], v[2:3], off nt
	v_lshlrev_b32_e32 v208, 14, v86
	v_lshl_add_u64 v[2:3], v[0:1], 0, v[208:209]
	global_load_dwordx4 v[18:21], v[2:3], off nt
	v_lshlrev_b32_e32 v208, 14, v87
	v_lshl_add_u64 v[2:3], v[0:1], 0, v[208:209]
	global_load_dwordx4 v[22:25], v[2:3], off nt
	v_lshlrev_b32_e32 v208, 14, v88
	v_lshl_add_u64 v[2:3], v[0:1], 0, v[208:209]
	global_load_dwordx4 v[26:29], v[2:3], off nt
	v_lshlrev_b32_e32 v208, 14, v89
	v_lshl_add_u64 v[2:3], v[0:1], 0, v[208:209]
	global_load_dwordx4 v[30:33], v[2:3], off nt
	v_lshlrev_b32_e32 v208, 14, v90
	v_lshl_add_u64 v[2:3], v[0:1], 0, v[208:209]
	global_load_dwordx4 v[34:37], v[2:3], off nt
	v_lshlrev_b32_e32 v208, 14, v91
	v_lshl_add_u64 v[2:3], v[0:1], 0, v[208:209]
	global_load_dwordx4 v[38:41], v[2:3], off nt
	v_lshlrev_b32_e32 v208, 14, v92
	v_lshl_add_u64 v[2:3], v[0:1], 0, v[208:209]
	global_load_dwordx4 v[42:45], v[2:3], off nt
	v_lshlrev_b32_e32 v208, 14, v93
	v_lshl_add_u64 v[2:3], v[0:1], 0, v[208:209]
	global_load_dwordx4 v[46:49], v[2:3], off nt
	v_lshlrev_b32_e32 v208, 14, v94
	v_lshl_add_u64 v[2:3], v[0:1], 0, v[208:209]
	global_load_dwordx4 v[50:53], v[2:3], off nt
	v_lshlrev_b32_e32 v208, 14, v95
	v_lshl_add_u64 v[2:3], v[0:1], 0, v[208:209]
	global_load_dwordx4 v[54:57], v[2:3], off nt
	v_lshlrev_b32_e32 v208, 14, v96
	v_lshl_add_u64 v[2:3], v[0:1], 0, v[208:209]
	global_load_dwordx4 v[58:61], v[2:3], off nt
	v_lshlrev_b32_e32 v208, 14, v97
	v_lshl_add_u64 v[2:3], v[0:1], 0, v[208:209]
	global_load_dwordx4 v[82:85], v[2:3], off nt
	v_lshlrev_b32_e32 v208, 14, v98
	v_lshl_add_u64 v[0:1], v[0:1], 0, v[208:209]
	global_load_dwordx4 v[0:3], v[0:1], off nt
	s_lshl_b32 s28, s11, 1
	v_lshlrev_b32_e32 v176, 2, v63
	global_load_dword v160, v176, s[4:5]
	v_lshlrev_b32_e32 v176, 2, v71
	global_load_dword v161, v176, s[4:5]
	v_lshlrev_b32_e32 v176, 2, v86
	global_load_dword v162, v176, s[4:5]
	v_lshlrev_b32_e32 v176, 2, v87
	global_load_dword v163, v176, s[4:5]
	v_lshlrev_b32_e32 v176, 2, v88
	global_load_dword v164, v176, s[4:5]
	v_lshlrev_b32_e32 v176, 2, v89
	global_load_dword v165, v176, s[4:5]
	v_lshlrev_b32_e32 v176, 2, v90
	global_load_dword v166, v176, s[4:5]
	v_lshlrev_b32_e32 v176, 2, v91
	global_load_dword v167, v176, s[4:5]
	v_lshlrev_b32_e32 v176, 2, v92
	global_load_dword v168, v176, s[4:5]
	v_lshlrev_b32_e32 v176, 2, v93
	global_load_dword v169, v176, s[4:5]
	v_lshlrev_b32_e32 v176, 2, v94
	global_load_dword v170, v176, s[4:5]
	v_lshlrev_b32_e32 v176, 2, v95
	global_load_dword v171, v176, s[4:5]
	v_lshlrev_b32_e32 v176, 2, v96
	global_load_dword v172, v176, s[4:5]
	v_lshlrev_b32_e32 v176, 2, v97
	global_load_dword v173, v176, s[4:5]
	v_lshlrev_b32_e32 v176, 2, v98
	global_load_dword v174, v176, s[4:5]
	s_waitcnt vmcnt(0)
	v_pk_mul_f32 v[4:5], v[8:9], v[62:63] op_sel_hi:[1,0]
	v_lshlrev_b32_e32 v8, 2, v63
	v_pk_mul_f32 v[6:7], v[6:7], v[62:63] op_sel_hi:[1,0]
	v_mov_b32_e32 v62, v160
	s_waitcnt vmcnt(0)
	v_pk_mul_f32 v[8:9], v[12:13], v[62:63] op_sel_hi:[1,0]
	v_lshlrev_b32_e32 v12, 2, v71
	v_pk_mul_f32 v[10:11], v[10:11], v[62:63] op_sel_hi:[1,0]
	v_mov_b32_e32 v62, v161
	v_lshlrev_b32_e32 v71, 2, v98
	s_waitcnt vmcnt(0)
	v_pk_mul_f32 v[12:13], v[16:17], v[62:63] op_sel_hi:[1,0]
	v_lshlrev_b32_e32 v16, 2, v86
	v_pk_mul_f32 v[14:15], v[14:15], v[62:63] op_sel_hi:[1,0]
	v_mov_b32_e32 v62, v162
	s_waitcnt vmcnt(0)
	v_pk_mul_f32 v[16:17], v[20:21], v[62:63] op_sel_hi:[1,0]
	v_lshlrev_b32_e32 v20, 2, v87
	v_pk_mul_f32 v[18:19], v[18:19], v[62:63] op_sel_hi:[1,0]
	v_mov_b32_e32 v62, v163
	s_waitcnt vmcnt(0)
	v_pk_mul_f32 v[20:21], v[24:25], v[62:63] op_sel_hi:[1,0]
	v_lshlrev_b32_e32 v24, 2, v88
	v_pk_mul_f32 v[22:23], v[22:23], v[62:63] op_sel_hi:[1,0]
	v_mov_b32_e32 v62, v164
	s_waitcnt vmcnt(0)
	v_pk_mul_f32 v[24:25], v[28:29], v[62:63] op_sel_hi:[1,0]
	v_lshlrev_b32_e32 v28, 2, v89
	v_pk_mul_f32 v[26:27], v[26:27], v[62:63] op_sel_hi:[1,0]
	v_mov_b32_e32 v62, v165
	s_waitcnt vmcnt(0)
	v_pk_mul_f32 v[28:29], v[32:33], v[62:63] op_sel_hi:[1,0]
	v_lshlrev_b32_e32 v32, 2, v90
	v_pk_mul_f32 v[30:31], v[30:31], v[62:63] op_sel_hi:[1,0]
	v_mov_b32_e32 v62, v166
	s_waitcnt vmcnt(0)
	v_pk_mul_f32 v[32:33], v[36:37], v[62:63] op_sel_hi:[1,0]
	v_lshlrev_b32_e32 v36, 2, v91
	v_pk_mul_f32 v[34:35], v[34:35], v[62:63] op_sel_hi:[1,0]
	v_mov_b32_e32 v62, v167
	s_waitcnt vmcnt(0)
	v_pk_mul_f32 v[36:37], v[40:41], v[62:63] op_sel_hi:[1,0]
	v_lshlrev_b32_e32 v40, 2, v92
	v_mov_b32_e32 v40, v168
	v_pk_mul_f32 v[38:39], v[38:39], v[62:63] op_sel_hi:[1,0]
	s_waitcnt vmcnt(0)
	v_pk_mul_f32 v[44:45], v[44:45], v[40:41] op_sel_hi:[1,0]
	v_pk_mul_f32 v[40:41], v[42:43], v[40:41] op_sel_hi:[1,0]
	v_lshlrev_b32_e32 v42, 2, v93
	v_mov_b32_e32 v42, v169
	s_waitcnt vmcnt(0)
	v_pk_mul_f32 v[48:49], v[48:49], v[42:43] op_sel_hi:[1,0]
	v_pk_mul_f32 v[42:43], v[46:47], v[42:43] op_sel_hi:[1,0]
	v_lshlrev_b32_e32 v46, 2, v94
	v_mov_b32_e32 v46, v170
	s_waitcnt vmcnt(0)
	v_pk_mul_f32 v[52:53], v[52:53], v[46:47] op_sel_hi:[1,0]
	v_pk_mul_f32 v[46:47], v[50:51], v[46:47] op_sel_hi:[1,0]
	v_lshlrev_b32_e32 v50, 2, v95
	v_mov_b32_e32 v50, v171
	s_waitcnt vmcnt(0)
	v_pk_mul_f32 v[56:57], v[56:57], v[50:51] op_sel_hi:[1,0]
	v_pk_mul_f32 v[50:51], v[54:55], v[50:51] op_sel_hi:[1,0]
	v_lshlrev_b32_e32 v54, 2, v96
	v_mov_b32_e32 v54, v172
	s_waitcnt vmcnt(0)
	v_pk_mul_f32 v[60:61], v[60:61], v[54:55] op_sel_hi:[1,0]
	v_pk_mul_f32 v[54:55], v[58:59], v[54:55] op_sel_hi:[1,0]
	v_lshlrev_b32_e32 v58, 2, v97
	v_mov_b32_e32 v58, v173
	s_waitcnt vmcnt(0)
	v_pk_mul_f32 v[62:63], v[84:85], v[58:59] op_sel_hi:[1,0]
	v_pk_mul_f32 v[58:59], v[82:83], v[58:59] op_sel_hi:[1,0]
	v_mov_b32_e32 v82, v174
	ds_write2_b32 v72, v6, v7 offset1:1
	ds_write2_b32 v72, v4, v5 offset0:2 offset1:3
	v_add_u32_e32 v4, 0x410, v72
	ds_write2_b32 v4, v10, v11 offset1:1
	v_add_u32_e32 v4, 0x418, v72
	ds_write2_b32 v4, v8, v9 offset1:1
	v_add_u32_e32 v4, 0x820, v72
	ds_write2_b32 v4, v14, v15 offset1:1
	v_add_u32_e32 v4, 0x828, v72
	ds_write2_b32 v4, v12, v13 offset1:1
	v_add_u32_e32 v4, 0xc30, v72
	ds_write2_b32 v4, v18, v19 offset1:1
	v_add_u32_e32 v4, 0xc38, v72
	ds_write2_b32 v4, v16, v17 offset1:1
	v_add_u32_e32 v4, 0x1040, v72
	ds_write2_b32 v4, v22, v23 offset1:1
	v_add_u32_e32 v4, 0x1048, v72
	ds_write2_b32 v4, v20, v21 offset1:1
	v_add_u32_e32 v4, 0x1450, v72
	ds_write2_b32 v4, v26, v27 offset1:1
	v_add_u32_e32 v4, 0x1458, v72
	ds_write2_b32 v4, v24, v25 offset1:1
	v_add_u32_e32 v4, 0x1860, v72
	ds_write2_b32 v4, v30, v31 offset1:1
	v_add_u32_e32 v4, 0x1868, v72
	ds_write2_b32 v4, v28, v29 offset1:1
	v_add_u32_e32 v4, 0x1c70, v72
	ds_write2_b32 v4, v34, v35 offset1:1
	v_add_u32_e32 v4, 0x1c78, v72
	ds_write2_b32 v4, v32, v33 offset1:1
	v_add_u32_e32 v4, 0x2080, v72
	ds_write2_b32 v4, v38, v39 offset1:1
	v_add_u32_e32 v4, 0x2088, v72
	ds_write2_b32 v4, v36, v37 offset1:1
	v_add_u32_e32 v4, 0x2490, v72
	ds_write2_b32 v4, v40, v41 offset1:1
	v_add_u32_e32 v4, 0x2498, v72
	ds_write2_b32 v4, v44, v45 offset1:1
	v_add_u32_e32 v4, 0x28a0, v72
	ds_write2_b32 v4, v42, v43 offset1:1
	v_add_u32_e32 v4, 0x28a8, v72
	ds_write2_b32 v4, v48, v49 offset1:1
	v_add_u32_e32 v4, 0x2cb0, v72
	ds_write2_b32 v4, v46, v47 offset1:1
	v_add_u32_e32 v4, 0x2cb8, v72
	ds_write2_b32 v4, v52, v53 offset1:1
	v_add_u32_e32 v4, 0x30c0, v72
	ds_write2_b32 v4, v50, v51 offset1:1
	v_add_u32_e32 v4, 0x30c8, v72
	ds_write2_b32 v4, v56, v57 offset1:1
	v_add_u32_e32 v4, 0x34d0, v72
	ds_write2_b32 v4, v54, v55 offset1:1
	v_add_u32_e32 v4, 0x34d8, v72
	ds_write2_b32 v4, v60, v61 offset1:1
	v_add_u32_e32 v4, 0x38e0, v72
	ds_write2_b32 v4, v58, v59 offset1:1
	v_add_u32_e32 v4, 0x38e8, v72
	ds_write2_b32 v4, v62, v63 offset1:1
	v_add_u32_e32 v4, 0x3cf0, v72
	s_waitcnt vmcnt(0)
	v_pk_mul_f32 v[0:1], v[0:1], v[82:83] op_sel_hi:[1,0]
	v_pk_mul_f32 v[2:3], v[2:3], v[82:83] op_sel_hi:[1,0]
	ds_write2_b32 v4, v0, v1 offset1:1
	v_add_u32_e32 v0, 0x3cf8, v72
	ds_write2_b32 v0, v2, v3 offset1:1
	s_waitcnt lgkmcnt(0)
	ds_read2_b32 v[2:3], v74 offset0:65 offset1:73
	ds_read2_b32 v[8:9], v74 offset1:8
	ds_read2_b32 v[10:11], v74 offset0:130 offset1:138
	ds_read2_b32 v[12:13], v74 offset0:195 offset1:203
	v_lshl_add_u64 v[0:1], v[66:67], 0, s[28:29]
	s_waitcnt lgkmcnt(3)
	v_bfe_u32 v5, v2, 16, 1
	s_waitcnt lgkmcnt(2)
	v_bfe_u32 v4, v8, 16, 1
	v_add3_u32 v4, v8, v4, s85
	v_lshrrev_b32_e32 v4, 16, v4
	v_add3_u32 v2, v2, v5, s85
	v_and_or_b32 v4, v2, s1, v4
	s_waitcnt lgkmcnt(1)
	v_bfe_u32 v2, v10, 16, 1
	v_add3_u32 v2, v10, v2, s85
	s_waitcnt lgkmcnt(0)
	v_bfe_u32 v5, v12, 16, 1
	v_lshrrev_b32_e32 v2, 16, v2
	v_add3_u32 v5, v12, v5, s85
	v_and_or_b32 v5, v5, s1, v2
	v_add_u32_e32 v2, 0x400, v74
	ds_read2_b32 v[14:15], v2 offset0:4 offset1:12
	ds_read2_b32 v[16:17], v2 offset0:69 offset1:77
	ds_read2_b32 v[18:19], v2 offset0:134 offset1:142
	ds_read2_b32 v[20:21], v2 offset0:199 offset1:207
	s_waitcnt lgkmcnt(3)
	v_bfe_u32 v6, v14, 16, 1
	v_add3_u32 v6, v14, v6, s85
	s_waitcnt lgkmcnt(2)
	v_bfe_u32 v7, v16, 16, 1
	v_lshrrev_b32_e32 v6, 16, v6
	v_add3_u32 v7, v16, v7, s85
	v_and_or_b32 v6, v7, s1, v6
	s_waitcnt lgkmcnt(1)
	v_bfe_u32 v7, v18, 16, 1
	v_add3_u32 v7, v18, v7, s85
	s_waitcnt lgkmcnt(0)
	v_bfe_u32 v8, v20, 16, 1
	v_lshrrev_b32_e32 v7, 16, v7
	v_add3_u32 v8, v20, v8, s85
	v_and_or_b32 v7, v8, s1, v7
	v_or_b32_e32 v8, s10, v73
	v_lshlrev_b32_e32 v208, 12, v8
	v_lshl_add_u64 v[22:23], v[0:1], 0, v[208:209]
	global_store_dwordx4 v[22:23], v[4:7], off
	s_nop 1
	v_bfe_u32 v4, v9, 16, 1
	v_add3_u32 v4, v9, v4, s85
	v_bfe_u32 v5, v3, 16, 1
	v_lshrrev_b32_e32 v4, 16, v4
	v_add3_u32 v3, v3, v5, s85
	v_and_or_b32 v4, v3, s1, v4
	v_bfe_u32 v3, v11, 16, 1
	v_add3_u32 v3, v11, v3, s85
	v_bfe_u32 v5, v13, 16, 1
	v_lshrrev_b32_e32 v3, 16, v3
	v_add3_u32 v5, v13, v5, s85
	v_and_or_b32 v5, v5, s1, v3
	v_bfe_u32 v3, v15, 16, 1
	v_add3_u32 v3, v15, v3, s85
	v_bfe_u32 v6, v17, 16, 1
	v_lshrrev_b32_e32 v3, 16, v3
	v_add3_u32 v6, v17, v6, s85
	v_and_or_b32 v6, v6, s1, v3
	v_bfe_u32 v3, v19, 16, 1
	v_add3_u32 v3, v19, v3, s85
	v_bfe_u32 v7, v21, 16, 1
	v_lshrrev_b32_e32 v3, 16, v3
	v_add3_u32 v7, v21, v7, s85
	v_and_or_b32 v7, v7, s1, v3
	v_or_b32_e32 v3, s10, v75
	v_lshlrev_b32_e32 v208, 12, v3
	v_lshl_add_u64 v[8:9], v[0:1], 0, v[208:209]
	global_store_dwordx4 v[8:9], v[4:7], off
	ds_read2_b32 v[8:9], v74 offset0:81 offset1:89
	ds_read2_b32 v[10:11], v74 offset0:16 offset1:24
	ds_read2_b32 v[12:13], v74 offset0:146 offset1:154
	ds_read2_b32 v[14:15], v74 offset0:211 offset1:219
	ds_read2_b32 v[16:17], v2 offset0:20 offset1:28
	ds_read2_b32 v[18:19], v2 offset0:85 offset1:93
	ds_read2_b32 v[20:21], v2 offset0:150 offset1:158
	ds_read2_b32 v[22:23], v2 offset0:215 offset1:223
	s_waitcnt lgkmcnt(7)
	v_bfe_u32 v4, v8, 16, 1
	s_waitcnt lgkmcnt(6)
	v_bfe_u32 v3, v10, 16, 1
	v_add3_u32 v3, v10, v3, s85
	v_lshrrev_b32_e32 v3, 16, v3
	v_add3_u32 v4, v8, v4, s85
	v_and_or_b32 v4, v4, s1, v3
	s_waitcnt lgkmcnt(5)
	v_bfe_u32 v3, v12, 16, 1
	v_add3_u32 v3, v12, v3, s85
	s_waitcnt lgkmcnt(4)
	v_bfe_u32 v5, v14, 16, 1
	v_lshrrev_b32_e32 v3, 16, v3
	v_add3_u32 v5, v14, v5, s85
	v_and_or_b32 v5, v5, s1, v3
	s_waitcnt lgkmcnt(3)
	v_bfe_u32 v3, v16, 16, 1
	v_add3_u32 v3, v16, v3, s85
	s_waitcnt lgkmcnt(2)
	v_bfe_u32 v6, v18, 16, 1
	v_lshrrev_b32_e32 v3, 16, v3
	v_add3_u32 v6, v18, v6, s85
	v_and_or_b32 v6, v6, s1, v3
	s_waitcnt lgkmcnt(1)
	v_bfe_u32 v3, v20, 16, 1
	v_add3_u32 v3, v20, v3, s85
	s_waitcnt lgkmcnt(0)
	v_bfe_u32 v7, v22, 16, 1
	v_lshrrev_b32_e32 v3, 16, v3
	v_add3_u32 v7, v22, v7, s85
	v_and_or_b32 v7, v7, s1, v3
	v_or_b32_e32 v3, s10, v76
	v_lshlrev_b32_e32 v208, 12, v3
	v_lshl_add_u64 v[24:25], v[0:1], 0, v[208:209]
	v_bfe_u32 v3, v11, 16, 1
	global_store_dwordx4 v[24:25], v[4:7], off
	v_add3_u32 v3, v11, v3, s85
	v_lshrrev_b32_e32 v3, 16, v3
	v_bfe_u32 v4, v9, 16, 1
	v_add3_u32 v4, v9, v4, s85
	v_and_or_b32 v4, v4, s1, v3
	v_bfe_u32 v3, v13, 16, 1
	v_add3_u32 v3, v13, v3, s85
	v_bfe_u32 v5, v15, 16, 1
	v_lshrrev_b32_e32 v3, 16, v3
	v_add3_u32 v5, v15, v5, s85
	v_and_or_b32 v5, v5, s1, v3
	v_bfe_u32 v3, v17, 16, 1
	v_add3_u32 v3, v17, v3, s85
	v_bfe_u32 v6, v19, 16, 1
	v_lshrrev_b32_e32 v3, 16, v3
	v_add3_u32 v6, v19, v6, s85
	v_and_or_b32 v6, v6, s1, v3
	v_bfe_u32 v3, v21, 16, 1
	v_add3_u32 v3, v21, v3, s85
	v_bfe_u32 v7, v23, 16, 1
	v_lshrrev_b32_e32 v3, 16, v3
	v_add3_u32 v7, v23, v7, s85
	v_and_or_b32 v7, v7, s1, v3
	v_or_b32_e32 v3, s10, v77
	v_lshlrev_b32_e32 v208, 12, v3
	v_lshl_add_u64 v[8:9], v[0:1], 0, v[208:209]
	global_store_dwordx4 v[8:9], v[4:7], off
	ds_read2_b32 v[8:9], v74 offset0:97 offset1:105
	ds_read2_b32 v[10:11], v74 offset0:32 offset1:40
	ds_read2_b32 v[12:13], v74 offset0:162 offset1:170
	ds_read2_b32 v[14:15], v74 offset0:227 offset1:235
	ds_read2_b32 v[16:17], v2 offset0:36 offset1:44
	ds_read2_b32 v[18:19], v2 offset0:101 offset1:109
	ds_read2_b32 v[20:21], v2 offset0:166 offset1:174
	ds_read2_b32 v[22:23], v2 offset0:231 offset1:239
	s_waitcnt lgkmcnt(7)
	v_bfe_u32 v4, v8, 16, 1
	s_waitcnt lgkmcnt(6)
	v_bfe_u32 v3, v10, 16, 1
	v_add3_u32 v3, v10, v3, s85
	v_lshrrev_b32_e32 v3, 16, v3
	v_add3_u32 v4, v8, v4, s85
	v_and_or_b32 v4, v4, s1, v3
	s_waitcnt lgkmcnt(5)
	v_bfe_u32 v3, v12, 16, 1
	v_add3_u32 v3, v12, v3, s85
	s_waitcnt lgkmcnt(4)
	v_bfe_u32 v5, v14, 16, 1
	v_lshrrev_b32_e32 v3, 16, v3
	v_add3_u32 v5, v14, v5, s85
	v_and_or_b32 v5, v5, s1, v3
	s_waitcnt lgkmcnt(3)
	v_bfe_u32 v3, v16, 16, 1
	v_add3_u32 v3, v16, v3, s85
	s_waitcnt lgkmcnt(2)
	v_bfe_u32 v6, v18, 16, 1
	v_lshrrev_b32_e32 v3, 16, v3
	v_add3_u32 v6, v18, v6, s85
	v_and_or_b32 v6, v6, s1, v3
	s_waitcnt lgkmcnt(1)
	v_bfe_u32 v3, v20, 16, 1
	v_add3_u32 v3, v20, v3, s85
	s_waitcnt lgkmcnt(0)
	v_bfe_u32 v7, v22, 16, 1
	v_lshrrev_b32_e32 v3, 16, v3
	v_add3_u32 v7, v22, v7, s85
	v_and_or_b32 v7, v7, s1, v3
	v_or_b32_e32 v3, s10, v78
	v_lshlrev_b32_e32 v208, 12, v3
	v_lshl_add_u64 v[24:25], v[0:1], 0, v[208:209]
	v_bfe_u32 v3, v11, 16, 1
	global_store_dwordx4 v[24:25], v[4:7], off
	v_add3_u32 v3, v11, v3, s85
	v_lshrrev_b32_e32 v3, 16, v3
	v_bfe_u32 v4, v9, 16, 1
	v_add3_u32 v4, v9, v4, s85
	v_and_or_b32 v4, v4, s1, v3
	v_bfe_u32 v3, v13, 16, 1
	v_add3_u32 v3, v13, v3, s85
	v_bfe_u32 v5, v15, 16, 1
	v_lshrrev_b32_e32 v3, 16, v3
	v_add3_u32 v5, v15, v5, s85
	v_and_or_b32 v5, v5, s1, v3
	v_bfe_u32 v3, v17, 16, 1
	v_add3_u32 v3, v17, v3, s85
	v_bfe_u32 v6, v19, 16, 1
	v_lshrrev_b32_e32 v3, 16, v3
	v_add3_u32 v6, v19, v6, s85
	v_and_or_b32 v6, v6, s1, v3
	v_bfe_u32 v3, v21, 16, 1
	v_add3_u32 v3, v21, v3, s85
	v_bfe_u32 v7, v23, 16, 1
	v_lshrrev_b32_e32 v3, 16, v3
	v_add3_u32 v7, v23, v7, s85
	v_and_or_b32 v7, v7, s1, v3
	v_or_b32_e32 v3, s10, v79
	v_lshlrev_b32_e32 v208, 12, v3
	v_lshl_add_u64 v[8:9], v[0:1], 0, v[208:209]
	global_store_dwordx4 v[8:9], v[4:7], off
	ds_read2_b32 v[8:9], v74 offset0:48 offset1:56
	ds_read2_b32 v[10:11], v74 offset0:113 offset1:121
	ds_read2_b32 v[12:13], v74 offset0:178 offset1:186
	ds_read2_b32 v[14:15], v74 offset0:243 offset1:251
	ds_read2_b32 v[16:17], v2 offset0:52 offset1:60
	ds_read2_b32 v[18:19], v2 offset0:117 offset1:125
	ds_read2_b32 v[20:21], v2 offset0:182 offset1:190
	ds_read2_b32 v[22:23], v2 offset0:247 offset1:255
	s_waitcnt lgkmcnt(7)
	v_bfe_u32 v3, v8, 16, 1
	v_add3_u32 v3, v8, v3, s85
	s_waitcnt lgkmcnt(6)
	v_bfe_u32 v4, v10, 16, 1
	v_lshrrev_b32_e32 v3, 16, v3
	v_add3_u32 v4, v10, v4, s85
	v_and_or_b32 v4, v4, s1, v3
	s_waitcnt lgkmcnt(5)
	v_bfe_u32 v3, v12, 16, 1
	v_add3_u32 v3, v12, v3, s85
	s_waitcnt lgkmcnt(4)
	v_bfe_u32 v5, v14, 16, 1
	v_lshrrev_b32_e32 v3, 16, v3
	v_add3_u32 v5, v14, v5, s85
	v_and_or_b32 v5, v5, s1, v3
	s_waitcnt lgkmcnt(3)
	v_bfe_u32 v3, v16, 16, 1
	v_add3_u32 v3, v16, v3, s85
	s_waitcnt lgkmcnt(2)
	v_bfe_u32 v6, v18, 16, 1
	v_lshrrev_b32_e32 v3, 16, v3
	v_add3_u32 v6, v18, v6, s85
	s_waitcnt lgkmcnt(1)
	v_bfe_u32 v2, v20, 16, 1
	v_and_or_b32 v6, v6, s1, v3
	v_add3_u32 v2, v20, v2, s85
	s_waitcnt lgkmcnt(0)
	v_bfe_u32 v3, v22, 16, 1
	v_lshrrev_b32_e32 v2, 16, v2
	v_add3_u32 v3, v22, v3, s85
	v_and_or_b32 v7, v3, s1, v2
	v_or_b32_e32 v2, s10, v80
	v_lshlrev_b32_e32 v208, 12, v2
	v_lshl_add_u64 v[2:3], v[0:1], 0, v[208:209]
	global_store_dwordx4 v[2:3], v[4:7], off
	v_bfe_u32 v2, v9, 16, 1
	v_add3_u32 v2, v9, v2, s85
	v_bfe_u32 v3, v11, 16, 1
	v_lshrrev_b32_e32 v2, 16, v2
	v_add3_u32 v3, v11, v3, s85
	v_and_or_b32 v2, v3, s1, v2
	v_bfe_u32 v3, v13, 16, 1
	v_add3_u32 v3, v13, v3, s85
	v_bfe_u32 v4, v15, 16, 1
	v_lshrrev_b32_e32 v3, 16, v3
	v_add3_u32 v4, v15, v4, s85
	v_and_or_b32 v3, v4, s1, v3
	v_bfe_u32 v4, v17, 16, 1
	v_add3_u32 v4, v17, v4, s85
	v_bfe_u32 v5, v19, 16, 1
	v_lshrrev_b32_e32 v4, 16, v4
	v_add3_u32 v5, v19, v5, s85
	v_and_or_b32 v4, v5, s1, v4
	v_bfe_u32 v5, v21, 16, 1
	v_add3_u32 v5, v21, v5, s85
	v_bfe_u32 v6, v23, 16, 1
	v_lshrrev_b32_e32 v5, 16, v5
	v_add3_u32 v6, v23, v6, s85
	v_and_or_b32 v5, v6, s1, v5
	v_or_b32_e32 v6, s10, v81
	v_lshlrev_b32_e32 v208, 12, v6
	v_lshl_add_u64 v[0:1], v[0:1], 0, v[208:209]
	global_store_dwordx4 v[0:1], v[2:5], off
	s_waitcnt lgkmcnt(0)
	s_mov_b64 s[10:11], 0
.LBB0_995:
	s_andn2_b64 vcc, exec, s[10:11]
	s_cbranch_vccnz .LBB0_997
	s_load_dwordx2 s[16:17], s[88:89], 0x70
	s_add_i32 s10, s14, 0xf800
	s_lshr_b32 s10, s10, 1
	s_and_b32 s11, s10, 0x7fc0
	s_lshl_b32 s10, s14, 6
	s_and_b32 s10, s10, 0x1fc0
	s_lshl_b32 s13, s10, 2
	v_or_b32_e32 v62, s11, v65
	s_waitcnt lgkmcnt(0)
	s_add_u32 s16, s16, s13
	s_addc_u32 s17, s17, 0
	v_lshlrev_b32_e32 v208, 2, v64
	v_mul_u32_u24_e32 v2, 0x2010, v62
	v_lshl_add_u64 v[0:1], s[16:17], 0, v[208:209]
	v_lshlrev_b32_e32 v208, 2, v2
	v_lshl_add_u64 v[2:3], v[0:1], 0, v[208:209]
	v_add_co_u32_e32 v4, vcc, s19, v2
	s_mov_b32 s13, 0x40000
	s_nop 0
	v_addc_co_u32_e32 v5, vcc, 0, v3, vcc
	global_load_dwordx4 v[6:9], v[2:3], off nt
	global_load_dwordx4 v[10:13], v[4:5], off offset:256
	v_add_co_u32_e32 v2, vcc, s13, v2
	v_lshlrev_b32_e32 v71, 2, v62
	s_nop 0
	v_addc_co_u32_e32 v3, vcc, 0, v3, vcc
	global_load_dwordx4 v[14:17], v[2:3], off offset:512
	v_add_u32_e32 v2, 0x60300, v208
	v_mov_b32_e32 v3, v209
	v_lshl_add_u64 v[2:3], v[0:1], 0, v[2:3]
	global_load_dwordx4 v[18:21], v[2:3], off nt
	v_add_u32_e32 v2, 0x80400, v208
	v_mov_b32_e32 v3, v209
	v_lshl_add_u64 v[2:3], v[0:1], 0, v[2:3]
	global_load_dwordx4 v[22:25], v[2:3], off nt
	v_add_u32_e32 v2, 0xa0500, v208
	v_mov_b32_e32 v3, v209
	v_lshl_add_u64 v[2:3], v[0:1], 0, v[2:3]
	global_load_dwordx4 v[26:29], v[2:3], off nt
	v_add_u32_e32 v2, 0xc0600, v208
	v_mov_b32_e32 v3, v209
	v_lshl_add_u64 v[2:3], v[0:1], 0, v[2:3]
	global_load_dwordx4 v[30:33], v[2:3], off nt
	v_add_u32_e32 v2, 0xe0700, v208
	v_mov_b32_e32 v3, v209
	v_lshl_add_u64 v[2:3], v[0:1], 0, v[2:3]
	global_load_dwordx4 v[34:37], v[2:3], off nt
	v_add_u32_e32 v2, 0x100800, v208
	v_mov_b32_e32 v3, v209
	v_lshl_add_u64 v[2:3], v[0:1], 0, v[2:3]
	global_load_dwordx4 v[38:41], v[2:3], off nt
	v_add_u32_e32 v2, 0x120900, v208
	v_mov_b32_e32 v3, v209
	v_lshl_add_u64 v[2:3], v[0:1], 0, v[2:3]
	global_load_dwordx4 v[42:45], v[2:3], off nt
	v_add_u32_e32 v2, 0x140a00, v208
	v_mov_b32_e32 v3, v209
	v_lshl_add_u64 v[2:3], v[0:1], 0, v[2:3]
	global_load_dwordx4 v[46:49], v[2:3], off nt
	v_add_u32_e32 v2, 0x160b00, v208
	v_mov_b32_e32 v3, v209
	v_lshl_add_u64 v[2:3], v[0:1], 0, v[2:3]
	global_load_dwordx4 v[50:53], v[2:3], off nt
	v_add_u32_e32 v2, 0x180c00, v208
	v_mov_b32_e32 v3, v209
	v_lshl_add_u64 v[2:3], v[0:1], 0, v[2:3]
	global_load_dwordx4 v[54:57], v[2:3], off nt
	v_add_u32_e32 v2, 0x1a0d00, v208
	v_mov_b32_e32 v3, v209
	v_lshl_add_u64 v[2:3], v[0:1], 0, v[2:3]
	global_load_dwordx4 v[58:61], v[2:3], off nt
	v_add_u32_e32 v2, 0x1c0e00, v208
	v_mov_b32_e32 v3, v209
	v_add_u32_e32 v208, 0x1e0f00, v208
	v_lshl_add_u64 v[2:3], v[0:1], 0, v[2:3]
	v_lshl_add_u64 v[0:1], v[0:1], 0, v[208:209]
	global_load_dwordx4 v[82:85], v[2:3], off nt
	s_nop 0
	global_load_dwordx4 v[0:3], v[0:1], off nt
	s_nop 0
	global_load_dword v62, v71, s[6:7]
	s_lshl_b32 s28, s11, 1
	global_load_dword v160, v71, s[6:7] offset:16
	global_load_dword v161, v71, s[6:7] offset:32
	global_load_dword v162, v71, s[6:7] offset:48
	global_load_dword v163, v71, s[6:7] offset:64
	global_load_dword v164, v71, s[6:7] offset:80
	global_load_dword v165, v71, s[6:7] offset:96
	global_load_dword v166, v71, s[6:7] offset:112
	global_load_dword v167, v71, s[6:7] offset:128
	global_load_dword v168, v71, s[6:7] offset:144
	global_load_dword v169, v71, s[6:7] offset:160
	global_load_dword v170, v71, s[6:7] offset:176
	global_load_dword v171, v71, s[6:7] offset:192
	global_load_dword v172, v71, s[6:7] offset:208
	global_load_dword v173, v71, s[6:7] offset:224
	global_load_dword v174, v71, s[6:7] offset:240
	s_waitcnt vmcnt(0)
	v_pk_mul_f32 v[4:5], v[8:9], v[62:63] op_sel_hi:[1,0]
	v_or_b32_e32 v8, 16, v71
	v_pk_mul_f32 v[6:7], v[6:7], v[62:63] op_sel_hi:[1,0]
	v_mov_b32_e32 v62, v160
	s_waitcnt vmcnt(0)
	v_pk_mul_f32 v[8:9], v[12:13], v[62:63] op_sel_hi:[1,0]
	v_or_b32_e32 v12, 32, v71
	v_pk_mul_f32 v[10:11], v[10:11], v[62:63] op_sel_hi:[1,0]
	v_mov_b32_e32 v62, v161
	s_waitcnt vmcnt(0)
	v_pk_mul_f32 v[12:13], v[16:17], v[62:63] op_sel_hi:[1,0]
	v_or_b32_e32 v16, 48, v71
	v_pk_mul_f32 v[14:15], v[14:15], v[62:63] op_sel_hi:[1,0]
	v_mov_b32_e32 v62, v162
	s_waitcnt vmcnt(0)
	v_pk_mul_f32 v[16:17], v[20:21], v[62:63] op_sel_hi:[1,0]
	v_or_b32_e32 v20, 64, v71
	v_pk_mul_f32 v[18:19], v[18:19], v[62:63] op_sel_hi:[1,0]
	v_mov_b32_e32 v62, v163
	s_waitcnt vmcnt(0)
	v_pk_mul_f32 v[20:21], v[24:25], v[62:63] op_sel_hi:[1,0]
	v_or_b32_e32 v24, 0x50, v71
	v_pk_mul_f32 v[22:23], v[22:23], v[62:63] op_sel_hi:[1,0]
	v_mov_b32_e32 v62, v164
	s_waitcnt vmcnt(0)
	v_pk_mul_f32 v[24:25], v[28:29], v[62:63] op_sel_hi:[1,0]
	v_or_b32_e32 v28, 0x60, v71
	v_pk_mul_f32 v[26:27], v[26:27], v[62:63] op_sel_hi:[1,0]
	v_mov_b32_e32 v62, v165
	s_waitcnt vmcnt(0)
	v_pk_mul_f32 v[28:29], v[32:33], v[62:63] op_sel_hi:[1,0]
	v_or_b32_e32 v32, 0x70, v71
	v_pk_mul_f32 v[30:31], v[30:31], v[62:63] op_sel_hi:[1,0]
	v_mov_b32_e32 v62, v166
	s_waitcnt vmcnt(0)
	v_pk_mul_f32 v[32:33], v[36:37], v[62:63] op_sel_hi:[1,0]
	v_or_b32_e32 v36, 0x80, v71
	v_pk_mul_f32 v[34:35], v[34:35], v[62:63] op_sel_hi:[1,0]
	v_mov_b32_e32 v62, v167
	s_waitcnt vmcnt(0)
	v_pk_mul_f32 v[36:37], v[40:41], v[62:63] op_sel_hi:[1,0]
	v_or_b32_e32 v40, 0x90, v71
	v_mov_b32_e32 v40, v168
	v_pk_mul_f32 v[38:39], v[38:39], v[62:63] op_sel_hi:[1,0]
	s_waitcnt vmcnt(0)
	v_pk_mul_f32 v[44:45], v[44:45], v[40:41] op_sel_hi:[1,0]
	v_pk_mul_f32 v[40:41], v[42:43], v[40:41] op_sel_hi:[1,0]
	v_or_b32_e32 v42, 0xa0, v71
	v_mov_b32_e32 v42, v169
	s_waitcnt vmcnt(0)
	v_pk_mul_f32 v[48:49], v[48:49], v[42:43] op_sel_hi:[1,0]
	v_pk_mul_f32 v[42:43], v[46:47], v[42:43] op_sel_hi:[1,0]
	v_or_b32_e32 v46, 0xb0, v71
	v_mov_b32_e32 v46, v170
	s_waitcnt vmcnt(0)
	v_pk_mul_f32 v[52:53], v[52:53], v[46:47] op_sel_hi:[1,0]
	v_pk_mul_f32 v[46:47], v[50:51], v[46:47] op_sel_hi:[1,0]
	v_or_b32_e32 v50, 0xc0, v71
	v_mov_b32_e32 v50, v171
	s_waitcnt vmcnt(0)
	v_pk_mul_f32 v[56:57], v[56:57], v[50:51] op_sel_hi:[1,0]
	v_pk_mul_f32 v[50:51], v[54:55], v[50:51] op_sel_hi:[1,0]
	v_or_b32_e32 v54, 0xd0, v71
	v_mov_b32_e32 v54, v172
	s_waitcnt vmcnt(0)
	v_pk_mul_f32 v[60:61], v[60:61], v[54:55] op_sel_hi:[1,0]
	v_pk_mul_f32 v[54:55], v[58:59], v[54:55] op_sel_hi:[1,0]
	v_or_b32_e32 v58, 0xe0, v71
	v_mov_b32_e32 v58, v173
	v_or_b32_e32 v71, 0xf0, v71
	s_waitcnt vmcnt(0)
	v_pk_mul_f32 v[62:63], v[84:85], v[58:59] op_sel_hi:[1,0]
	v_pk_mul_f32 v[58:59], v[82:83], v[58:59] op_sel_hi:[1,0]
	v_mov_b32_e32 v82, v174
	ds_write2_b32 v72, v6, v7 offset1:1
	ds_write2_b32 v72, v4, v5 offset0:2 offset1:3
	v_add_u32_e32 v4, 0x410, v72
	ds_write2_b32 v4, v10, v11 offset1:1
	v_add_u32_e32 v4, 0x418, v72
	ds_write2_b32 v4, v8, v9 offset1:1
	v_add_u32_e32 v4, 0x820, v72
	ds_write2_b32 v4, v14, v15 offset1:1
	v_add_u32_e32 v4, 0x828, v72
	ds_write2_b32 v4, v12, v13 offset1:1
	v_add_u32_e32 v4, 0xc30, v72
	ds_write2_b32 v4, v18, v19 offset1:1
	v_add_u32_e32 v4, 0xc38, v72
	ds_write2_b32 v4, v16, v17 offset1:1
	v_add_u32_e32 v4, 0x1040, v72
	ds_write2_b32 v4, v22, v23 offset1:1
	v_add_u32_e32 v4, 0x1048, v72
	ds_write2_b32 v4, v20, v21 offset1:1
	v_add_u32_e32 v4, 0x1450, v72
	ds_write2_b32 v4, v26, v27 offset1:1
	v_add_u32_e32 v4, 0x1458, v72
	ds_write2_b32 v4, v24, v25 offset1:1
	v_add_u32_e32 v4, 0x1860, v72
	ds_write2_b32 v4, v30, v31 offset1:1
	v_add_u32_e32 v4, 0x1868, v72
	ds_write2_b32 v4, v28, v29 offset1:1
	v_add_u32_e32 v4, 0x1c70, v72
	ds_write2_b32 v4, v34, v35 offset1:1
	v_add_u32_e32 v4, 0x1c78, v72
	ds_write2_b32 v4, v32, v33 offset1:1
	v_add_u32_e32 v4, 0x2080, v72
	ds_write2_b32 v4, v38, v39 offset1:1
	v_add_u32_e32 v4, 0x2088, v72
	ds_write2_b32 v4, v36, v37 offset1:1
	v_add_u32_e32 v4, 0x2490, v72
	ds_write2_b32 v4, v40, v41 offset1:1
	v_add_u32_e32 v4, 0x2498, v72
	ds_write2_b32 v4, v44, v45 offset1:1
	v_add_u32_e32 v4, 0x28a0, v72
	ds_write2_b32 v4, v42, v43 offset1:1
	v_add_u32_e32 v4, 0x28a8, v72
	ds_write2_b32 v4, v48, v49 offset1:1
	v_add_u32_e32 v4, 0x2cb0, v72
	ds_write2_b32 v4, v46, v47 offset1:1
	v_add_u32_e32 v4, 0x2cb8, v72
	ds_write2_b32 v4, v52, v53 offset1:1
	v_add_u32_e32 v4, 0x30c0, v72
	ds_write2_b32 v4, v50, v51 offset1:1
	v_add_u32_e32 v4, 0x30c8, v72
	ds_write2_b32 v4, v56, v57 offset1:1
	v_add_u32_e32 v4, 0x34d0, v72
	ds_write2_b32 v4, v54, v55 offset1:1
	v_add_u32_e32 v4, 0x34d8, v72
	ds_write2_b32 v4, v60, v61 offset1:1
	v_add_u32_e32 v4, 0x38e0, v72
	ds_write2_b32 v4, v58, v59 offset1:1
	v_add_u32_e32 v4, 0x38e8, v72
	ds_write2_b32 v4, v62, v63 offset1:1
	v_add_u32_e32 v4, 0x3cf0, v72
	s_waitcnt vmcnt(0)
	v_pk_mul_f32 v[0:1], v[0:1], v[82:83] op_sel_hi:[1,0]
	v_pk_mul_f32 v[2:3], v[2:3], v[82:83] op_sel_hi:[1,0]
	ds_write2_b32 v4, v0, v1 offset1:1
	v_add_u32_e32 v0, 0x3cf8, v72
	ds_write2_b32 v0, v2, v3 offset1:1
	s_waitcnt lgkmcnt(0)
	ds_read2_b32 v[2:3], v74 offset0:65 offset1:73
	ds_read2_b32 v[8:9], v74 offset1:8
	ds_read2_b32 v[10:11], v74 offset0:130 offset1:138
	ds_read2_b32 v[12:13], v74 offset0:195 offset1:203
	v_lshl_add_u64 v[0:1], v[68:69], 0, s[28:29]
	s_waitcnt lgkmcnt(3)
	v_bfe_u32 v5, v2, 16, 1
	s_waitcnt lgkmcnt(2)
	v_bfe_u32 v4, v8, 16, 1
	v_add3_u32 v4, v8, v4, s85
	v_lshrrev_b32_e32 v4, 16, v4
	v_add3_u32 v2, v2, v5, s85
	v_and_or_b32 v4, v2, s1, v4
	s_waitcnt lgkmcnt(1)
	v_bfe_u32 v2, v10, 16, 1
	v_add3_u32 v2, v10, v2, s85
	s_waitcnt lgkmcnt(0)
	v_bfe_u32 v5, v12, 16, 1
	v_lshrrev_b32_e32 v2, 16, v2
	v_add3_u32 v5, v12, v5, s85
	v_and_or_b32 v5, v5, s1, v2
	v_add_u32_e32 v2, 0x400, v74
	ds_read2_b32 v[14:15], v2 offset0:4 offset1:12
	ds_read2_b32 v[16:17], v2 offset0:69 offset1:77
	ds_read2_b32 v[18:19], v2 offset0:134 offset1:142
	ds_read2_b32 v[20:21], v2 offset0:199 offset1:207
	s_waitcnt lgkmcnt(3)
	v_bfe_u32 v6, v14, 16, 1
	v_add3_u32 v6, v14, v6, s85
	s_waitcnt lgkmcnt(2)
	v_bfe_u32 v7, v16, 16, 1
	v_lshrrev_b32_e32 v6, 16, v6
	v_add3_u32 v7, v16, v7, s85
	v_and_or_b32 v6, v7, s1, v6
	s_waitcnt lgkmcnt(1)
	v_bfe_u32 v7, v18, 16, 1
	v_add3_u32 v7, v18, v7, s85
	s_waitcnt lgkmcnt(0)
	v_bfe_u32 v8, v20, 16, 1
	v_lshrrev_b32_e32 v7, 16, v7
	v_add3_u32 v8, v20, v8, s85
	v_and_or_b32 v7, v8, s1, v7
	v_or_b32_e32 v8, s10, v73
	v_lshlrev_b32_e32 v208, 12, v8
	v_lshl_add_u64 v[22:23], v[0:1], 0, v[208:209]
	global_store_dwordx4 v[22:23], v[4:7], off
	s_nop 1
	v_bfe_u32 v4, v9, 16, 1
	v_add3_u32 v4, v9, v4, s85
	v_bfe_u32 v5, v3, 16, 1
	v_lshrrev_b32_e32 v4, 16, v4
	v_add3_u32 v3, v3, v5, s85
	v_and_or_b32 v4, v3, s1, v4
	v_bfe_u32 v3, v11, 16, 1
	v_add3_u32 v3, v11, v3, s85
	v_bfe_u32 v5, v13, 16, 1
	v_lshrrev_b32_e32 v3, 16, v3
	v_add3_u32 v5, v13, v5, s85
	v_and_or_b32 v5, v5, s1, v3
	v_bfe_u32 v3, v15, 16, 1
	v_add3_u32 v3, v15, v3, s85
	v_bfe_u32 v6, v17, 16, 1
	v_lshrrev_b32_e32 v3, 16, v3
	v_add3_u32 v6, v17, v6, s85
	v_and_or_b32 v6, v6, s1, v3
	v_bfe_u32 v3, v19, 16, 1
	v_add3_u32 v3, v19, v3, s85
	v_bfe_u32 v7, v21, 16, 1
	v_lshrrev_b32_e32 v3, 16, v3
	v_add3_u32 v7, v21, v7, s85
	v_and_or_b32 v7, v7, s1, v3
	v_or_b32_e32 v3, s10, v75
	v_lshlrev_b32_e32 v208, 12, v3
	v_lshl_add_u64 v[8:9], v[0:1], 0, v[208:209]
	global_store_dwordx4 v[8:9], v[4:7], off
	ds_read2_b32 v[8:9], v74 offset0:81 offset1:89
	ds_read2_b32 v[10:11], v74 offset0:16 offset1:24
	ds_read2_b32 v[12:13], v74 offset0:146 offset1:154
	ds_read2_b32 v[14:15], v74 offset0:211 offset1:219
	ds_read2_b32 v[16:17], v2 offset0:20 offset1:28
	ds_read2_b32 v[18:19], v2 offset0:85 offset1:93
	ds_read2_b32 v[20:21], v2 offset0:150 offset1:158
	ds_read2_b32 v[22:23], v2 offset0:215 offset1:223
	s_waitcnt lgkmcnt(7)
	v_bfe_u32 v4, v8, 16, 1
	s_waitcnt lgkmcnt(6)
	v_bfe_u32 v3, v10, 16, 1
	v_add3_u32 v3, v10, v3, s85
	v_lshrrev_b32_e32 v3, 16, v3
	v_add3_u32 v4, v8, v4, s85
	v_and_or_b32 v4, v4, s1, v3
	s_waitcnt lgkmcnt(5)
	v_bfe_u32 v3, v12, 16, 1
	v_add3_u32 v3, v12, v3, s85
	s_waitcnt lgkmcnt(4)
	v_bfe_u32 v5, v14, 16, 1
	v_lshrrev_b32_e32 v3, 16, v3
	v_add3_u32 v5, v14, v5, s85
	v_and_or_b32 v5, v5, s1, v3
	s_waitcnt lgkmcnt(3)
	v_bfe_u32 v3, v16, 16, 1
	v_add3_u32 v3, v16, v3, s85
	s_waitcnt lgkmcnt(2)
	v_bfe_u32 v6, v18, 16, 1
	v_lshrrev_b32_e32 v3, 16, v3
	v_add3_u32 v6, v18, v6, s85
	v_and_or_b32 v6, v6, s1, v3
	s_waitcnt lgkmcnt(1)
	v_bfe_u32 v3, v20, 16, 1
	v_add3_u32 v3, v20, v3, s85
	s_waitcnt lgkmcnt(0)
	v_bfe_u32 v7, v22, 16, 1
	v_lshrrev_b32_e32 v3, 16, v3
	v_add3_u32 v7, v22, v7, s85
	v_and_or_b32 v7, v7, s1, v3
	v_or_b32_e32 v3, s10, v76
	v_lshlrev_b32_e32 v208, 12, v3
	v_lshl_add_u64 v[24:25], v[0:1], 0, v[208:209]
	v_bfe_u32 v3, v11, 16, 1
	global_store_dwordx4 v[24:25], v[4:7], off
	v_add3_u32 v3, v11, v3, s85
	v_lshrrev_b32_e32 v3, 16, v3
	v_bfe_u32 v4, v9, 16, 1
	v_add3_u32 v4, v9, v4, s85
	v_and_or_b32 v4, v4, s1, v3
	v_bfe_u32 v3, v13, 16, 1
	v_add3_u32 v3, v13, v3, s85
	v_bfe_u32 v5, v15, 16, 1
	v_lshrrev_b32_e32 v3, 16, v3
	v_add3_u32 v5, v15, v5, s85
	v_and_or_b32 v5, v5, s1, v3
	v_bfe_u32 v3, v17, 16, 1
	v_add3_u32 v3, v17, v3, s85
	v_bfe_u32 v6, v19, 16, 1
	v_lshrrev_b32_e32 v3, 16, v3
	v_add3_u32 v6, v19, v6, s85
	v_and_or_b32 v6, v6, s1, v3
	v_bfe_u32 v3, v21, 16, 1
	v_add3_u32 v3, v21, v3, s85
	v_bfe_u32 v7, v23, 16, 1
	v_lshrrev_b32_e32 v3, 16, v3
	v_add3_u32 v7, v23, v7, s85
	v_and_or_b32 v7, v7, s1, v3
	v_or_b32_e32 v3, s10, v77
	v_lshlrev_b32_e32 v208, 12, v3
	v_lshl_add_u64 v[8:9], v[0:1], 0, v[208:209]
	global_store_dwordx4 v[8:9], v[4:7], off
	ds_read2_b32 v[8:9], v74 offset0:97 offset1:105
	ds_read2_b32 v[10:11], v74 offset0:32 offset1:40
	ds_read2_b32 v[12:13], v74 offset0:162 offset1:170
	ds_read2_b32 v[14:15], v74 offset0:227 offset1:235
	ds_read2_b32 v[16:17], v2 offset0:36 offset1:44
	ds_read2_b32 v[18:19], v2 offset0:101 offset1:109
	ds_read2_b32 v[20:21], v2 offset0:166 offset1:174
	ds_read2_b32 v[22:23], v2 offset0:231 offset1:239
	s_waitcnt lgkmcnt(7)
	v_bfe_u32 v4, v8, 16, 1
	s_waitcnt lgkmcnt(6)
	v_bfe_u32 v3, v10, 16, 1
	v_add3_u32 v3, v10, v3, s85
	v_lshrrev_b32_e32 v3, 16, v3
	v_add3_u32 v4, v8, v4, s85
	v_and_or_b32 v4, v4, s1, v3
	s_waitcnt lgkmcnt(5)
	v_bfe_u32 v3, v12, 16, 1
	v_add3_u32 v3, v12, v3, s85
	s_waitcnt lgkmcnt(4)
	v_bfe_u32 v5, v14, 16, 1
	v_lshrrev_b32_e32 v3, 16, v3
	v_add3_u32 v5, v14, v5, s85
	v_and_or_b32 v5, v5, s1, v3
	s_waitcnt lgkmcnt(3)
	v_bfe_u32 v3, v16, 16, 1
	v_add3_u32 v3, v16, v3, s85
	s_waitcnt lgkmcnt(2)
	v_bfe_u32 v6, v18, 16, 1
	v_lshrrev_b32_e32 v3, 16, v3
	v_add3_u32 v6, v18, v6, s85
	v_and_or_b32 v6, v6, s1, v3
	s_waitcnt lgkmcnt(1)
	v_bfe_u32 v3, v20, 16, 1
	v_add3_u32 v3, v20, v3, s85
	s_waitcnt lgkmcnt(0)
	v_bfe_u32 v7, v22, 16, 1
	v_lshrrev_b32_e32 v3, 16, v3
	v_add3_u32 v7, v22, v7, s85
	v_and_or_b32 v7, v7, s1, v3
	v_or_b32_e32 v3, s10, v78
	v_lshlrev_b32_e32 v208, 12, v3
	v_lshl_add_u64 v[24:25], v[0:1], 0, v[208:209]
	v_bfe_u32 v3, v11, 16, 1
	global_store_dwordx4 v[24:25], v[4:7], off
	v_add3_u32 v3, v11, v3, s85
	v_lshrrev_b32_e32 v3, 16, v3
	v_bfe_u32 v4, v9, 16, 1
	v_add3_u32 v4, v9, v4, s85
	v_and_or_b32 v4, v4, s1, v3
	v_bfe_u32 v3, v13, 16, 1
	v_add3_u32 v3, v13, v3, s85
	v_bfe_u32 v5, v15, 16, 1
	v_lshrrev_b32_e32 v3, 16, v3
	v_add3_u32 v5, v15, v5, s85
	v_and_or_b32 v5, v5, s1, v3
	v_bfe_u32 v3, v17, 16, 1
	v_add3_u32 v3, v17, v3, s85
	v_bfe_u32 v6, v19, 16, 1
	v_lshrrev_b32_e32 v3, 16, v3
	v_add3_u32 v6, v19, v6, s85
	v_and_or_b32 v6, v6, s1, v3
	v_bfe_u32 v3, v21, 16, 1
	v_add3_u32 v3, v21, v3, s85
	v_bfe_u32 v7, v23, 16, 1
	v_lshrrev_b32_e32 v3, 16, v3
	v_add3_u32 v7, v23, v7, s85
	v_and_or_b32 v7, v7, s1, v3
	v_or_b32_e32 v3, s10, v79
	v_lshlrev_b32_e32 v208, 12, v3
	v_lshl_add_u64 v[8:9], v[0:1], 0, v[208:209]
	global_store_dwordx4 v[8:9], v[4:7], off
	ds_read2_b32 v[8:9], v74 offset0:48 offset1:56
	ds_read2_b32 v[10:11], v74 offset0:113 offset1:121
	ds_read2_b32 v[12:13], v74 offset0:178 offset1:186
	ds_read2_b32 v[14:15], v74 offset0:243 offset1:251
	ds_read2_b32 v[16:17], v2 offset0:52 offset1:60
	ds_read2_b32 v[18:19], v2 offset0:117 offset1:125
	ds_read2_b32 v[20:21], v2 offset0:182 offset1:190
	ds_read2_b32 v[22:23], v2 offset0:247 offset1:255
	s_waitcnt lgkmcnt(7)
	v_bfe_u32 v3, v8, 16, 1
	v_add3_u32 v3, v8, v3, s85
	s_waitcnt lgkmcnt(6)
	v_bfe_u32 v4, v10, 16, 1
	v_lshrrev_b32_e32 v3, 16, v3
	v_add3_u32 v4, v10, v4, s85
	v_and_or_b32 v4, v4, s1, v3
	s_waitcnt lgkmcnt(5)
	v_bfe_u32 v3, v12, 16, 1
	v_add3_u32 v3, v12, v3, s85
	s_waitcnt lgkmcnt(4)
	v_bfe_u32 v5, v14, 16, 1
	v_lshrrev_b32_e32 v3, 16, v3
	v_add3_u32 v5, v14, v5, s85
	v_and_or_b32 v5, v5, s1, v3
	s_waitcnt lgkmcnt(3)
	v_bfe_u32 v3, v16, 16, 1
	v_add3_u32 v3, v16, v3, s85
	s_waitcnt lgkmcnt(2)
	v_bfe_u32 v6, v18, 16, 1
	v_lshrrev_b32_e32 v3, 16, v3
	v_add3_u32 v6, v18, v6, s85
	s_waitcnt lgkmcnt(1)
	v_bfe_u32 v2, v20, 16, 1
	v_and_or_b32 v6, v6, s1, v3
	v_add3_u32 v2, v20, v2, s85
	s_waitcnt lgkmcnt(0)
	v_bfe_u32 v3, v22, 16, 1
	v_lshrrev_b32_e32 v2, 16, v2
	v_add3_u32 v3, v22, v3, s85
	v_and_or_b32 v7, v3, s1, v2
	v_or_b32_e32 v2, s10, v80
	v_lshlrev_b32_e32 v208, 12, v2
	v_lshl_add_u64 v[2:3], v[0:1], 0, v[208:209]
	global_store_dwordx4 v[2:3], v[4:7], off
	v_bfe_u32 v2, v9, 16, 1
	v_add3_u32 v2, v9, v2, s85
	v_bfe_u32 v3, v11, 16, 1
	v_lshrrev_b32_e32 v2, 16, v2
	v_add3_u32 v3, v11, v3, s85
	v_and_or_b32 v2, v3, s1, v2
	v_bfe_u32 v3, v13, 16, 1
	v_add3_u32 v3, v13, v3, s85
	v_bfe_u32 v4, v15, 16, 1
	v_lshrrev_b32_e32 v3, 16, v3
	v_add3_u32 v4, v15, v4, s85
	v_and_or_b32 v3, v4, s1, v3
	v_bfe_u32 v4, v17, 16, 1
	v_add3_u32 v4, v17, v4, s85
	v_bfe_u32 v5, v19, 16, 1
	v_lshrrev_b32_e32 v4, 16, v4
	v_add3_u32 v5, v19, v5, s85
	v_and_or_b32 v4, v5, s1, v4
	v_bfe_u32 v5, v21, 16, 1
	v_add3_u32 v5, v21, v5, s85
	v_bfe_u32 v6, v23, 16, 1
	v_lshrrev_b32_e32 v5, 16, v5
	v_add3_u32 v6, v23, v6, s85
	v_and_or_b32 v5, v6, s1, v5
	v_or_b32_e32 v6, s10, v81
	v_lshlrev_b32_e32 v208, 12, v6
	v_lshl_add_u64 v[0:1], v[0:1], 0, v[208:209]
	global_store_dwordx4 v[0:1], v[2:5], off
	s_waitcnt lgkmcnt(0)

.LBB0_999:
	s_load_dwordx2 s[16:17], s[88:89], 0x18
	s_ashr_i32 s10, s12, 11
	s_ashr_i32 s11, s10, 31
	s_lshl_b64 s[12:13], s[10:11], 25
	v_lshlrev_b32_e32 v208, 2, v64
	s_waitcnt lgkmcnt(0)
	s_add_u32 s12, s16, s12
	s_addc_u32 s13, s17, s13
	s_lshl_b32 s16, s14, 6
	s_and_b32 s16, s16, 0xfc0
	s_and_b32 s15, s14, 0x7c0
	s_lshl_b32 s17, s16, 2
	s_add_u32 s12, s12, s17
	v_or_b32_e32 v71, s15, v65
	s_addc_u32 s13, s13, 0
	v_lshl_add_u64 v[52:53], s[12:13], 0, v[208:209]
	v_lshlrev_b32_e32 v208, 14, v71
	v_lshl_add_u64 v[0:1], v[52:53], 0, v[208:209]
	v_or_b32_e32 v2, 0x10000, v208
	v_mov_b32_e32 v3, v209
	v_or_b32_e32 v4, 0x20000, v208
	v_mov_b32_e32 v5, v209
	v_or_b32_e32 v6, 0x30000, v208
	v_mov_b32_e32 v7, v209
	v_or_b32_e32 v12, 0x40000, v208
	v_mov_b32_e32 v13, v209
	v_or_b32_e32 v14, 0x50000, v208
	v_mov_b32_e32 v15, v209
	v_or_b32_e32 v20, 0x60000, v208
	v_mov_b32_e32 v21, v209
	v_or_b32_e32 v22, 0x70000, v208
	v_mov_b32_e32 v23, v209
	v_or_b32_e32 v28, 0x80000, v208
	v_mov_b32_e32 v29, v209
	v_or_b32_e32 v30, 0x90000, v208
	v_mov_b32_e32 v31, v209
	v_or_b32_e32 v36, 0xa0000, v208
	v_mov_b32_e32 v37, v209
	v_or_b32_e32 v38, 0xb0000, v208
	v_mov_b32_e32 v39, v209
	v_or_b32_e32 v44, 0xc0000, v208
	v_mov_b32_e32 v45, v209
	v_or_b32_e32 v46, 0xd0000, v208
	v_mov_b32_e32 v47, v209
	v_or_b32_e32 v54, 0xe0000, v208
	v_mov_b32_e32 v55, v209
	v_or_b32_e32 v208, 0xf0000, v208
	v_lshl_add_u64 v[2:3], v[52:53], 0, v[2:3]
	v_lshl_add_u64 v[4:5], v[52:53], 0, v[4:5]
	v_lshl_add_u64 v[6:7], v[52:53], 0, v[6:7]
	v_lshl_add_u64 v[12:13], v[52:53], 0, v[12:13]
	v_lshl_add_u64 v[14:15], v[52:53], 0, v[14:15]
	v_lshl_add_u64 v[20:21], v[52:53], 0, v[20:21]
	v_lshl_add_u64 v[22:23], v[52:53], 0, v[22:23]
	v_lshl_add_u64 v[28:29], v[52:53], 0, v[28:29]
	v_lshl_add_u64 v[30:31], v[52:53], 0, v[30:31]
	v_lshl_add_u64 v[36:37], v[52:53], 0, v[36:37]
	v_lshl_add_u64 v[38:39], v[52:53], 0, v[38:39]
	v_lshl_add_u64 v[44:45], v[52:53], 0, v[44:45]
	v_lshl_add_u64 v[46:47], v[52:53], 0, v[46:47]
	v_lshl_add_u64 v[54:55], v[52:53], 0, v[54:55]
	v_lshl_add_u64 v[52:53], v[52:53], 0, v[208:209]
	global_load_dwordx4 v[8:11], v[0:1], off nt
	s_nop 0
	global_load_dwordx4 v[0:3], v[2:3], off nt
	s_nop 0
	global_load_dwordx4 v[16:19], v[4:5], off nt
	s_nop 0
	global_load_dwordx4 v[4:7], v[6:7], off nt
	s_nop 0
	global_load_dwordx4 v[24:27], v[12:13], off nt
	s_nop 0
	global_load_dwordx4 v[12:15], v[14:15], off nt
	s_nop 0
	global_load_dwordx4 v[32:35], v[20:21], off nt
	s_nop 0
	global_load_dwordx4 v[20:23], v[22:23], off nt
	s_nop 0
	global_load_dwordx4 v[40:43], v[28:29], off nt
	s_nop 0
	global_load_dwordx4 v[28:31], v[30:31], off nt
	s_nop 0
	global_load_dwordx4 v[48:51], v[36:37], off nt
	s_nop 0
	global_load_dwordx4 v[36:39], v[38:39], off nt
	s_nop 0
	global_load_dwordx4 v[56:59], v[44:45], off nt
	s_nop 0
	global_load_dwordx4 v[44:47], v[46:47], off nt
	s_nop 0
	global_load_dwordx4 v[60:63], v[54:55], off nt
	s_nop 0
	global_load_dwordx4 v[52:55], v[52:53], off nt
	s_andn2_b64 vcc, exec, s[8:9]
	s_cbranch_vccnz .LBB0_990
	s_mul_i32 s12, s10, 0x1800
	s_ashr_i32 s13, s12, 31
	s_lshl_b64 s[12:13], s[12:13], 2
	s_add_u32 s12, s2, s12
	s_addc_u32 s13, s3, s13
	v_lshlrev_b32_e32 v71, 2, v71
	global_load_dword v160, v71, s[12:13]
	global_load_dword v161, v71, s[12:13] offset:16
	global_load_dword v162, v71, s[12:13] offset:32
	global_load_dword v163, v71, s[12:13] offset:48
	global_load_dword v164, v71, s[12:13] offset:64
	global_load_dword v165, v71, s[12:13] offset:80
	global_load_dword v166, v71, s[12:13] offset:96
	global_load_dword v167, v71, s[12:13] offset:112
	global_load_dword v168, v71, s[12:13] offset:128
	global_load_dword v169, v71, s[12:13] offset:144
	global_load_dword v170, v71, s[12:13] offset:160
	global_load_dword v171, v71, s[12:13] offset:176
	global_load_dword v172, v71, s[12:13] offset:192
	global_load_dword v173, v71, s[12:13] offset:208
	global_load_dword v174, v71, s[12:13] offset:224
	global_load_dword v175, v71, s[12:13] offset:240
	s_waitcnt vmcnt(0)
	v_mov_b32_e32 v82, v160
	s_waitcnt vmcnt(0)
	v_pk_mul_f32 v[10:11], v[10:11], v[82:83] op_sel_hi:[1,0]
	v_pk_mul_f32 v[8:9], v[8:9], v[82:83] op_sel_hi:[1,0]
	v_mov_b32_e32 v82, v161
	s_waitcnt vmcnt(0)
	v_pk_mul_f32 v[2:3], v[2:3], v[82:83] op_sel_hi:[1,0]
	v_pk_mul_f32 v[0:1], v[0:1], v[82:83] op_sel_hi:[1,0]
	v_mov_b32_e32 v82, v162
	s_waitcnt vmcnt(0)
	v_pk_mul_f32 v[18:19], v[18:19], v[82:83] op_sel_hi:[1,0]
	v_pk_mul_f32 v[16:17], v[16:17], v[82:83] op_sel_hi:[1,0]
	v_mov_b32_e32 v82, v163
	s_waitcnt vmcnt(0)
	v_pk_mul_f32 v[6:7], v[6:7], v[82:83] op_sel_hi:[1,0]
	v_pk_mul_f32 v[4:5], v[4:5], v[82:83] op_sel_hi:[1,0]
	v_mov_b32_e32 v82, v164
	s_waitcnt vmcnt(0)
	v_pk_mul_f32 v[26:27], v[26:27], v[82:83] op_sel_hi:[1,0]
	v_pk_mul_f32 v[24:25], v[24:25], v[82:83] op_sel_hi:[1,0]
	v_mov_b32_e32 v82, v165
	s_waitcnt vmcnt(0)
	v_pk_mul_f32 v[14:15], v[14:15], v[82:83] op_sel_hi:[1,0]
	v_pk_mul_f32 v[12:13], v[12:13], v[82:83] op_sel_hi:[1,0]
	v_mov_b32_e32 v82, v166
	s_waitcnt vmcnt(0)
	v_pk_mul_f32 v[34:35], v[34:35], v[82:83] op_sel_hi:[1,0]
	v_pk_mul_f32 v[32:33], v[32:33], v[82:83] op_sel_hi:[1,0]
	v_mov_b32_e32 v82, v167
	s_waitcnt vmcnt(0)
	v_pk_mul_f32 v[22:23], v[22:23], v[82:83] op_sel_hi:[1,0]
	v_pk_mul_f32 v[20:21], v[20:21], v[82:83] op_sel_hi:[1,0]
	v_mov_b32_e32 v82, v168
	s_waitcnt vmcnt(0)
	v_pk_mul_f32 v[42:43], v[42:43], v[82:83] op_sel_hi:[1,0]
	v_pk_mul_f32 v[40:41], v[40:41], v[82:83] op_sel_hi:[1,0]
	v_mov_b32_e32 v82, v169
	s_waitcnt vmcnt(0)
	v_pk_mul_f32 v[30:31], v[30:31], v[82:83] op_sel_hi:[1,0]
	v_pk_mul_f32 v[28:29], v[28:29], v[82:83] op_sel_hi:[1,0]
	v_mov_b32_e32 v82, v170
	s_waitcnt vmcnt(0)
	v_pk_mul_f32 v[50:51], v[50:51], v[82:83] op_sel_hi:[1,0]
	v_pk_mul_f32 v[48:49], v[48:49], v[82:83] op_sel_hi:[1,0]
	v_mov_b32_e32 v82, v171
	s_waitcnt vmcnt(0)
	v_pk_mul_f32 v[38:39], v[38:39], v[82:83] op_sel_hi:[1,0]
	v_pk_mul_f32 v[36:37], v[36:37], v[82:83] op_sel_hi:[1,0]
	v_mov_b32_e32 v82, v172
	s_waitcnt vmcnt(0)
	v_pk_mul_f32 v[58:59], v[58:59], v[82:83] op_sel_hi:[1,0]
	v_pk_mul_f32 v[56:57], v[56:57], v[82:83] op_sel_hi:[1,0]
	v_mov_b32_e32 v82, v173
	s_waitcnt vmcnt(0)
	v_pk_mul_f32 v[46:47], v[46:47], v[82:83] op_sel_hi:[1,0]
	v_pk_mul_f32 v[44:45], v[44:45], v[82:83] op_sel_hi:[1,0]
	v_mov_b32_e32 v82, v174
	s_waitcnt vmcnt(0)
	v_pk_mul_f32 v[62:63], v[62:63], v[82:83] op_sel_hi:[1,0]
	v_pk_mul_f32 v[60:61], v[60:61], v[82:83] op_sel_hi:[1,0]
	v_mov_b32_e32 v82, v175
	s_waitcnt vmcnt(0)
	v_pk_mul_f32 v[54:55], v[54:55], v[82:83] op_sel_hi:[1,0]
	v_pk_mul_f32 v[52:53], v[52:53], v[82:83] op_sel_hi:[1,0]
	s_branch .LBB0_990
